# GEMM K-loops: 5th-phase B-operand LDS reads issued before the 4th phase's closing barrier
# baseline (speedup 1.0000x reference)
.LBB0_297:
	s_add_u32 s22, s20, 0xfffc0080
	s_addc_u32 s23, s21, -1
	s_add_i32 s49, 0, 0x10000
	v_add_u32_e32 v145, s49, v142
	ds_read_b128 v[146:149], v145
	ds_read_b128 v[150:153], v145 offset:1024
	ds_read_b128 v[154:157], v145 offset:2048
	ds_read_b128 v[158:161], v145 offset:3072
	s_cmp_eq_u32 s48, 12
	s_cselect_b32 s25, s9, s23
	s_cselect_b32 s24, s44, s22
	s_cselect_b32 s23, s7, s47
	s_cselect_b32 s22, s45, s46
	s_add_i32 m0, s19, 0xc000
	ds_read_b128 v[162:165], v144
	ds_read_b128 v[166:169], v144 offset:1024
	ds_read_b128 v[170:173], v144 offset:2048
	ds_read_b128 v[174:177], v144 offset:3072
	ds_read_b128 v[190:193], v144 offset:4096
	ds_read_b128 v[194:197], v144 offset:5120
	ds_read_b128 v[198:201], v144 offset:6144
	ds_read_b128 v[202:205], v144 offset:7168
	global_load_lds_dwordx4 v138, s[20:21]
	s_add_i32 m0, s19, 0xe000
	s_nop 0
	global_load_lds_dwordx4 v140, s[20:21]
	s_waitcnt lgkmcnt(8)
	s_barrier
	s_waitcnt lgkmcnt(0)
	s_waitcnt lgkmcnt(0)
	v_mfma_f32_16x16x32_bf16 v[126:129], v[146:149], v[162:165], v[126:129]
	v_mfma_f32_16x16x32_bf16 v[118:121], v[154:157], v[162:165], v[118:121]
	v_mfma_f32_16x16x32_bf16 v[110:113], v[146:149], v[170:173], v[110:113]
	v_mfma_f32_16x16x32_bf16 v[102:105], v[154:157], v[170:173], v[102:105]
	v_mfma_f32_16x16x32_bf16 v[94:97], v[146:149], v[190:193], v[94:97]
	v_mfma_f32_16x16x32_bf16 v[86:89], v[154:157], v[190:193], v[86:89]
	v_mfma_f32_16x16x32_bf16 v[78:81], v[146:149], v[198:201], v[78:81]
	v_mfma_f32_16x16x32_bf16 v[70:73], v[154:157], v[198:201], v[70:73]
	v_mfma_f32_16x16x32_bf16 v[126:129], v[150:153], v[166:169], v[126:129]
	v_mfma_f32_16x16x32_bf16 v[118:121], v[158:161], v[166:169], v[118:121]
	v_mfma_f32_16x16x32_bf16 v[110:113], v[150:153], v[174:177], v[110:113]
	v_mfma_f32_16x16x32_bf16 v[102:105], v[158:161], v[174:177], v[102:105]
	v_mfma_f32_16x16x32_bf16 v[94:97], v[150:153], v[194:197], v[94:97]
	v_mfma_f32_16x16x32_bf16 v[86:89], v[158:161], v[194:197], v[86:89]
	v_mfma_f32_16x16x32_bf16 v[78:81], v[150:153], v[202:205], v[78:81]
	v_mfma_f32_16x16x32_bf16 v[70:73], v[158:161], v[202:205], v[70:73]
	s_barrier
	s_add_i32 s54, 0, 0x14000
	s_add_i32 s49, s49, s35
	v_add_u32_e32 v145, s54, v142
	s_add_u32 s64, s22, 0x80
	s_addc_u32 s65, s23, 0
	s_mov_b32 m0, s49
	ds_read_b128 v[206:209], v145
	ds_read_b128 v[210:213], v145 offset:1024
	ds_read_b128 v[214:217], v145 offset:2048
	ds_read_b128 v[218:221], v145 offset:3072
	global_load_lds_dwordx4 v134, s[22:23]
	s_add_i32 m0, s49, 0x2000
	s_nop 0
	global_load_lds_dwordx4 v130, s[22:23]
	s_barrier
	s_waitcnt lgkmcnt(0)
	s_waitcnt lgkmcnt(0)
	v_mfma_f32_16x16x32_bf16 v[122:125], v[206:209], v[162:165], v[122:125]
	v_mfma_f32_16x16x32_bf16 v[114:117], v[214:217], v[162:165], v[114:117]
	v_mfma_f32_16x16x32_bf16 v[106:109], v[206:209], v[170:173], v[106:109]
	v_mfma_f32_16x16x32_bf16 v[98:101], v[214:217], v[170:173], v[98:101]
	v_mfma_f32_16x16x32_bf16 v[90:93], v[206:209], v[190:193], v[90:93]
	v_mfma_f32_16x16x32_bf16 v[82:85], v[214:217], v[190:193], v[82:85]
	v_mfma_f32_16x16x32_bf16 v[74:77], v[206:209], v[198:201], v[74:77]
	v_mfma_f32_16x16x32_bf16 v[66:69], v[214:217], v[198:201], v[66:69]
	v_mfma_f32_16x16x32_bf16 v[122:125], v[210:213], v[166:169], v[122:125]
	v_mfma_f32_16x16x32_bf16 v[114:117], v[218:221], v[166:169], v[114:117]
	v_mfma_f32_16x16x32_bf16 v[106:109], v[210:213], v[174:177], v[106:109]
	v_mfma_f32_16x16x32_bf16 v[98:101], v[218:221], v[174:177], v[98:101]
	v_mfma_f32_16x16x32_bf16 v[90:93], v[210:213], v[194:197], v[90:93]
	v_mfma_f32_16x16x32_bf16 v[82:85], v[218:221], v[194:197], v[82:85]
	v_mfma_f32_16x16x32_bf16 v[74:77], v[210:213], v[202:205], v[74:77]
	v_mfma_f32_16x16x32_bf16 v[66:69], v[218:221], v[202:205], v[66:69]
	s_mov_b32 m0, s19
	s_add_u32 s62, s24, 0x80
	s_addc_u32 s63, s25, 0
	s_barrier
	ds_read_b128 v[162:165], v144 offset:16384
	ds_read_b128 v[166:169], v144 offset:17408
	ds_read_b128 v[170:173], v144 offset:18432
	ds_read_b128 v[174:177], v144 offset:19456
	ds_read_b128 v[190:193], v144 offset:20480
	ds_read_b128 v[194:197], v144 offset:21504
	ds_read_b128 v[198:201], v144 offset:22528
	ds_read_b128 v[202:205], v144 offset:23552
	global_load_lds_dwordx4 v136, s[24:25]
	s_mov_b32 m0, s36
	s_nop 0
	global_load_lds_dwordx4 v132, s[24:25]
	s_barrier
	s_waitcnt lgkmcnt(0)
	s_waitcnt lgkmcnt(0)
	v_mfma_f32_16x16x32_bf16 v[62:65], v[146:149], v[162:165], v[62:65]
	v_mfma_f32_16x16x32_bf16 v[54:57], v[154:157], v[162:165], v[54:57]
	v_mfma_f32_16x16x32_bf16 v[46:49], v[146:149], v[170:173], v[46:49]
	v_mfma_f32_16x16x32_bf16 v[38:41], v[154:157], v[170:173], v[38:41]
	v_mfma_f32_16x16x32_bf16 v[30:33], v[146:149], v[190:193], v[30:33]
	v_mfma_f32_16x16x32_bf16 v[22:25], v[154:157], v[190:193], v[22:25]
	v_mfma_f32_16x16x32_bf16 v[14:17], v[146:149], v[198:201], v[14:17]
	v_mfma_f32_16x16x32_bf16 v[6:9], v[154:157], v[198:201], v[6:9]
	v_mfma_f32_16x16x32_bf16 v[62:65], v[150:153], v[166:169], v[62:65]
	v_mfma_f32_16x16x32_bf16 v[54:57], v[158:161], v[166:169], v[54:57]
	v_mfma_f32_16x16x32_bf16 v[46:49], v[150:153], v[174:177], v[46:49]
	v_mfma_f32_16x16x32_bf16 v[38:41], v[158:161], v[174:177], v[38:41]
	v_mfma_f32_16x16x32_bf16 v[30:33], v[150:153], v[194:197], v[30:33]
	v_mfma_f32_16x16x32_bf16 v[22:25], v[158:161], v[194:197], v[22:25]
	v_mfma_f32_16x16x32_bf16 v[14:17], v[150:153], v[202:205], v[14:17]
	v_mfma_f32_16x16x32_bf16 v[6:9], v[158:161], v[202:205], v[6:9]
	s_barrier
	s_add_u32 s50, s22, 0x40000
	s_addc_u32 s51, s23, 0
	s_add_i32 s49, s54, s35
	s_mov_b32 m0, s49
	s_nop 0
	global_load_lds_dwordx4 v134, s[50:51]
	s_add_i32 m0, s49, 0x2000
	s_nop 0
	global_load_lds_dwordx4 v130, s[50:51]
	s_waitcnt vmcnt(6)
	s_barrier
	v_mfma_f32_16x16x32_bf16 v[58:61], v[206:209], v[162:165], v[58:61]
	v_mfma_f32_16x16x32_bf16 v[50:53], v[214:217], v[162:165], v[50:53]
	v_mfma_f32_16x16x32_bf16 v[42:45], v[206:209], v[170:173], v[42:45]
	v_mfma_f32_16x16x32_bf16 v[34:37], v[214:217], v[170:173], v[34:37]
	v_mfma_f32_16x16x32_bf16 v[26:29], v[206:209], v[190:193], v[26:29]
	v_mfma_f32_16x16x32_bf16 v[18:21], v[214:217], v[190:193], v[18:21]
	v_mfma_f32_16x16x32_bf16 v[10:13], v[206:209], v[198:201], v[10:13]
	v_mfma_f32_16x16x32_bf16 v[2:5], v[214:217], v[198:201], v[2:5]
	v_mfma_f32_16x16x32_bf16 v[58:61], v[210:213], v[166:169], v[58:61]
	v_mfma_f32_16x16x32_bf16 v[50:53], v[218:221], v[166:169], v[50:53]
	v_mfma_f32_16x16x32_bf16 v[42:45], v[210:213], v[174:177], v[42:45]
	v_mfma_f32_16x16x32_bf16 v[34:37], v[218:221], v[174:177], v[34:37]
	v_mfma_f32_16x16x32_bf16 v[26:29], v[210:213], v[194:197], v[26:29]
	v_mfma_f32_16x16x32_bf16 v[18:21], v[218:221], v[194:197], v[18:21]
	v_mfma_f32_16x16x32_bf16 v[10:13], v[210:213], v[202:205], v[10:13]
	v_mfma_f32_16x16x32_bf16 v[2:5], v[218:221], v[202:205], v[2:5]
	s_add_i32 s49, 0, 0x18000
	v_add_u32_e32 v145, s49, v142
	ds_read_b128 v[146:149], v145
	ds_read_b128 v[150:153], v145 offset:1024
	ds_read_b128 v[154:157], v145 offset:2048
	ds_read_b128 v[158:161], v145 offset:3072
	s_barrier
	s_add_u32 s24, s24, 0x40000
	s_addc_u32 s25, s25, 0
	s_mov_b32 m0, s37
	ds_read_b128 v[162:165], v144 offset:32768
	ds_read_b128 v[166:169], v144 offset:33792
	ds_read_b128 v[170:173], v144 offset:34816
	ds_read_b128 v[174:177], v144 offset:35840
	ds_read_b128 v[190:193], v144 offset:36864
	ds_read_b128 v[194:197], v144 offset:37888
	ds_read_b128 v[198:201], v144 offset:38912
	ds_read_b128 v[202:205], v144 offset:39936
	global_load_lds_dwordx4 v136, s[24:25]
	s_mov_b32 m0, s38
	s_nop 0
	global_load_lds_dwordx4 v132, s[24:25]
	s_waitcnt lgkmcnt(8)
	s_barrier
	s_waitcnt lgkmcnt(0)
	s_waitcnt lgkmcnt(0)
	v_mfma_f32_16x16x32_bf16 v[126:129], v[146:149], v[162:165], v[126:129]
	v_mfma_f32_16x16x32_bf16 v[118:121], v[154:157], v[162:165], v[118:121]
	v_mfma_f32_16x16x32_bf16 v[110:113], v[146:149], v[170:173], v[110:113]
	v_mfma_f32_16x16x32_bf16 v[102:105], v[154:157], v[170:173], v[102:105]
	v_mfma_f32_16x16x32_bf16 v[94:97], v[146:149], v[190:193], v[94:97]
	v_mfma_f32_16x16x32_bf16 v[86:89], v[154:157], v[190:193], v[86:89]
	v_mfma_f32_16x16x32_bf16 v[78:81], v[146:149], v[198:201], v[78:81]
	v_mfma_f32_16x16x32_bf16 v[70:73], v[154:157], v[198:201], v[70:73]
	v_mfma_f32_16x16x32_bf16 v[126:129], v[150:153], v[166:169], v[126:129]
	v_mfma_f32_16x16x32_bf16 v[118:121], v[158:161], v[166:169], v[118:121]
	v_mfma_f32_16x16x32_bf16 v[110:113], v[150:153], v[174:177], v[110:113]
	v_mfma_f32_16x16x32_bf16 v[102:105], v[158:161], v[174:177], v[102:105]
	v_mfma_f32_16x16x32_bf16 v[94:97], v[150:153], v[194:197], v[94:97]
	v_mfma_f32_16x16x32_bf16 v[86:89], v[158:161], v[194:197], v[86:89]
	v_mfma_f32_16x16x32_bf16 v[78:81], v[150:153], v[202:205], v[78:81]
	v_mfma_f32_16x16x32_bf16 v[70:73], v[158:161], v[202:205], v[70:73]
	s_barrier
	s_add_i32 s24, 0, 0x1c000
	s_add_i32 s25, s49, s35
	v_add_u32_e32 v145, s24, v142
	s_mov_b32 m0, s25
	ds_read_b128 v[206:209], v145
	ds_read_b128 v[210:213], v145 offset:1024
	ds_read_b128 v[214:217], v145 offset:2048
	ds_read_b128 v[218:221], v145 offset:3072
	global_load_lds_dwordx4 v134, s[64:65]
	s_add_i32 m0, s25, 0x2000
	s_nop 0
	global_load_lds_dwordx4 v130, s[64:65]
	s_barrier
	s_waitcnt lgkmcnt(0)
	s_waitcnt lgkmcnt(0)
	v_mfma_f32_16x16x32_bf16 v[122:125], v[206:209], v[162:165], v[122:125]
	v_mfma_f32_16x16x32_bf16 v[114:117], v[214:217], v[162:165], v[114:117]
	v_mfma_f32_16x16x32_bf16 v[106:109], v[206:209], v[170:173], v[106:109]
	v_mfma_f32_16x16x32_bf16 v[98:101], v[214:217], v[170:173], v[98:101]
	v_mfma_f32_16x16x32_bf16 v[90:93], v[206:209], v[190:193], v[90:93]
	v_mfma_f32_16x16x32_bf16 v[82:85], v[214:217], v[190:193], v[82:85]
	v_mfma_f32_16x16x32_bf16 v[74:77], v[206:209], v[198:201], v[74:77]
	v_mfma_f32_16x16x32_bf16 v[66:69], v[214:217], v[198:201], v[66:69]
	v_mfma_f32_16x16x32_bf16 v[122:125], v[210:213], v[166:169], v[122:125]
	v_mfma_f32_16x16x32_bf16 v[114:117], v[218:221], v[166:169], v[114:117]
	v_mfma_f32_16x16x32_bf16 v[106:109], v[210:213], v[174:177], v[106:109]
	v_mfma_f32_16x16x32_bf16 v[98:101], v[218:221], v[174:177], v[98:101]
	v_mfma_f32_16x16x32_bf16 v[90:93], v[210:213], v[194:197], v[90:93]
	v_mfma_f32_16x16x32_bf16 v[82:85], v[218:221], v[194:197], v[82:85]
	v_mfma_f32_16x16x32_bf16 v[74:77], v[210:213], v[202:205], v[74:77]
	v_mfma_f32_16x16x32_bf16 v[66:69], v[218:221], v[202:205], v[66:69]
	s_mov_b32 m0, s39
	s_barrier
	ds_read_b128 v[162:165], v144 offset:49152
	ds_read_b128 v[166:169], v144 offset:50176
	ds_read_b128 v[170:173], v144 offset:51200
	ds_read_b128 v[174:177], v144 offset:52224
	ds_read_b128 v[190:193], v144 offset:53248
	ds_read_b128 v[194:197], v144 offset:54272
	ds_read_b128 v[198:201], v144 offset:55296
	ds_read_b128 v[202:205], v144 offset:56320
	global_load_lds_dwordx4 v136, s[62:63]
	s_mov_b32 m0, s40
	s_nop 0
	global_load_lds_dwordx4 v132, s[62:63]
	s_barrier
	s_waitcnt lgkmcnt(0)
	s_waitcnt lgkmcnt(0)
	v_mfma_f32_16x16x32_bf16 v[62:65], v[146:149], v[162:165], v[62:65]
	v_mfma_f32_16x16x32_bf16 v[54:57], v[154:157], v[162:165], v[54:57]
	v_mfma_f32_16x16x32_bf16 v[46:49], v[146:149], v[170:173], v[46:49]
	v_mfma_f32_16x16x32_bf16 v[38:41], v[154:157], v[170:173], v[38:41]
	v_mfma_f32_16x16x32_bf16 v[30:33], v[146:149], v[190:193], v[30:33]
	v_mfma_f32_16x16x32_bf16 v[22:25], v[154:157], v[190:193], v[22:25]
	v_mfma_f32_16x16x32_bf16 v[14:17], v[146:149], v[198:201], v[14:17]
	v_mfma_f32_16x16x32_bf16 v[6:9], v[154:157], v[198:201], v[6:9]
	v_mfma_f32_16x16x32_bf16 v[62:65], v[150:153], v[166:169], v[62:65]
	v_mfma_f32_16x16x32_bf16 v[54:57], v[158:161], v[166:169], v[54:57]
	v_mfma_f32_16x16x32_bf16 v[46:49], v[150:153], v[174:177], v[46:49]
	v_mfma_f32_16x16x32_bf16 v[38:41], v[158:161], v[174:177], v[38:41]
	v_mfma_f32_16x16x32_bf16 v[30:33], v[150:153], v[194:197], v[30:33]
	v_mfma_f32_16x16x32_bf16 v[22:25], v[158:161], v[194:197], v[22:25]
	v_mfma_f32_16x16x32_bf16 v[14:17], v[150:153], v[202:205], v[14:17]
	v_mfma_f32_16x16x32_bf16 v[6:9], v[158:161], v[202:205], v[6:9]
	s_barrier
	s_add_u32 s22, s22, 0x40080
	s_addc_u32 s23, s23, 0
	s_add_i32 s24, s24, s35
	s_mov_b32 m0, s24
	s_nop 0
	global_load_lds_dwordx4 v134, s[22:23]
	s_add_i32 m0, s24, 0x2000
	s_nop 0
	global_load_lds_dwordx4 v130, s[22:23]
	s_waitcnt vmcnt(6)
	s_barrier
	v_mfma_f32_16x16x32_bf16 v[58:61], v[206:209], v[162:165], v[58:61]
	v_mfma_f32_16x16x32_bf16 v[50:53], v[214:217], v[162:165], v[50:53]
	v_mfma_f32_16x16x32_bf16 v[42:45], v[206:209], v[170:173], v[42:45]
	v_mfma_f32_16x16x32_bf16 v[34:37], v[214:217], v[170:173], v[34:37]
	v_mfma_f32_16x16x32_bf16 v[26:29], v[206:209], v[190:193], v[26:29]
	v_mfma_f32_16x16x32_bf16 v[18:21], v[214:217], v[190:193], v[18:21]
	v_mfma_f32_16x16x32_bf16 v[10:13], v[206:209], v[198:201], v[10:13]
	v_mfma_f32_16x16x32_bf16 v[2:5], v[214:217], v[198:201], v[2:5]
	v_mfma_f32_16x16x32_bf16 v[58:61], v[210:213], v[166:169], v[58:61]
	v_mfma_f32_16x16x32_bf16 v[50:53], v[218:221], v[166:169], v[50:53]
	v_mfma_f32_16x16x32_bf16 v[42:45], v[210:213], v[174:177], v[42:45]
	v_mfma_f32_16x16x32_bf16 v[34:37], v[218:221], v[174:177], v[34:37]
	v_mfma_f32_16x16x32_bf16 v[26:29], v[210:213], v[194:197], v[26:29]
	v_mfma_f32_16x16x32_bf16 v[18:21], v[218:221], v[194:197], v[18:21]
	v_mfma_f32_16x16x32_bf16 v[10:13], v[210:213], v[202:205], v[10:13]
	v_mfma_f32_16x16x32_bf16 v[2:5], v[218:221], v[202:205], v[2:5]
	s_add_i32 s48, s48, 2
	s_add_u32 s20, s20, 0x100
	s_addc_u32 s21, s21, 0
	s_add_u32 s46, s46, 0x100
	s_addc_u32 s47, s47, 0
	s_cmp_gt_u32 s48, 13
	s_barrier
	s_cbranch_scc0 .LBB0_297
	v_mul_f32_e32 v148, 0xbfb8aa3b, v126
	v_mul_f32_e32 v149, 0xbfb8aa3b, v127
	v_exp_f32_e32 v148, v148
	v_exp_f32_e32 v149, v149
	v_lshl_or_b32 v146, s43, 7, v143
	v_lshl_add_u32 v145, s18, 8, v1
	v_add_f32_e32 v148, 1.0, v148
	v_add_f32_e32 v149, 1.0, v149
	v_rcp_f32_e32 v148, v148
	v_rcp_f32_e32 v149, v149
	v_ashrrev_i32_e32 v147, 31, v146
	s_movk_i32 s7, 0x1700
	s_and_b64 vcc, exec, s[4:5]
	v_pk_mul_f32 v[126:127], v[126:127], v[148:149]
	s_mov_b32 s43, s6
	v_pk_mul_f32 v[122:123], v[126:127], v[122:123]
	v_mul_f32_e32 v126, 0xbfb8aa3b, v128
	v_mul_f32_e32 v127, 0xbfb8aa3b, v129
	v_exp_f32_e32 v126, v126
	v_exp_f32_e32 v127, v127
	s_mov_b32 s18, s8
	s_mov_b64 s[22:23], s[14:15]
	v_add_f32_e32 v126, 1.0, v126
	v_add_f32_e32 v127, 1.0, v127
	v_rcp_f32_e32 v126, v126
	v_rcp_f32_e32 v127, v127
	s_nop 0
	v_pk_mul_f32 v[126:127], v[128:129], v[126:127]
	s_nop 0
	v_pk_mul_f32 v[124:125], v[126:127], v[124:125]
	v_mul_f32_e32 v126, 0xbfb8aa3b, v118
	v_mul_f32_e32 v127, 0xbfb8aa3b, v119
	v_exp_f32_e32 v126, v126
	v_exp_f32_e32 v127, v127
	v_add_f32_e32 v126, 1.0, v126
	v_add_f32_e32 v127, 1.0, v127
	v_rcp_f32_e32 v126, v126
	v_rcp_f32_e32 v127, v127
	s_nop 0
	v_pk_mul_f32 v[118:119], v[118:119], v[126:127]
	s_nop 0
	v_pk_mul_f32 v[114:115], v[118:119], v[114:115]
	v_mul_f32_e32 v118, 0xbfb8aa3b, v120
	v_mul_f32_e32 v119, 0xbfb8aa3b, v121
	v_exp_f32_e32 v118, v118
	v_exp_f32_e32 v119, v119
	v_add_f32_e32 v118, 1.0, v118
	v_add_f32_e32 v119, 1.0, v119
	v_rcp_f32_e32 v118, v118
	v_rcp_f32_e32 v119, v119
	s_nop 0
	v_pk_mul_f32 v[118:119], v[120:121], v[118:119]
	s_nop 0
	v_pk_mul_f32 v[116:117], v[118:119], v[116:117]
	v_cvt_pk_bf16_f32 v120, v114, v115
	v_mov_b64_e32 v[114:115], s[2:3]
	v_cvt_pk_bf16_f32 v118, v122, v123
	v_cvt_pk_bf16_f32 v121, v116, v117
	v_mad_i64_i32 v[122:123], s[20:21], v145, s7, v[114:115]
	v_lshlrev_b64 v[116:117], 1, v[146:147]
	v_cvt_pk_bf16_f32 v119, v124, v125
	v_lshl_add_u64 v[122:123], v[122:123], 0, v[116:117]
	global_store_dwordx4 v[122:123], v[118:121], off
	s_nop 1
	v_mul_f32_e32 v118, 0xbfb8aa3b, v110
	v_mul_f32_e32 v119, 0xbfb8aa3b, v111
	v_exp_f32_e32 v118, v118
	v_exp_f32_e32 v119, v119
	v_add_f32_e32 v118, 1.0, v118
	v_add_f32_e32 v119, 1.0, v119
	v_rcp_f32_e32 v118, v118
	v_rcp_f32_e32 v119, v119
	s_nop 0
	v_pk_mul_f32 v[110:111], v[110:111], v[118:119]
	s_nop 0
	v_pk_mul_f32 v[106:107], v[110:111], v[106:107]
	v_mul_f32_e32 v110, 0xbfb8aa3b, v112
	v_mul_f32_e32 v111, 0xbfb8aa3b, v113
	v_exp_f32_e32 v110, v110
	v_exp_f32_e32 v111, v111
	v_add_f32_e32 v110, 1.0, v110
	v_add_f32_e32 v111, 1.0, v111
	v_rcp_f32_e32 v110, v110
	v_rcp_f32_e32 v111, v111
	s_nop 0
	v_pk_mul_f32 v[110:111], v[112:113], v[110:111]
	s_nop 0
	v_pk_mul_f32 v[108:109], v[110:111], v[108:109]
	v_mul_f32_e32 v110, 0xbfb8aa3b, v102
	v_mul_f32_e32 v111, 0xbfb8aa3b, v103
	v_exp_f32_e32 v110, v110
	v_exp_f32_e32 v111, v111
	v_add_f32_e32 v110, 1.0, v110
	v_add_f32_e32 v111, 1.0, v111
	v_rcp_f32_e32 v110, v110
	v_rcp_f32_e32 v111, v111
	s_nop 0
	v_pk_mul_f32 v[102:103], v[102:103], v[110:111]
	s_nop 0
	v_pk_mul_f32 v[102:103], v[102:103], v[98:99]
	v_mul_f32_e32 v98, 0xbfb8aa3b, v104
	v_mul_f32_e32 v99, 0xbfb8aa3b, v105
	v_exp_f32_e32 v98, v98
	v_exp_f32_e32 v99, v99
	v_add_f32_e32 v98, 1.0, v98
	v_add_f32_e32 v99, 1.0, v99
	v_rcp_f32_e32 v98, v98
	v_rcp_f32_e32 v99, v99
	s_nop 0
	v_pk_mul_f32 v[98:99], v[104:105], v[98:99]
	s_nop 0
	v_pk_mul_f32 v[104:105], v[98:99], v[100:101]
	v_cvt_pk_bf16_f32 v100, v102, v103
	v_or_b32_e32 v102, 16, v145
	v_mad_i64_i32 v[102:103], s[20:21], v102, s7, v[114:115]
	v_cvt_pk_bf16_f32 v98, v106, v107
	v_cvt_pk_bf16_f32 v99, v108, v109
	v_cvt_pk_bf16_f32 v101, v104, v105
	v_lshl_add_u64 v[102:103], v[102:103], 0, v[116:117]
	global_store_dwordx4 v[102:103], v[98:101], off
	s_nop 1
	v_mul_f32_e32 v98, 0xbfb8aa3b, v94
	v_mul_f32_e32 v99, 0xbfb8aa3b, v95
	v_exp_f32_e32 v98, v98
	v_exp_f32_e32 v99, v99
	v_add_f32_e32 v98, 1.0, v98
	v_add_f32_e32 v99, 1.0, v99
	v_rcp_f32_e32 v98, v98
	v_rcp_f32_e32 v99, v99
	s_nop 0
	v_pk_mul_f32 v[94:95], v[94:95], v[98:99]
	s_nop 0
	v_pk_mul_f32 v[90:91], v[94:95], v[90:91]
	v_mul_f32_e32 v94, 0xbfb8aa3b, v96
	v_mul_f32_e32 v95, 0xbfb8aa3b, v97
	v_exp_f32_e32 v94, v94
	v_exp_f32_e32 v95, v95
	v_add_f32_e32 v94, 1.0, v94
	v_add_f32_e32 v95, 1.0, v95
	v_rcp_f32_e32 v94, v94
	v_rcp_f32_e32 v95, v95
	s_nop 0
	v_pk_mul_f32 v[94:95], v[96:97], v[94:95]
	s_nop 0
	v_pk_mul_f32 v[92:93], v[94:95], v[92:93]
	v_mul_f32_e32 v94, 0xbfb8aa3b, v86
	v_mul_f32_e32 v95, 0xbfb8aa3b, v87
	v_exp_f32_e32 v94, v94
	v_exp_f32_e32 v95, v95
	v_add_f32_e32 v94, 1.0, v94
	v_add_f32_e32 v95, 1.0, v95
	v_rcp_f32_e32 v94, v94
	v_rcp_f32_e32 v95, v95
	s_nop 0
	v_pk_mul_f32 v[86:87], v[86:87], v[94:95]
	s_nop 0
	v_pk_mul_f32 v[86:87], v[86:87], v[82:83]
	v_mul_f32_e32 v82, 0xbfb8aa3b, v88
	v_mul_f32_e32 v83, 0xbfb8aa3b, v89
	v_exp_f32_e32 v82, v82
	v_exp_f32_e32 v83, v83
	v_add_f32_e32 v82, 1.0, v82
	v_add_f32_e32 v83, 1.0, v83
	v_rcp_f32_e32 v82, v82
	v_rcp_f32_e32 v83, v83
	s_nop 0
	v_pk_mul_f32 v[82:83], v[88:89], v[82:83]
	s_nop 0
	v_pk_mul_f32 v[88:89], v[82:83], v[84:85]
	v_cvt_pk_bf16_f32 v84, v86, v87
	v_or_b32_e32 v86, 32, v145
	v_mad_i64_i32 v[86:87], s[20:21], v86, s7, v[114:115]
	v_cvt_pk_bf16_f32 v82, v90, v91
	v_cvt_pk_bf16_f32 v83, v92, v93
	v_cvt_pk_bf16_f32 v85, v88, v89
	v_lshl_add_u64 v[86:87], v[86:87], 0, v[116:117]
	global_store_dwordx4 v[86:87], v[82:85], off
	s_nop 1
	v_mul_f32_e32 v82, 0xbfb8aa3b, v78
	v_mul_f32_e32 v83, 0xbfb8aa3b, v79
	v_exp_f32_e32 v82, v82
	v_exp_f32_e32 v83, v83
	v_add_f32_e32 v82, 1.0, v82
	v_add_f32_e32 v83, 1.0, v83
	v_rcp_f32_e32 v82, v82
	v_rcp_f32_e32 v83, v83
	s_nop 0
	v_pk_mul_f32 v[78:79], v[78:79], v[82:83]
	s_nop 0
	v_pk_mul_f32 v[74:75], v[78:79], v[74:75]
	v_mul_f32_e32 v78, 0xbfb8aa3b, v80
	v_mul_f32_e32 v79, 0xbfb8aa3b, v81
	v_exp_f32_e32 v78, v78
	v_exp_f32_e32 v79, v79
	v_add_f32_e32 v78, 1.0, v78
	v_add_f32_e32 v79, 1.0, v79
	v_rcp_f32_e32 v78, v78
	v_rcp_f32_e32 v79, v79
	s_nop 0
	v_pk_mul_f32 v[78:79], v[80:81], v[78:79]
	s_nop 0
	v_pk_mul_f32 v[76:77], v[78:79], v[76:77]
	v_mul_f32_e32 v78, 0xbfb8aa3b, v70
	v_mul_f32_e32 v79, 0xbfb8aa3b, v71
	v_exp_f32_e32 v78, v78
	v_exp_f32_e32 v79, v79
	v_add_f32_e32 v78, 1.0, v78
	v_add_f32_e32 v79, 1.0, v79
	v_rcp_f32_e32 v78, v78
	v_rcp_f32_e32 v79, v79
	s_nop 0
	v_pk_mul_f32 v[70:71], v[70:71], v[78:79]
	s_nop 0
	v_pk_mul_f32 v[70:71], v[70:71], v[66:67]
	v_mul_f32_e32 v66, 0xbfb8aa3b, v72
	v_mul_f32_e32 v67, 0xbfb8aa3b, v73
	v_exp_f32_e32 v66, v66
	v_exp_f32_e32 v67, v67
	v_add_f32_e32 v66, 1.0, v66
	v_add_f32_e32 v67, 1.0, v67
	v_rcp_f32_e32 v66, v66
	v_rcp_f32_e32 v67, v67
	s_nop 0
	v_pk_mul_f32 v[66:67], v[72:73], v[66:67]
	s_nop 0
	v_pk_mul_f32 v[72:73], v[66:67], v[68:69]
	v_cvt_pk_bf16_f32 v68, v70, v71
	v_or_b32_e32 v70, 48, v145
	v_mad_i64_i32 v[70:71], s[20:21], v70, s7, v[114:115]
	v_cvt_pk_bf16_f32 v66, v74, v75
	v_cvt_pk_bf16_f32 v67, v76, v77
	v_cvt_pk_bf16_f32 v69, v72, v73
	v_lshl_add_u64 v[70:71], v[70:71], 0, v[116:117]
	global_store_dwordx4 v[70:71], v[66:69], off
	s_nop 1
	v_mul_f32_e32 v66, 0xbfb8aa3b, v62
	v_mul_f32_e32 v67, 0xbfb8aa3b, v63
	v_exp_f32_e32 v66, v66
	v_exp_f32_e32 v67, v67
	v_add_u32_e32 v68, 0x80, v145
	v_add_f32_e32 v66, 1.0, v66
	v_add_f32_e32 v67, 1.0, v67
	v_rcp_f32_e32 v66, v66
	v_rcp_f32_e32 v67, v67
	s_nop 0
	v_pk_mul_f32 v[62:63], v[62:63], v[66:67]
	s_nop 0
	v_pk_mul_f32 v[58:59], v[62:63], v[58:59]
	v_mul_f32_e32 v62, 0xbfb8aa3b, v64
	v_mul_f32_e32 v63, 0xbfb8aa3b, v65
	v_exp_f32_e32 v62, v62
	v_exp_f32_e32 v63, v63
	v_add_f32_e32 v62, 1.0, v62
	v_add_f32_e32 v63, 1.0, v63
	v_rcp_f32_e32 v62, v62
	v_rcp_f32_e32 v63, v63
	s_nop 0
	v_pk_mul_f32 v[62:63], v[64:65], v[62:63]
	s_nop 0
	v_pk_mul_f32 v[60:61], v[62:63], v[60:61]
	v_mul_f32_e32 v62, 0xbfb8aa3b, v54
	v_mul_f32_e32 v63, 0xbfb8aa3b, v55
	v_exp_f32_e32 v62, v62
	v_exp_f32_e32 v63, v63
	v_add_f32_e32 v62, 1.0, v62
	v_add_f32_e32 v63, 1.0, v63
	v_rcp_f32_e32 v62, v62
	v_rcp_f32_e32 v63, v63
	s_nop 0
	v_pk_mul_f32 v[54:55], v[54:55], v[62:63]
	s_nop 0
	v_pk_mul_f32 v[54:55], v[54:55], v[50:51]
	v_mul_f32_e32 v50, 0xbfb8aa3b, v56
	v_mul_f32_e32 v51, 0xbfb8aa3b, v57
	v_exp_f32_e32 v50, v50
	v_exp_f32_e32 v51, v51
	v_add_f32_e32 v50, 1.0, v50
	v_add_f32_e32 v51, 1.0, v51
	v_rcp_f32_e32 v50, v50
	v_rcp_f32_e32 v51, v51
	s_nop 0
	v_pk_mul_f32 v[50:51], v[56:57], v[50:51]
	s_nop 0
	v_pk_mul_f32 v[56:57], v[50:51], v[52:53]
	v_cvt_pk_bf16_f32 v52, v54, v55
	v_mad_i64_i32 v[54:55], s[20:21], v68, s7, v[114:115]
	v_cvt_pk_bf16_f32 v50, v58, v59
	v_cvt_pk_bf16_f32 v51, v60, v61
	v_cvt_pk_bf16_f32 v53, v56, v57
	v_lshl_add_u64 v[54:55], v[54:55], 0, v[116:117]
	global_store_dwordx4 v[54:55], v[50:53], off
	s_nop 1
	v_mul_f32_e32 v50, 0xbfb8aa3b, v46
	v_mul_f32_e32 v51, 0xbfb8aa3b, v47
	v_exp_f32_e32 v50, v50
	v_exp_f32_e32 v51, v51
	v_add_f32_e32 v50, 1.0, v50
	v_add_f32_e32 v51, 1.0, v51
	v_rcp_f32_e32 v50, v50
	v_rcp_f32_e32 v51, v51
	s_nop 0
	v_pk_mul_f32 v[46:47], v[46:47], v[50:51]
	s_nop 0
	v_pk_mul_f32 v[42:43], v[46:47], v[42:43]
	v_mul_f32_e32 v46, 0xbfb8aa3b, v48
	v_mul_f32_e32 v47, 0xbfb8aa3b, v49
	v_exp_f32_e32 v46, v46
	v_exp_f32_e32 v47, v47
	v_add_f32_e32 v46, 1.0, v46
	v_add_f32_e32 v47, 1.0, v47
	v_rcp_f32_e32 v46, v46
	v_rcp_f32_e32 v47, v47
	s_nop 0
	v_pk_mul_f32 v[46:47], v[48:49], v[46:47]
	s_nop 0
	v_pk_mul_f32 v[44:45], v[46:47], v[44:45]
	v_mul_f32_e32 v46, 0xbfb8aa3b, v38
	v_mul_f32_e32 v47, 0xbfb8aa3b, v39
	v_exp_f32_e32 v46, v46
	v_exp_f32_e32 v47, v47
	v_add_f32_e32 v46, 1.0, v46
	v_add_f32_e32 v47, 1.0, v47
	v_rcp_f32_e32 v46, v46
	v_rcp_f32_e32 v47, v47
	s_nop 0
	v_pk_mul_f32 v[38:39], v[38:39], v[46:47]
	s_nop 0
	v_pk_mul_f32 v[38:39], v[38:39], v[34:35]
	v_mul_f32_e32 v34, 0xbfb8aa3b, v40
	v_mul_f32_e32 v35, 0xbfb8aa3b, v41
	v_exp_f32_e32 v34, v34
	v_exp_f32_e32 v35, v35
	v_add_f32_e32 v34, 1.0, v34
	v_add_f32_e32 v35, 1.0, v35
	v_rcp_f32_e32 v34, v34
	v_rcp_f32_e32 v35, v35
	s_nop 0
	v_pk_mul_f32 v[34:35], v[40:41], v[34:35]
	s_nop 0
	v_pk_mul_f32 v[40:41], v[34:35], v[36:37]
	v_cvt_pk_bf16_f32 v36, v38, v39
	v_add_u32_e32 v38, 0x90, v145
	v_mad_i64_i32 v[38:39], s[20:21], v38, s7, v[114:115]
	v_cvt_pk_bf16_f32 v34, v42, v43
	v_cvt_pk_bf16_f32 v35, v44, v45
	v_cvt_pk_bf16_f32 v37, v40, v41
	v_lshl_add_u64 v[38:39], v[38:39], 0, v[116:117]
	global_store_dwordx4 v[38:39], v[34:37], off
	s_nop 1
	v_mul_f32_e32 v34, 0xbfb8aa3b, v30
	v_mul_f32_e32 v35, 0xbfb8aa3b, v31
	v_exp_f32_e32 v34, v34
	v_exp_f32_e32 v35, v35
	v_add_f32_e32 v34, 1.0, v34
	v_add_f32_e32 v35, 1.0, v35
	v_rcp_f32_e32 v34, v34
	v_rcp_f32_e32 v35, v35
	s_nop 0
	v_pk_mul_f32 v[30:31], v[30:31], v[34:35]
	s_nop 0
	v_pk_mul_f32 v[26:27], v[30:31], v[26:27]
	v_mul_f32_e32 v30, 0xbfb8aa3b, v32
	v_mul_f32_e32 v31, 0xbfb8aa3b, v33
	v_exp_f32_e32 v30, v30
	v_exp_f32_e32 v31, v31
	v_add_f32_e32 v30, 1.0, v30
	v_add_f32_e32 v31, 1.0, v31
	v_rcp_f32_e32 v30, v30
	v_rcp_f32_e32 v31, v31
	s_nop 0
	v_pk_mul_f32 v[30:31], v[32:33], v[30:31]
	s_nop 0
	v_pk_mul_f32 v[28:29], v[30:31], v[28:29]
	v_mul_f32_e32 v30, 0xbfb8aa3b, v22
	v_mul_f32_e32 v31, 0xbfb8aa3b, v23
	v_exp_f32_e32 v30, v30
	v_exp_f32_e32 v31, v31
	v_add_f32_e32 v30, 1.0, v30
	v_add_f32_e32 v31, 1.0, v31
	v_rcp_f32_e32 v30, v30
	v_rcp_f32_e32 v31, v31
	s_nop 0
	v_pk_mul_f32 v[22:23], v[22:23], v[30:31]
	s_nop 0
	v_pk_mul_f32 v[22:23], v[22:23], v[18:19]
	v_mul_f32_e32 v18, 0xbfb8aa3b, v24
	v_mul_f32_e32 v19, 0xbfb8aa3b, v25
	v_exp_f32_e32 v18, v18
	v_exp_f32_e32 v19, v19
	v_add_f32_e32 v18, 1.0, v18
	v_add_f32_e32 v19, 1.0, v19
	v_rcp_f32_e32 v18, v18
	v_rcp_f32_e32 v19, v19
	s_nop 0
	v_pk_mul_f32 v[18:19], v[24:25], v[18:19]
	s_nop 0
	v_pk_mul_f32 v[24:25], v[18:19], v[20:21]
	v_cvt_pk_bf16_f32 v20, v22, v23
	v_add_u32_e32 v22, 0xa0, v145
	v_mad_i64_i32 v[22:23], s[20:21], v22, s7, v[114:115]
	v_cvt_pk_bf16_f32 v18, v26, v27
	v_cvt_pk_bf16_f32 v19, v28, v29
	v_cvt_pk_bf16_f32 v21, v24, v25
	v_lshl_add_u64 v[22:23], v[22:23], 0, v[116:117]
	global_store_dwordx4 v[22:23], v[18:21], off
	s_nop 1
	v_mul_f32_e32 v18, 0xbfb8aa3b, v14
	v_mul_f32_e32 v19, 0xbfb8aa3b, v15
	v_exp_f32_e32 v18, v18
	v_exp_f32_e32 v19, v19
	v_add_f32_e32 v18, 1.0, v18
	v_add_f32_e32 v19, 1.0, v19
	v_rcp_f32_e32 v18, v18
	v_rcp_f32_e32 v19, v19
	s_nop 0
	v_pk_mul_f32 v[14:15], v[14:15], v[18:19]
	s_nop 0
	v_pk_mul_f32 v[10:11], v[14:15], v[10:11]
	v_mul_f32_e32 v14, 0xbfb8aa3b, v16
	v_mul_f32_e32 v15, 0xbfb8aa3b, v17
	v_exp_f32_e32 v14, v14
	v_exp_f32_e32 v15, v15
	v_add_f32_e32 v14, 1.0, v14
	v_add_f32_e32 v15, 1.0, v15
	v_rcp_f32_e32 v14, v14
	v_rcp_f32_e32 v15, v15
	s_nop 0
	v_pk_mul_f32 v[14:15], v[16:17], v[14:15]
	s_nop 0
	v_pk_mul_f32 v[12:13], v[14:15], v[12:13]
	v_mul_f32_e32 v14, 0xbfb8aa3b, v6
	v_mul_f32_e32 v15, 0xbfb8aa3b, v7
	v_exp_f32_e32 v14, v14
	v_exp_f32_e32 v15, v15
	v_add_f32_e32 v14, 1.0, v14
	v_add_f32_e32 v15, 1.0, v15
	v_rcp_f32_e32 v14, v14
	v_rcp_f32_e32 v15, v15
	s_nop 0
	v_pk_mul_f32 v[6:7], v[6:7], v[14:15]
	s_nop 0
	v_pk_mul_f32 v[6:7], v[6:7], v[2:3]
	v_mul_f32_e32 v2, 0xbfb8aa3b, v8
	v_mul_f32_e32 v3, 0xbfb8aa3b, v9
	v_exp_f32_e32 v2, v2
	v_exp_f32_e32 v3, v3
	v_add_f32_e32 v2, 1.0, v2
	v_add_f32_e32 v3, 1.0, v3
	v_rcp_f32_e32 v2, v2
	v_rcp_f32_e32 v3, v3
	s_nop 0
	v_pk_mul_f32 v[2:3], v[8:9], v[2:3]
	s_nop 0
	v_pk_mul_f32 v[8:9], v[2:3], v[4:5]
	v_cvt_pk_bf16_f32 v4, v6, v7
	v_add_u32_e32 v6, 0xb0, v145
	v_mad_i64_i32 v[6:7], s[20:21], v6, s7, v[114:115]
	v_cvt_pk_bf16_f32 v2, v10, v11
	v_cvt_pk_bf16_f32 v3, v12, v13
	v_cvt_pk_bf16_f32 v5, v8, v9
	v_lshl_add_u64 v[6:7], v[6:7], 0, v[116:117]
	s_mov_b64 s[20:21], s[12:13]
	global_store_dwordx4 v[6:7], v[2:5], off
	s_cbranch_vccz .LBB0_294
	s_waitcnt vmcnt(0)
	s_cmpk_gt_u32 s28, 0xff
	s_cbranch_scc1 .LBB0_301
	s_barrier

.LBB0_374:
	s_add_u32 s16, s14, 0x100
	s_addc_u32 s17, s15, 0
	s_add_i32 s49, 0, 0x10000
	v_add_u32_e32 v154, s49, v164
	ds_read_b128 v[142:145], v154
	ds_read_b128 v[146:149], v154 offset:1024
	ds_read_b128 v[150:153], v154 offset:2048
	ds_read_b128 v[154:157], v154 offset:3072
	s_cmp_eq_u32 s48, 40
	s_cselect_b32 s21, s7, s17
	s_cselect_b32 s20, s6, s16
	s_cselect_b32 s19, s9, s47
	s_cselect_b32 s18, s8, s46
	v_lshl_add_u64 v[162:163], s[14:15], 0, v[138:139]
	s_add_i32 m0, s35, 0xc000
	ds_read_b128 v[158:161], v166
	ds_read_b128 v[168:171], v166 offset:1024
	ds_read_b128 v[172:175], v166 offset:2048
	ds_read_b128 v[190:193], v166 offset:3072
	ds_read_b128 v[194:197], v166 offset:4096
	ds_read_b128 v[198:201], v166 offset:5120
	ds_read_b128 v[202:205], v166 offset:6144
	ds_read_b128 v[206:209], v166 offset:7168
	global_load_lds_dwordx4 v[162:163], off
	v_lshl_add_u64 v[162:163], s[14:15], 0, v[140:141]
	s_add_i32 m0, s35, 0xe000
	s_nop 0
	global_load_lds_dwordx4 v[162:163], off
	s_waitcnt lgkmcnt(8)
	s_barrier
	s_waitcnt lgkmcnt(0)
	s_waitcnt lgkmcnt(0)
	v_mfma_f32_16x16x32_bf16 v[126:129], v[142:145], v[158:161], v[126:129]
	v_mfma_f32_16x16x32_bf16 v[122:125], v[150:153], v[158:161], v[122:125]
	v_mfma_f32_16x16x32_bf16 v[110:113], v[142:145], v[172:175], v[110:113]
	v_mfma_f32_16x16x32_bf16 v[106:109], v[150:153], v[172:175], v[106:109]
	v_mfma_f32_16x16x32_bf16 v[94:97], v[142:145], v[194:197], v[94:97]
	v_mfma_f32_16x16x32_bf16 v[90:93], v[150:153], v[194:197], v[90:93]
	v_mfma_f32_16x16x32_bf16 v[78:81], v[142:145], v[202:205], v[78:81]
	v_mfma_f32_16x16x32_bf16 v[74:77], v[150:153], v[202:205], v[74:77]
	v_mfma_f32_16x16x32_bf16 v[126:129], v[146:149], v[168:171], v[126:129]
	v_mfma_f32_16x16x32_bf16 v[122:125], v[154:157], v[168:171], v[122:125]
	v_mfma_f32_16x16x32_bf16 v[110:113], v[146:149], v[190:193], v[110:113]
	v_mfma_f32_16x16x32_bf16 v[106:109], v[154:157], v[190:193], v[106:109]
	v_mfma_f32_16x16x32_bf16 v[94:97], v[146:149], v[198:201], v[94:97]
	v_mfma_f32_16x16x32_bf16 v[90:93], v[154:157], v[198:201], v[90:93]
	v_mfma_f32_16x16x32_bf16 v[78:81], v[146:149], v[206:209], v[78:81]
	v_mfma_f32_16x16x32_bf16 v[74:77], v[154:157], v[206:209], v[74:77]
	s_barrier
	s_add_i32 s50, 0, 0x14000
	v_add_u32_e32 v162, s50, v164
	s_add_i32 s14, s49, s34
	ds_read_b128 v[210:213], v162
	ds_read_b128 v[214:217], v162 offset:1024
	ds_read_b128 v[218:221], v162 offset:2048
	ds_read_b128 v[222:225], v162 offset:3072
	s_add_u32 s64, s18, 0x80
	s_addc_u32 s65, s19, 0
	s_mov_b32 m0, s14
	s_nop 0
	global_load_lds_dwordx4 v132, s[18:19]
	s_add_i32 m0, s14, 0x2000
	s_nop 0
	global_load_lds_dwordx4 v136, s[18:19]
	s_barrier
	s_waitcnt lgkmcnt(0)
	s_waitcnt lgkmcnt(0)
	v_mfma_f32_16x16x32_bf16 v[118:121], v[210:213], v[158:161], v[118:121]
	v_mfma_f32_16x16x32_bf16 v[114:117], v[218:221], v[158:161], v[114:117]
	v_mfma_f32_16x16x32_bf16 v[102:105], v[210:213], v[172:175], v[102:105]
	v_mfma_f32_16x16x32_bf16 v[98:101], v[218:221], v[172:175], v[98:101]
	v_mfma_f32_16x16x32_bf16 v[86:89], v[210:213], v[194:197], v[86:89]
	v_mfma_f32_16x16x32_bf16 v[82:85], v[218:221], v[194:197], v[82:85]
	v_mfma_f32_16x16x32_bf16 v[70:73], v[210:213], v[202:205], v[70:73]
	v_mfma_f32_16x16x32_bf16 v[66:69], v[218:221], v[202:205], v[66:69]
	v_mfma_f32_16x16x32_bf16 v[118:121], v[214:217], v[168:171], v[118:121]
	v_mfma_f32_16x16x32_bf16 v[114:117], v[222:225], v[168:171], v[114:117]
	v_mfma_f32_16x16x32_bf16 v[102:105], v[214:217], v[190:193], v[102:105]
	v_mfma_f32_16x16x32_bf16 v[98:101], v[222:225], v[190:193], v[98:101]
	v_mfma_f32_16x16x32_bf16 v[86:89], v[214:217], v[198:201], v[86:89]
	v_mfma_f32_16x16x32_bf16 v[82:85], v[222:225], v[198:201], v[82:85]
	v_mfma_f32_16x16x32_bf16 v[70:73], v[214:217], v[206:209], v[70:73]
	v_mfma_f32_16x16x32_bf16 v[66:69], v[222:225], v[206:209], v[66:69]
	s_mov_b32 m0, s35
	s_add_u32 s62, s20, 0x80
	s_addc_u32 s63, s21, 0
	s_barrier
	ds_read_b128 v[158:161], v166 offset:16384
	ds_read_b128 v[168:171], v166 offset:17408
	ds_read_b128 v[172:175], v166 offset:18432
	ds_read_b128 v[190:193], v166 offset:19456
	ds_read_b128 v[194:197], v166 offset:20480
	ds_read_b128 v[198:201], v166 offset:21504
	ds_read_b128 v[202:205], v166 offset:22528
	ds_read_b128 v[206:209], v166 offset:23552
	global_load_lds_dwordx4 v130, s[20:21]
	s_mov_b32 m0, s36
	s_nop 0
	global_load_lds_dwordx4 v134, s[20:21]
	s_barrier
	s_waitcnt lgkmcnt(0)
	s_waitcnt lgkmcnt(0)
	v_mfma_f32_16x16x32_bf16 v[62:65], v[142:145], v[158:161], v[62:65]
	v_mfma_f32_16x16x32_bf16 v[58:61], v[150:153], v[158:161], v[58:61]
	v_mfma_f32_16x16x32_bf16 v[46:49], v[142:145], v[172:175], v[46:49]
	v_mfma_f32_16x16x32_bf16 v[42:45], v[150:153], v[172:175], v[42:45]
	v_mfma_f32_16x16x32_bf16 v[30:33], v[142:145], v[194:197], v[30:33]
	v_mfma_f32_16x16x32_bf16 v[26:29], v[150:153], v[194:197], v[26:29]
	v_mfma_f32_16x16x32_bf16 v[14:17], v[142:145], v[202:205], v[14:17]
	v_mfma_f32_16x16x32_bf16 v[10:13], v[150:153], v[202:205], v[10:13]
	v_mfma_f32_16x16x32_bf16 v[62:65], v[146:149], v[168:171], v[62:65]
	v_mfma_f32_16x16x32_bf16 v[58:61], v[154:157], v[168:171], v[58:61]
	v_mfma_f32_16x16x32_bf16 v[46:49], v[146:149], v[190:193], v[46:49]
	v_mfma_f32_16x16x32_bf16 v[42:45], v[154:157], v[190:193], v[42:45]
	v_mfma_f32_16x16x32_bf16 v[30:33], v[146:149], v[198:201], v[30:33]
	v_mfma_f32_16x16x32_bf16 v[26:29], v[154:157], v[198:201], v[26:29]
	v_mfma_f32_16x16x32_bf16 v[14:17], v[146:149], v[206:209], v[14:17]
	v_mfma_f32_16x16x32_bf16 v[10:13], v[154:157], v[206:209], v[10:13]
	s_barrier
	s_add_u32 s14, s18, 0xb0000
	s_addc_u32 s15, s19, 0
	s_add_i32 s49, s50, s34
	s_mov_b32 m0, s49
	s_nop 0
	global_load_lds_dwordx4 v132, s[14:15]
	s_add_i32 m0, s49, 0x2000
	s_nop 0
	global_load_lds_dwordx4 v136, s[14:15]
	s_waitcnt vmcnt(6)
	s_barrier
	v_mfma_f32_16x16x32_bf16 v[54:57], v[210:213], v[158:161], v[54:57]
	v_mfma_f32_16x16x32_bf16 v[50:53], v[218:221], v[158:161], v[50:53]
	v_mfma_f32_16x16x32_bf16 v[38:41], v[210:213], v[172:175], v[38:41]
	v_mfma_f32_16x16x32_bf16 v[34:37], v[218:221], v[172:175], v[34:37]
	v_mfma_f32_16x16x32_bf16 v[22:25], v[210:213], v[194:197], v[22:25]
	v_mfma_f32_16x16x32_bf16 v[18:21], v[218:221], v[194:197], v[18:21]
	v_mfma_f32_16x16x32_bf16 v[6:9], v[210:213], v[202:205], v[6:9]
	v_mfma_f32_16x16x32_bf16 v[2:5], v[218:221], v[202:205], v[2:5]
	v_mfma_f32_16x16x32_bf16 v[54:57], v[214:217], v[168:171], v[54:57]
	v_mfma_f32_16x16x32_bf16 v[50:53], v[222:225], v[168:171], v[50:53]
	v_mfma_f32_16x16x32_bf16 v[38:41], v[214:217], v[190:193], v[38:41]
	v_mfma_f32_16x16x32_bf16 v[34:37], v[222:225], v[190:193], v[34:37]
	v_mfma_f32_16x16x32_bf16 v[22:25], v[214:217], v[198:201], v[22:25]
	v_mfma_f32_16x16x32_bf16 v[18:21], v[222:225], v[198:201], v[18:21]
	v_mfma_f32_16x16x32_bf16 v[6:9], v[214:217], v[206:209], v[6:9]
	v_mfma_f32_16x16x32_bf16 v[2:5], v[222:225], v[206:209], v[2:5]
	s_add_i32 s49, 0, 0x18000
	v_add_u32_e32 v154, s49, v164
	ds_read_b128 v[142:145], v154
	ds_read_b128 v[146:149], v154 offset:1024
	ds_read_b128 v[150:153], v154 offset:2048
	ds_read_b128 v[154:157], v154 offset:3072
	s_barrier
	s_add_u32 s14, s20, 0xb8000
	s_addc_u32 s15, s21, 0
	s_mov_b32 m0, s37
	ds_read_b128 v[158:161], v166 offset:32768
	ds_read_b128 v[168:171], v166 offset:33792
	ds_read_b128 v[172:175], v166 offset:34816
	ds_read_b128 v[190:193], v166 offset:35840
	ds_read_b128 v[194:197], v166 offset:36864
	ds_read_b128 v[198:201], v166 offset:37888
	ds_read_b128 v[202:205], v166 offset:38912
	ds_read_b128 v[206:209], v166 offset:39936
	global_load_lds_dwordx4 v130, s[14:15]
	s_mov_b32 m0, s38
	s_nop 0
	global_load_lds_dwordx4 v134, s[14:15]
	s_waitcnt lgkmcnt(8)
	s_barrier
	s_waitcnt lgkmcnt(0)
	s_waitcnt lgkmcnt(0)
	v_mfma_f32_16x16x32_bf16 v[126:129], v[142:145], v[158:161], v[126:129]
	v_mfma_f32_16x16x32_bf16 v[122:125], v[150:153], v[158:161], v[122:125]
	v_mfma_f32_16x16x32_bf16 v[110:113], v[142:145], v[172:175], v[110:113]
	v_mfma_f32_16x16x32_bf16 v[106:109], v[150:153], v[172:175], v[106:109]
	v_mfma_f32_16x16x32_bf16 v[94:97], v[142:145], v[194:197], v[94:97]
	v_mfma_f32_16x16x32_bf16 v[90:93], v[150:153], v[194:197], v[90:93]
	v_mfma_f32_16x16x32_bf16 v[78:81], v[142:145], v[202:205], v[78:81]
	v_mfma_f32_16x16x32_bf16 v[74:77], v[150:153], v[202:205], v[74:77]
	v_mfma_f32_16x16x32_bf16 v[126:129], v[146:149], v[168:171], v[126:129]
	v_mfma_f32_16x16x32_bf16 v[122:125], v[154:157], v[168:171], v[122:125]
	v_mfma_f32_16x16x32_bf16 v[110:113], v[146:149], v[190:193], v[110:113]
	v_mfma_f32_16x16x32_bf16 v[106:109], v[154:157], v[190:193], v[106:109]
	v_mfma_f32_16x16x32_bf16 v[94:97], v[146:149], v[198:201], v[94:97]
	v_mfma_f32_16x16x32_bf16 v[90:93], v[154:157], v[198:201], v[90:93]
	v_mfma_f32_16x16x32_bf16 v[78:81], v[146:149], v[206:209], v[78:81]
	v_mfma_f32_16x16x32_bf16 v[74:77], v[154:157], v[206:209], v[74:77]
	s_barrier
	s_add_i32 s20, 0, 0x1c000
	s_add_i32 s14, s49, s34
	v_add_u32_e32 v167, s20, v164
	s_mov_b32 m0, s14
	ds_read_b128 v[210:213], v167
	ds_read_b128 v[214:217], v167 offset:1024
	ds_read_b128 v[218:221], v167 offset:2048
	ds_read_b128 v[222:225], v167 offset:3072
	global_load_lds_dwordx4 v132, s[64:65]
	s_add_i32 m0, s14, 0x2000
	s_nop 0
	global_load_lds_dwordx4 v136, s[64:65]
	s_barrier
	s_waitcnt lgkmcnt(0)
	s_waitcnt lgkmcnt(0)
	v_mfma_f32_16x16x32_bf16 v[118:121], v[210:213], v[158:161], v[118:121]
	v_mfma_f32_16x16x32_bf16 v[114:117], v[218:221], v[158:161], v[114:117]
	v_mfma_f32_16x16x32_bf16 v[102:105], v[210:213], v[172:175], v[102:105]
	v_mfma_f32_16x16x32_bf16 v[98:101], v[218:221], v[172:175], v[98:101]
	v_mfma_f32_16x16x32_bf16 v[86:89], v[210:213], v[194:197], v[86:89]
	v_mfma_f32_16x16x32_bf16 v[82:85], v[218:221], v[194:197], v[82:85]
	v_mfma_f32_16x16x32_bf16 v[70:73], v[210:213], v[202:205], v[70:73]
	v_mfma_f32_16x16x32_bf16 v[66:69], v[218:221], v[202:205], v[66:69]
	v_mfma_f32_16x16x32_bf16 v[118:121], v[214:217], v[168:171], v[118:121]
	v_mfma_f32_16x16x32_bf16 v[114:117], v[222:225], v[168:171], v[114:117]
	v_mfma_f32_16x16x32_bf16 v[102:105], v[214:217], v[190:193], v[102:105]
	v_mfma_f32_16x16x32_bf16 v[98:101], v[222:225], v[190:193], v[98:101]
	v_mfma_f32_16x16x32_bf16 v[86:89], v[214:217], v[198:201], v[86:89]
	v_mfma_f32_16x16x32_bf16 v[82:85], v[222:225], v[198:201], v[82:85]
	v_mfma_f32_16x16x32_bf16 v[70:73], v[214:217], v[206:209], v[70:73]
	v_mfma_f32_16x16x32_bf16 v[66:69], v[222:225], v[206:209], v[66:69]
	s_mov_b32 m0, s39
	s_barrier
	ds_read_b128 v[158:161], v166 offset:49152
	ds_read_b128 v[168:171], v166 offset:50176
	ds_read_b128 v[172:175], v166 offset:51200
	ds_read_b128 v[190:193], v166 offset:52224
	ds_read_b128 v[194:197], v166 offset:53248
	ds_read_b128 v[198:201], v166 offset:54272
	ds_read_b128 v[202:205], v166 offset:55296
	ds_read_b128 v[206:209], v166 offset:56320
	global_load_lds_dwordx4 v130, s[62:63]
	s_mov_b32 m0, s40
	s_nop 0
	global_load_lds_dwordx4 v134, s[62:63]
	s_barrier
	s_waitcnt lgkmcnt(0)
	s_waitcnt lgkmcnt(0)
	v_mfma_f32_16x16x32_bf16 v[62:65], v[142:145], v[158:161], v[62:65]
	v_mfma_f32_16x16x32_bf16 v[58:61], v[150:153], v[158:161], v[58:61]
	v_mfma_f32_16x16x32_bf16 v[46:49], v[142:145], v[172:175], v[46:49]
	v_mfma_f32_16x16x32_bf16 v[42:45], v[150:153], v[172:175], v[42:45]
	v_mfma_f32_16x16x32_bf16 v[30:33], v[142:145], v[194:197], v[30:33]
	v_mfma_f32_16x16x32_bf16 v[26:29], v[150:153], v[194:197], v[26:29]
	v_mfma_f32_16x16x32_bf16 v[14:17], v[142:145], v[202:205], v[14:17]
	v_mfma_f32_16x16x32_bf16 v[10:13], v[150:153], v[202:205], v[10:13]
	v_mfma_f32_16x16x32_bf16 v[62:65], v[146:149], v[168:171], v[62:65]
	v_mfma_f32_16x16x32_bf16 v[58:61], v[154:157], v[168:171], v[58:61]
	v_mfma_f32_16x16x32_bf16 v[46:49], v[146:149], v[190:193], v[46:49]
	v_mfma_f32_16x16x32_bf16 v[42:45], v[154:157], v[190:193], v[42:45]
	v_mfma_f32_16x16x32_bf16 v[30:33], v[146:149], v[198:201], v[30:33]
	v_mfma_f32_16x16x32_bf16 v[26:29], v[154:157], v[198:201], v[26:29]
	v_mfma_f32_16x16x32_bf16 v[14:17], v[146:149], v[206:209], v[14:17]
	v_mfma_f32_16x16x32_bf16 v[10:13], v[154:157], v[206:209], v[10:13]
	s_barrier
	s_add_u32 s14, s18, 0xb0080
	s_addc_u32 s15, s19, 0
	s_add_i32 s18, s20, s34
	s_mov_b32 m0, s18
	s_nop 0
	global_load_lds_dwordx4 v132, s[14:15]
	s_add_i32 m0, s18, 0x2000
	s_nop 0
	global_load_lds_dwordx4 v136, s[14:15]
	s_waitcnt vmcnt(6)
	s_barrier
	v_mfma_f32_16x16x32_bf16 v[54:57], v[210:213], v[158:161], v[54:57]
	v_mfma_f32_16x16x32_bf16 v[50:53], v[218:221], v[158:161], v[50:53]
	v_mfma_f32_16x16x32_bf16 v[38:41], v[210:213], v[172:175], v[38:41]
	v_mfma_f32_16x16x32_bf16 v[34:37], v[218:221], v[172:175], v[34:37]
	v_mfma_f32_16x16x32_bf16 v[22:25], v[210:213], v[194:197], v[22:25]
	v_mfma_f32_16x16x32_bf16 v[18:21], v[218:221], v[194:197], v[18:21]
	v_mfma_f32_16x16x32_bf16 v[6:9], v[210:213], v[202:205], v[6:9]
	v_mfma_f32_16x16x32_bf16 v[2:5], v[218:221], v[202:205], v[2:5]
	v_mfma_f32_16x16x32_bf16 v[54:57], v[214:217], v[168:171], v[54:57]
	v_mfma_f32_16x16x32_bf16 v[50:53], v[222:225], v[168:171], v[50:53]
	v_mfma_f32_16x16x32_bf16 v[38:41], v[214:217], v[190:193], v[38:41]
	v_mfma_f32_16x16x32_bf16 v[34:37], v[222:225], v[190:193], v[34:37]
	v_mfma_f32_16x16x32_bf16 v[22:25], v[214:217], v[198:201], v[22:25]
	v_mfma_f32_16x16x32_bf16 v[18:21], v[222:225], v[198:201], v[18:21]
	v_mfma_f32_16x16x32_bf16 v[6:9], v[214:217], v[206:209], v[6:9]
	v_mfma_f32_16x16x32_bf16 v[2:5], v[222:225], v[206:209], v[2:5]
	s_add_i32 s48, s48, 2
	s_add_u32 s46, s46, 0x100
	s_addc_u32 s47, s47, 0
	s_cmp_gt_u32 s48, 41
	s_mov_b64 s[14:15], s[16:17]
	s_barrier
	s_cbranch_scc0 .LBB0_374
	s_ashr_i32 s14, s33, 5
	s_mul_hi_i32 s15, s14, 0x9000
	s_mul_i32 s14, s14, 0x9000
	v_lshl_or_b32 v158, s45, 8, v165
	s_add_u32 s14, s26, s14
	s_addc_u32 s15, s27, s15
	v_ashrrev_i32_e32 v159, 31, v158
	v_lshl_add_u64 v[160:161], v[158:159], 2, s[14:15]
	global_load_dwordx4 v[142:145], v[160:161], off offset:16
	global_load_dwordx4 v[146:149], v[160:161], off
	v_lshl_add_u32 v162, s33, 8, v1
	v_ashrrev_i32_e32 v163, 31, v162
	s_mov_b64 s[14:15], 0x80000
	s_and_b64 vcc, exec, s[4:5]
	s_mov_b32 s45, s43
	s_mov_b32 s33, s44
	s_mov_b64 s[16:17], s[8:9]
	s_waitcnt vmcnt(0)
	v_pk_add_f32 v[144:145], v[144:145], 1.0 op_sel_hi:[1,0]
	v_pk_add_f32 v[148:149], v[148:149], 1.0 op_sel_hi:[1,0]
	v_pk_add_f32 v[146:147], v[146:147], 1.0 op_sel_hi:[1,0]
	v_pk_add_f32 v[142:143], v[142:143], 1.0 op_sel_hi:[1,0]
	v_pk_mul_f32 v[152:153], v[148:149], 0.5 op_sel_hi:[1,0]
	v_pk_mul_f32 v[156:157], v[146:147], 0.5 op_sel_hi:[1,0]
	v_pk_mul_f32 v[150:151], v[144:145], 0.5 op_sel_hi:[1,0]
	v_pk_mul_f32 v[154:155], v[142:143], 0.5 op_sel_hi:[1,0]
	global_load_dwordx4 v[142:145], v[160:161], off offset:528
	global_load_dwordx4 v[146:149], v[160:161], off offset:512
	s_waitcnt vmcnt(0)
	v_pk_add_f32 v[144:145], v[144:145], 1.0 op_sel_hi:[1,0]
	v_pk_add_f32 v[148:149], v[148:149], 1.0 op_sel_hi:[1,0]
	v_pk_add_f32 v[160:161], v[146:147], 1.0 op_sel_hi:[1,0]
	v_pk_mul_f32 v[146:147], v[148:149], 0.5 op_sel_hi:[1,0]
	v_pk_mul_f32 v[148:149], v[160:161], 0.5 op_sel_hi:[1,0]
	v_pk_add_f32 v[160:161], v[142:143], 1.0 op_sel_hi:[1,0]
	v_pk_mul_f32 v[142:143], v[144:145], 0.5 op_sel_hi:[1,0]
	v_pk_mul_f32 v[144:145], v[160:161], 0.5 op_sel_hi:[1,0]
	v_lshlrev_b64 v[160:161], 12, v[162:163]
	v_lshl_add_u64 v[168:169], s[12:13], 0, v[160:161]
	v_lshlrev_b64 v[160:161], 1, v[158:159]
	v_lshl_add_u64 v[158:159], v[168:169], 0, v[160:161]
	global_load_dwordx4 v[168:171], v[158:159], off offset:2048
	s_waitcnt vmcnt(0)
	v_lshlrev_b32_e32 v172, 16, v168
	v_and_b32_e32 v173, 0xffff0000, v168
	v_lshlrev_b32_e32 v168, 16, v169
	v_and_b32_e32 v169, 0xffff0000, v169
	v_pk_fma_f32 v[128:129], v[128:129], v[152:153], v[168:169]
	v_lshlrev_b32_e32 v168, 16, v170
	v_and_b32_e32 v169, 0xffff0000, v170
	v_pk_fma_f32 v[168:169], v[122:123], v[154:155], v[168:169]
	v_lshlrev_b32_e32 v122, 16, v171
	v_and_b32_e32 v123, 0xffff0000, v171
	v_pk_fma_f32 v[126:127], v[126:127], v[156:157], v[172:173]
	v_pk_fma_f32 v[170:171], v[124:125], v[150:151], v[122:123]
	v_cvt_pk_bf16_f32 v122, v126, v127
	v_cvt_pk_bf16_f32 v123, v128, v129
	v_cvt_pk_bf16_f32 v124, v168, v169
	v_cvt_pk_bf16_f32 v125, v170, v171
	global_store_dwordx4 v[158:159], v[122:125], off offset:2048
	global_load_dwordx4 v[122:125], v[158:159], off offset:2304
	s_waitcnt vmcnt(0)
	v_lshlrev_b32_e32 v126, 16, v122
	v_and_b32_e32 v127, 0xffff0000, v122
	v_lshlrev_b32_e32 v122, 16, v123
	v_and_b32_e32 v123, 0xffff0000, v123
	v_pk_fma_f32 v[120:121], v[120:121], v[146:147], v[122:123]
	v_lshlrev_b32_e32 v122, 16, v124
	v_and_b32_e32 v123, 0xffff0000, v124
	v_pk_fma_f32 v[122:123], v[114:115], v[144:145], v[122:123]
	v_lshlrev_b32_e32 v114, 16, v125
	v_and_b32_e32 v115, 0xffff0000, v125
	v_pk_fma_f32 v[118:119], v[118:119], v[148:149], v[126:127]
	v_pk_fma_f32 v[124:125], v[116:117], v[142:143], v[114:115]
	v_cvt_pk_bf16_f32 v114, v118, v119
	v_cvt_pk_bf16_f32 v115, v120, v121
	v_cvt_pk_bf16_f32 v116, v122, v123
	v_cvt_pk_bf16_f32 v117, v124, v125
	global_store_dwordx4 v[158:159], v[114:117], off offset:2304
	s_nop 1
	v_or_b32_e32 v114, 16, v162
	v_ashrrev_i32_e32 v115, 31, v114
	v_lshlrev_b64 v[114:115], 12, v[114:115]
	v_lshl_add_u64 v[114:115], s[12:13], 0, v[114:115]
	v_lshl_add_u64 v[118:119], v[114:115], 0, v[160:161]
	global_load_dwordx4 v[114:117], v[118:119], off offset:2048
	s_waitcnt vmcnt(0)
	v_lshlrev_b32_e32 v120, 16, v114
	v_and_b32_e32 v121, 0xffff0000, v114
	v_lshlrev_b32_e32 v114, 16, v115
	v_and_b32_e32 v115, 0xffff0000, v115
	v_pk_fma_f32 v[112:113], v[112:113], v[152:153], v[114:115]
	v_lshlrev_b32_e32 v114, 16, v116
	v_and_b32_e32 v115, 0xffff0000, v116
	v_pk_fma_f32 v[114:115], v[106:107], v[154:155], v[114:115]
	v_lshlrev_b32_e32 v106, 16, v117
	v_and_b32_e32 v107, 0xffff0000, v117
	v_pk_fma_f32 v[110:111], v[110:111], v[156:157], v[120:121]
	v_pk_fma_f32 v[116:117], v[108:109], v[150:151], v[106:107]
	v_cvt_pk_bf16_f32 v106, v110, v111
	v_cvt_pk_bf16_f32 v107, v112, v113
	v_cvt_pk_bf16_f32 v108, v114, v115
	v_cvt_pk_bf16_f32 v109, v116, v117
	global_store_dwordx4 v[118:119], v[106:109], off offset:2048
	global_load_dwordx4 v[106:109], v[118:119], off offset:2304
	s_waitcnt vmcnt(0)
	v_lshlrev_b32_e32 v110, 16, v106
	v_and_b32_e32 v111, 0xffff0000, v106
	v_lshlrev_b32_e32 v106, 16, v107
	v_and_b32_e32 v107, 0xffff0000, v107
	v_pk_fma_f32 v[104:105], v[104:105], v[146:147], v[106:107]
	v_lshlrev_b32_e32 v106, 16, v108
	v_and_b32_e32 v107, 0xffff0000, v108
	v_pk_fma_f32 v[106:107], v[98:99], v[144:145], v[106:107]
	v_lshlrev_b32_e32 v98, 16, v109
	v_and_b32_e32 v99, 0xffff0000, v109
	v_pk_fma_f32 v[102:103], v[102:103], v[148:149], v[110:111]
	v_pk_fma_f32 v[108:109], v[100:101], v[142:143], v[98:99]
	v_cvt_pk_bf16_f32 v98, v102, v103
	v_cvt_pk_bf16_f32 v99, v104, v105
	v_cvt_pk_bf16_f32 v100, v106, v107
	v_cvt_pk_bf16_f32 v101, v108, v109
	global_store_dwordx4 v[118:119], v[98:101], off offset:2304
	s_nop 1
	v_or_b32_e32 v98, 32, v162
	v_ashrrev_i32_e32 v99, 31, v98
	v_lshlrev_b64 v[98:99], 12, v[98:99]
	v_lshl_add_u64 v[98:99], s[12:13], 0, v[98:99]
	v_lshl_add_u64 v[102:103], v[98:99], 0, v[160:161]
	global_load_dwordx4 v[98:101], v[102:103], off offset:2048
	s_waitcnt vmcnt(0)
	v_lshlrev_b32_e32 v104, 16, v98
	v_and_b32_e32 v105, 0xffff0000, v98
	v_lshlrev_b32_e32 v98, 16, v99
	v_and_b32_e32 v99, 0xffff0000, v99
	v_pk_fma_f32 v[96:97], v[96:97], v[152:153], v[98:99]
	v_lshlrev_b32_e32 v98, 16, v100
	v_and_b32_e32 v99, 0xffff0000, v100
	v_pk_fma_f32 v[98:99], v[90:91], v[154:155], v[98:99]
	v_lshlrev_b32_e32 v90, 16, v101
	v_and_b32_e32 v91, 0xffff0000, v101
	v_pk_fma_f32 v[94:95], v[94:95], v[156:157], v[104:105]
	v_pk_fma_f32 v[100:101], v[92:93], v[150:151], v[90:91]
	v_cvt_pk_bf16_f32 v90, v94, v95
	v_cvt_pk_bf16_f32 v91, v96, v97
	v_cvt_pk_bf16_f32 v92, v98, v99
	v_cvt_pk_bf16_f32 v93, v100, v101
	global_store_dwordx4 v[102:103], v[90:93], off offset:2048
	global_load_dwordx4 v[90:93], v[102:103], off offset:2304
	s_waitcnt vmcnt(0)
	v_lshlrev_b32_e32 v94, 16, v90
	v_and_b32_e32 v95, 0xffff0000, v90
	v_lshlrev_b32_e32 v90, 16, v91
	v_and_b32_e32 v91, 0xffff0000, v91
	v_pk_fma_f32 v[88:89], v[88:89], v[146:147], v[90:91]
	v_lshlrev_b32_e32 v90, 16, v92
	v_and_b32_e32 v91, 0xffff0000, v92
	v_pk_fma_f32 v[90:91], v[82:83], v[144:145], v[90:91]
	v_lshlrev_b32_e32 v82, 16, v93
	v_and_b32_e32 v83, 0xffff0000, v93
	v_pk_fma_f32 v[86:87], v[86:87], v[148:149], v[94:95]
	v_pk_fma_f32 v[92:93], v[84:85], v[142:143], v[82:83]
	v_cvt_pk_bf16_f32 v82, v86, v87
	v_cvt_pk_bf16_f32 v83, v88, v89
	v_cvt_pk_bf16_f32 v84, v90, v91
	v_cvt_pk_bf16_f32 v85, v92, v93
	global_store_dwordx4 v[102:103], v[82:85], off offset:2304
	s_nop 1
	v_or_b32_e32 v82, 48, v162
	v_ashrrev_i32_e32 v83, 31, v82
	v_lshlrev_b64 v[82:83], 12, v[82:83]
	v_lshl_add_u64 v[82:83], s[12:13], 0, v[82:83]
	v_lshl_add_u64 v[82:83], v[82:83], 0, v[160:161]
	global_load_dwordx4 v[84:87], v[82:83], off offset:2048
	s_waitcnt vmcnt(0)
	v_lshlrev_b32_e32 v88, 16, v84
	v_and_b32_e32 v89, 0xffff0000, v84
	v_lshlrev_b32_e32 v84, 16, v85
	v_and_b32_e32 v85, 0xffff0000, v85
	v_pk_fma_f32 v[80:81], v[80:81], v[152:153], v[84:85]
	v_lshlrev_b32_e32 v84, 16, v86
	v_and_b32_e32 v85, 0xffff0000, v86
	v_pk_fma_f32 v[84:85], v[74:75], v[154:155], v[84:85]
	v_lshlrev_b32_e32 v74, 16, v87
	v_and_b32_e32 v75, 0xffff0000, v87
	v_pk_fma_f32 v[78:79], v[78:79], v[156:157], v[88:89]
	v_pk_fma_f32 v[86:87], v[76:77], v[150:151], v[74:75]
	v_cvt_pk_bf16_f32 v74, v78, v79
	v_cvt_pk_bf16_f32 v75, v80, v81
	v_cvt_pk_bf16_f32 v76, v84, v85
	v_cvt_pk_bf16_f32 v77, v86, v87
	global_store_dwordx4 v[82:83], v[74:77], off offset:2048
	global_load_dwordx4 v[74:77], v[82:83], off offset:2304
	s_waitcnt vmcnt(0)
	v_lshlrev_b32_e32 v78, 16, v74
	v_and_b32_e32 v79, 0xffff0000, v74
	v_lshlrev_b32_e32 v74, 16, v75
	v_and_b32_e32 v75, 0xffff0000, v75
	v_pk_fma_f32 v[72:73], v[72:73], v[146:147], v[74:75]
	v_lshlrev_b32_e32 v74, 16, v76
	v_and_b32_e32 v75, 0xffff0000, v76
	v_pk_fma_f32 v[74:75], v[66:67], v[144:145], v[74:75]
	v_lshlrev_b32_e32 v66, 16, v77
	v_and_b32_e32 v67, 0xffff0000, v77
	v_pk_fma_f32 v[70:71], v[70:71], v[148:149], v[78:79]
	v_pk_fma_f32 v[76:77], v[68:69], v[142:143], v[66:67]
	v_cvt_pk_bf16_f32 v66, v70, v71
	v_cvt_pk_bf16_f32 v67, v72, v73
	v_cvt_pk_bf16_f32 v68, v74, v75
	v_cvt_pk_bf16_f32 v69, v76, v77
	v_lshl_add_u64 v[70:71], v[158:159], 0, s[14:15]
	global_store_dwordx4 v[82:83], v[66:69], off offset:2304
	global_load_dwordx4 v[66:69], v[70:71], off offset:2048
	s_mov_b64 s[14:15], 0x90000
	s_waitcnt vmcnt(0)
	v_lshlrev_b32_e32 v72, 16, v66
	v_and_b32_e32 v73, 0xffff0000, v66
	v_lshlrev_b32_e32 v66, 16, v67
	v_and_b32_e32 v67, 0xffff0000, v67
	v_pk_fma_f32 v[64:65], v[64:65], v[152:153], v[66:67]
	v_lshlrev_b32_e32 v66, 16, v68
	v_and_b32_e32 v67, 0xffff0000, v68
	v_pk_fma_f32 v[66:67], v[58:59], v[154:155], v[66:67]
	v_lshlrev_b32_e32 v58, 16, v69
	v_and_b32_e32 v59, 0xffff0000, v69
	v_pk_fma_f32 v[62:63], v[62:63], v[156:157], v[72:73]
	v_pk_fma_f32 v[68:69], v[60:61], v[150:151], v[58:59]
	v_cvt_pk_bf16_f32 v58, v62, v63
	v_cvt_pk_bf16_f32 v59, v64, v65
	v_cvt_pk_bf16_f32 v60, v66, v67
	v_cvt_pk_bf16_f32 v61, v68, v69
	global_store_dwordx4 v[70:71], v[58:61], off offset:2048
	global_load_dwordx4 v[58:61], v[70:71], off offset:2304
	s_waitcnt vmcnt(0)
	v_lshlrev_b32_e32 v62, 16, v58
	v_and_b32_e32 v63, 0xffff0000, v58
	v_lshlrev_b32_e32 v58, 16, v59
	v_and_b32_e32 v59, 0xffff0000, v59
	v_pk_fma_f32 v[56:57], v[56:57], v[146:147], v[58:59]
	v_lshlrev_b32_e32 v58, 16, v60
	v_and_b32_e32 v59, 0xffff0000, v60
	v_pk_fma_f32 v[58:59], v[50:51], v[144:145], v[58:59]
	v_lshlrev_b32_e32 v50, 16, v61
	v_and_b32_e32 v51, 0xffff0000, v61
	v_pk_fma_f32 v[54:55], v[54:55], v[148:149], v[62:63]
	v_pk_fma_f32 v[60:61], v[52:53], v[142:143], v[50:51]
	v_cvt_pk_bf16_f32 v50, v54, v55
	v_cvt_pk_bf16_f32 v51, v56, v57
	v_cvt_pk_bf16_f32 v52, v58, v59
	v_cvt_pk_bf16_f32 v53, v60, v61
	v_lshl_add_u64 v[54:55], v[158:159], 0, s[14:15]
	global_store_dwordx4 v[70:71], v[50:53], off offset:2304
	global_load_dwordx4 v[50:53], v[54:55], off offset:2048
	s_mov_b64 s[14:15], 0xa0000
	s_waitcnt vmcnt(0)
	v_lshlrev_b32_e32 v56, 16, v50
	v_and_b32_e32 v57, 0xffff0000, v50
	v_lshlrev_b32_e32 v50, 16, v51
	v_and_b32_e32 v51, 0xffff0000, v51
	v_pk_fma_f32 v[48:49], v[48:49], v[152:153], v[50:51]
	v_lshlrev_b32_e32 v50, 16, v52
	v_and_b32_e32 v51, 0xffff0000, v52
	v_pk_fma_f32 v[50:51], v[42:43], v[154:155], v[50:51]
	v_lshlrev_b32_e32 v42, 16, v53
	v_and_b32_e32 v43, 0xffff0000, v53
	v_pk_fma_f32 v[46:47], v[46:47], v[156:157], v[56:57]
	v_pk_fma_f32 v[52:53], v[44:45], v[150:151], v[42:43]
	v_cvt_pk_bf16_f32 v42, v46, v47
	v_cvt_pk_bf16_f32 v43, v48, v49
	v_cvt_pk_bf16_f32 v44, v50, v51
	v_cvt_pk_bf16_f32 v45, v52, v53
	global_store_dwordx4 v[54:55], v[42:45], off offset:2048
	global_load_dwordx4 v[42:45], v[54:55], off offset:2304
	s_waitcnt vmcnt(0)
	v_lshlrev_b32_e32 v46, 16, v42
	v_and_b32_e32 v47, 0xffff0000, v42
	v_lshlrev_b32_e32 v42, 16, v43
	v_and_b32_e32 v43, 0xffff0000, v43
	v_pk_fma_f32 v[40:41], v[40:41], v[146:147], v[42:43]
	v_lshlrev_b32_e32 v42, 16, v44
	v_and_b32_e32 v43, 0xffff0000, v44
	v_pk_fma_f32 v[42:43], v[34:35], v[144:145], v[42:43]
	v_lshlrev_b32_e32 v34, 16, v45
	v_and_b32_e32 v35, 0xffff0000, v45
	v_pk_fma_f32 v[38:39], v[38:39], v[148:149], v[46:47]
	v_pk_fma_f32 v[44:45], v[36:37], v[142:143], v[34:35]
	v_cvt_pk_bf16_f32 v34, v38, v39
	v_cvt_pk_bf16_f32 v35, v40, v41
	v_cvt_pk_bf16_f32 v36, v42, v43
	v_cvt_pk_bf16_f32 v37, v44, v45
	v_lshl_add_u64 v[38:39], v[158:159], 0, s[14:15]
	global_store_dwordx4 v[54:55], v[34:37], off offset:2304
	global_load_dwordx4 v[34:37], v[38:39], off offset:2048
	s_mov_b64 s[14:15], 0xb0000
	s_waitcnt vmcnt(0)
	v_lshlrev_b32_e32 v40, 16, v34
	v_and_b32_e32 v41, 0xffff0000, v34
	v_lshlrev_b32_e32 v34, 16, v35
	v_and_b32_e32 v35, 0xffff0000, v35
	v_pk_fma_f32 v[32:33], v[32:33], v[152:153], v[34:35]
	v_lshlrev_b32_e32 v34, 16, v36
	v_and_b32_e32 v35, 0xffff0000, v36
	v_pk_fma_f32 v[34:35], v[26:27], v[154:155], v[34:35]
	v_lshlrev_b32_e32 v26, 16, v37
	v_and_b32_e32 v27, 0xffff0000, v37
	v_pk_fma_f32 v[30:31], v[30:31], v[156:157], v[40:41]
	v_pk_fma_f32 v[36:37], v[28:29], v[150:151], v[26:27]
	v_cvt_pk_bf16_f32 v26, v30, v31
	v_cvt_pk_bf16_f32 v27, v32, v33
	v_cvt_pk_bf16_f32 v28, v34, v35
	v_cvt_pk_bf16_f32 v29, v36, v37
	global_store_dwordx4 v[38:39], v[26:29], off offset:2048
	global_load_dwordx4 v[26:29], v[38:39], off offset:2304
	s_waitcnt vmcnt(0)
	v_lshlrev_b32_e32 v30, 16, v26
	v_and_b32_e32 v31, 0xffff0000, v26
	v_lshlrev_b32_e32 v26, 16, v27
	v_and_b32_e32 v27, 0xffff0000, v27
	v_pk_fma_f32 v[24:25], v[24:25], v[146:147], v[26:27]
	v_lshlrev_b32_e32 v26, 16, v28
	v_and_b32_e32 v27, 0xffff0000, v28
	v_pk_fma_f32 v[26:27], v[18:19], v[144:145], v[26:27]
	v_lshlrev_b32_e32 v18, 16, v29
	v_and_b32_e32 v19, 0xffff0000, v29
	v_pk_fma_f32 v[22:23], v[22:23], v[148:149], v[30:31]
	v_pk_fma_f32 v[28:29], v[20:21], v[142:143], v[18:19]
	v_cvt_pk_bf16_f32 v18, v22, v23
	v_cvt_pk_bf16_f32 v19, v24, v25
	v_cvt_pk_bf16_f32 v20, v26, v27
	v_cvt_pk_bf16_f32 v21, v28, v29
	global_store_dwordx4 v[38:39], v[18:21], off offset:2304
	s_nop 1
	v_lshl_add_u64 v[18:19], v[158:159], 0, s[14:15]
	global_load_dwordx4 v[20:23], v[18:19], off offset:2048
	s_mov_b64 s[14:15], s[6:7]
	s_waitcnt vmcnt(0)
	v_lshlrev_b32_e32 v24, 16, v20
	v_and_b32_e32 v25, 0xffff0000, v20
	v_lshlrev_b32_e32 v20, 16, v21
	v_and_b32_e32 v21, 0xffff0000, v21
	v_pk_fma_f32 v[16:17], v[16:17], v[152:153], v[20:21]
	v_lshlrev_b32_e32 v20, 16, v22
	v_and_b32_e32 v21, 0xffff0000, v22
	v_pk_fma_f32 v[20:21], v[10:11], v[154:155], v[20:21]
	v_lshlrev_b32_e32 v10, 16, v23
	v_and_b32_e32 v11, 0xffff0000, v23
	v_pk_fma_f32 v[14:15], v[14:15], v[156:157], v[24:25]
	v_pk_fma_f32 v[22:23], v[12:13], v[150:151], v[10:11]
	v_cvt_pk_bf16_f32 v10, v14, v15
	v_cvt_pk_bf16_f32 v11, v16, v17
	v_cvt_pk_bf16_f32 v12, v20, v21
	v_cvt_pk_bf16_f32 v13, v22, v23
	global_store_dwordx4 v[18:19], v[10:13], off offset:2048
	global_load_dwordx4 v[10:13], v[18:19], off offset:2304
	s_waitcnt vmcnt(0)
	v_lshlrev_b32_e32 v14, 16, v10
	v_and_b32_e32 v15, 0xffff0000, v10
	v_lshlrev_b32_e32 v10, 16, v11
	v_and_b32_e32 v11, 0xffff0000, v11
	v_pk_fma_f32 v[8:9], v[8:9], v[146:147], v[10:11]
	v_lshlrev_b32_e32 v10, 16, v12
	v_and_b32_e32 v11, 0xffff0000, v12
	v_pk_fma_f32 v[10:11], v[2:3], v[144:145], v[10:11]
	v_lshlrev_b32_e32 v2, 16, v13
	v_and_b32_e32 v3, 0xffff0000, v13
	v_pk_fma_f32 v[6:7], v[6:7], v[148:149], v[14:15]
	v_pk_fma_f32 v[12:13], v[4:5], v[142:143], v[2:3]
	v_cvt_pk_bf16_f32 v2, v6, v7
	v_cvt_pk_bf16_f32 v3, v8, v9
	v_cvt_pk_bf16_f32 v4, v10, v11
	v_cvt_pk_bf16_f32 v5, v12, v13
	global_store_dwordx4 v[18:19], v[2:5], off offset:2304
	s_cbranch_vccz .LBB0_363
	s_waitcnt vmcnt(0)
	s_cmpk_gt_u32 s30, 0xff
	s_cbranch_scc1 .LBB0_378
	s_barrier

.LBB0_400:
	s_add_u32 s16, s14, 0x100
	s_addc_u32 s17, s15, 0
	s_add_i32 s49, 0, 0x10000
	v_add_u32_e32 v154, s49, v164
	ds_read_b128 v[142:145], v154
	ds_read_b128 v[146:149], v154 offset:1024
	ds_read_b128 v[150:153], v154 offset:2048
	ds_read_b128 v[154:157], v154 offset:3072
	s_cmp_eq_u32 s48, 40
	s_cselect_b32 s21, s7, s17
	s_cselect_b32 s20, s6, s16
	s_cselect_b32 s19, s9, s47
	s_cselect_b32 s18, s8, s46
	v_lshl_add_u64 v[162:163], s[14:15], 0, v[138:139]
	s_add_i32 m0, s34, 0xc000
	ds_read_b128 v[158:161], v166
	ds_read_b128 v[168:171], v166 offset:1024
	ds_read_b128 v[172:175], v166 offset:2048
	ds_read_b128 v[190:193], v166 offset:3072
	ds_read_b128 v[194:197], v166 offset:4096
	ds_read_b128 v[198:201], v166 offset:5120
	ds_read_b128 v[202:205], v166 offset:6144
	ds_read_b128 v[206:209], v166 offset:7168
	global_load_lds_dwordx4 v[162:163], off
	v_lshl_add_u64 v[162:163], s[14:15], 0, v[140:141]
	s_add_i32 m0, s34, 0xe000
	s_nop 0
	global_load_lds_dwordx4 v[162:163], off
	s_waitcnt lgkmcnt(8)
	s_barrier
	s_waitcnt lgkmcnt(0)
	s_waitcnt lgkmcnt(0)
	v_mfma_f32_16x16x32_bf16 v[126:129], v[142:145], v[158:161], v[126:129]
	v_mfma_f32_16x16x32_bf16 v[122:125], v[150:153], v[158:161], v[122:125]
	v_mfma_f32_16x16x32_bf16 v[110:113], v[142:145], v[172:175], v[110:113]
	v_mfma_f32_16x16x32_bf16 v[106:109], v[150:153], v[172:175], v[106:109]
	v_mfma_f32_16x16x32_bf16 v[94:97], v[142:145], v[194:197], v[94:97]
	v_mfma_f32_16x16x32_bf16 v[90:93], v[150:153], v[194:197], v[90:93]
	v_mfma_f32_16x16x32_bf16 v[78:81], v[142:145], v[202:205], v[78:81]
	v_mfma_f32_16x16x32_bf16 v[74:77], v[150:153], v[202:205], v[74:77]
	v_mfma_f32_16x16x32_bf16 v[126:129], v[146:149], v[168:171], v[126:129]
	v_mfma_f32_16x16x32_bf16 v[122:125], v[154:157], v[168:171], v[122:125]
	v_mfma_f32_16x16x32_bf16 v[110:113], v[146:149], v[190:193], v[110:113]
	v_mfma_f32_16x16x32_bf16 v[106:109], v[154:157], v[190:193], v[106:109]
	v_mfma_f32_16x16x32_bf16 v[94:97], v[146:149], v[198:201], v[94:97]
	v_mfma_f32_16x16x32_bf16 v[90:93], v[154:157], v[198:201], v[90:93]
	v_mfma_f32_16x16x32_bf16 v[78:81], v[146:149], v[206:209], v[78:81]
	v_mfma_f32_16x16x32_bf16 v[74:77], v[154:157], v[206:209], v[74:77]
	s_barrier
	s_add_i32 s50, 0, 0x14000
	v_add_u32_e32 v162, s50, v164
	s_add_i32 s14, s49, s33
	ds_read_b128 v[210:213], v162
	ds_read_b128 v[214:217], v162 offset:1024
	ds_read_b128 v[218:221], v162 offset:2048
	ds_read_b128 v[222:225], v162 offset:3072
	s_add_u32 s64, s18, 0x80
	s_addc_u32 s65, s19, 0
	s_mov_b32 m0, s14
	s_nop 0
	global_load_lds_dwordx4 v132, s[18:19]
	s_add_i32 m0, s14, 0x2000
	s_nop 0
	global_load_lds_dwordx4 v136, s[18:19]
	s_barrier
	s_waitcnt lgkmcnt(0)
	s_waitcnt lgkmcnt(0)
	v_mfma_f32_16x16x32_bf16 v[118:121], v[210:213], v[158:161], v[118:121]
	v_mfma_f32_16x16x32_bf16 v[114:117], v[218:221], v[158:161], v[114:117]
	v_mfma_f32_16x16x32_bf16 v[102:105], v[210:213], v[172:175], v[102:105]
	v_mfma_f32_16x16x32_bf16 v[98:101], v[218:221], v[172:175], v[98:101]
	v_mfma_f32_16x16x32_bf16 v[86:89], v[210:213], v[194:197], v[86:89]
	v_mfma_f32_16x16x32_bf16 v[82:85], v[218:221], v[194:197], v[82:85]
	v_mfma_f32_16x16x32_bf16 v[70:73], v[210:213], v[202:205], v[70:73]
	v_mfma_f32_16x16x32_bf16 v[66:69], v[218:221], v[202:205], v[66:69]
	v_mfma_f32_16x16x32_bf16 v[118:121], v[214:217], v[168:171], v[118:121]
	v_mfma_f32_16x16x32_bf16 v[114:117], v[222:225], v[168:171], v[114:117]
	v_mfma_f32_16x16x32_bf16 v[102:105], v[214:217], v[190:193], v[102:105]
	v_mfma_f32_16x16x32_bf16 v[98:101], v[222:225], v[190:193], v[98:101]
	v_mfma_f32_16x16x32_bf16 v[86:89], v[214:217], v[198:201], v[86:89]
	v_mfma_f32_16x16x32_bf16 v[82:85], v[222:225], v[198:201], v[82:85]
	v_mfma_f32_16x16x32_bf16 v[70:73], v[214:217], v[206:209], v[70:73]
	v_mfma_f32_16x16x32_bf16 v[66:69], v[222:225], v[206:209], v[66:69]
	s_mov_b32 m0, s34
	s_add_u32 s62, s20, 0x80
	s_addc_u32 s63, s21, 0
	s_barrier
	ds_read_b128 v[158:161], v166 offset:16384
	ds_read_b128 v[168:171], v166 offset:17408
	ds_read_b128 v[172:175], v166 offset:18432
	ds_read_b128 v[190:193], v166 offset:19456
	ds_read_b128 v[194:197], v166 offset:20480
	ds_read_b128 v[198:201], v166 offset:21504
	ds_read_b128 v[202:205], v166 offset:22528
	ds_read_b128 v[206:209], v166 offset:23552
	global_load_lds_dwordx4 v130, s[20:21]
	s_mov_b32 m0, s35
	s_nop 0
	global_load_lds_dwordx4 v134, s[20:21]
	s_barrier
	s_waitcnt lgkmcnt(0)
	s_waitcnt lgkmcnt(0)
	v_mfma_f32_16x16x32_bf16 v[62:65], v[142:145], v[158:161], v[62:65]
	v_mfma_f32_16x16x32_bf16 v[58:61], v[150:153], v[158:161], v[58:61]
	v_mfma_f32_16x16x32_bf16 v[46:49], v[142:145], v[172:175], v[46:49]
	v_mfma_f32_16x16x32_bf16 v[42:45], v[150:153], v[172:175], v[42:45]
	v_mfma_f32_16x16x32_bf16 v[30:33], v[142:145], v[194:197], v[30:33]
	v_mfma_f32_16x16x32_bf16 v[26:29], v[150:153], v[194:197], v[26:29]
	v_mfma_f32_16x16x32_bf16 v[14:17], v[142:145], v[202:205], v[14:17]
	v_mfma_f32_16x16x32_bf16 v[10:13], v[150:153], v[202:205], v[10:13]
	v_mfma_f32_16x16x32_bf16 v[62:65], v[146:149], v[168:171], v[62:65]
	v_mfma_f32_16x16x32_bf16 v[58:61], v[154:157], v[168:171], v[58:61]
	v_mfma_f32_16x16x32_bf16 v[46:49], v[146:149], v[190:193], v[46:49]
	v_mfma_f32_16x16x32_bf16 v[42:45], v[154:157], v[190:193], v[42:45]
	v_mfma_f32_16x16x32_bf16 v[30:33], v[146:149], v[198:201], v[30:33]
	v_mfma_f32_16x16x32_bf16 v[26:29], v[154:157], v[198:201], v[26:29]
	v_mfma_f32_16x16x32_bf16 v[14:17], v[146:149], v[206:209], v[14:17]
	v_mfma_f32_16x16x32_bf16 v[10:13], v[154:157], v[206:209], v[10:13]
	s_barrier
	s_add_u32 s14, s18, 0xb0000
	s_addc_u32 s15, s19, 0
	s_add_i32 s49, s50, s33
	s_mov_b32 m0, s49
	s_nop 0
	global_load_lds_dwordx4 v132, s[14:15]
	s_add_i32 m0, s49, 0x2000
	s_nop 0
	global_load_lds_dwordx4 v136, s[14:15]
	s_waitcnt vmcnt(6)
	s_barrier
	v_mfma_f32_16x16x32_bf16 v[54:57], v[210:213], v[158:161], v[54:57]
	v_mfma_f32_16x16x32_bf16 v[50:53], v[218:221], v[158:161], v[50:53]
	v_mfma_f32_16x16x32_bf16 v[38:41], v[210:213], v[172:175], v[38:41]
	v_mfma_f32_16x16x32_bf16 v[34:37], v[218:221], v[172:175], v[34:37]
	v_mfma_f32_16x16x32_bf16 v[22:25], v[210:213], v[194:197], v[22:25]
	v_mfma_f32_16x16x32_bf16 v[18:21], v[218:221], v[194:197], v[18:21]
	v_mfma_f32_16x16x32_bf16 v[6:9], v[210:213], v[202:205], v[6:9]
	v_mfma_f32_16x16x32_bf16 v[2:5], v[218:221], v[202:205], v[2:5]
	v_mfma_f32_16x16x32_bf16 v[54:57], v[214:217], v[168:171], v[54:57]
	v_mfma_f32_16x16x32_bf16 v[50:53], v[222:225], v[168:171], v[50:53]
	v_mfma_f32_16x16x32_bf16 v[38:41], v[214:217], v[190:193], v[38:41]
	v_mfma_f32_16x16x32_bf16 v[34:37], v[222:225], v[190:193], v[34:37]
	v_mfma_f32_16x16x32_bf16 v[22:25], v[214:217], v[198:201], v[22:25]
	v_mfma_f32_16x16x32_bf16 v[18:21], v[222:225], v[198:201], v[18:21]
	v_mfma_f32_16x16x32_bf16 v[6:9], v[214:217], v[206:209], v[6:9]
	v_mfma_f32_16x16x32_bf16 v[2:5], v[222:225], v[206:209], v[2:5]
	s_add_i32 s49, 0, 0x18000
	v_add_u32_e32 v154, s49, v164
	ds_read_b128 v[142:145], v154
	ds_read_b128 v[146:149], v154 offset:1024
	ds_read_b128 v[150:153], v154 offset:2048
	ds_read_b128 v[154:157], v154 offset:3072
	s_barrier
	s_add_u32 s14, s20, 0xb8000
	s_addc_u32 s15, s21, 0
	s_mov_b32 m0, s36
	ds_read_b128 v[158:161], v166 offset:32768
	ds_read_b128 v[168:171], v166 offset:33792
	ds_read_b128 v[172:175], v166 offset:34816
	ds_read_b128 v[190:193], v166 offset:35840
	ds_read_b128 v[194:197], v166 offset:36864
	ds_read_b128 v[198:201], v166 offset:37888
	ds_read_b128 v[202:205], v166 offset:38912
	ds_read_b128 v[206:209], v166 offset:39936
	global_load_lds_dwordx4 v130, s[14:15]
	s_mov_b32 m0, s37
	s_nop 0
	global_load_lds_dwordx4 v134, s[14:15]
	s_waitcnt lgkmcnt(8)
	s_barrier
	s_waitcnt lgkmcnt(0)
	s_waitcnt lgkmcnt(0)
	v_mfma_f32_16x16x32_bf16 v[126:129], v[142:145], v[158:161], v[126:129]
	v_mfma_f32_16x16x32_bf16 v[122:125], v[150:153], v[158:161], v[122:125]
	v_mfma_f32_16x16x32_bf16 v[110:113], v[142:145], v[172:175], v[110:113]
	v_mfma_f32_16x16x32_bf16 v[106:109], v[150:153], v[172:175], v[106:109]
	v_mfma_f32_16x16x32_bf16 v[94:97], v[142:145], v[194:197], v[94:97]
	v_mfma_f32_16x16x32_bf16 v[90:93], v[150:153], v[194:197], v[90:93]
	v_mfma_f32_16x16x32_bf16 v[78:81], v[142:145], v[202:205], v[78:81]
	v_mfma_f32_16x16x32_bf16 v[74:77], v[150:153], v[202:205], v[74:77]
	v_mfma_f32_16x16x32_bf16 v[126:129], v[146:149], v[168:171], v[126:129]
	v_mfma_f32_16x16x32_bf16 v[122:125], v[154:157], v[168:171], v[122:125]
	v_mfma_f32_16x16x32_bf16 v[110:113], v[146:149], v[190:193], v[110:113]
	v_mfma_f32_16x16x32_bf16 v[106:109], v[154:157], v[190:193], v[106:109]
	v_mfma_f32_16x16x32_bf16 v[94:97], v[146:149], v[198:201], v[94:97]
	v_mfma_f32_16x16x32_bf16 v[90:93], v[154:157], v[198:201], v[90:93]
	v_mfma_f32_16x16x32_bf16 v[78:81], v[146:149], v[206:209], v[78:81]
	v_mfma_f32_16x16x32_bf16 v[74:77], v[154:157], v[206:209], v[74:77]
	s_barrier
	s_add_i32 s20, 0, 0x1c000
	s_add_i32 s14, s49, s33
	v_add_u32_e32 v167, s20, v164
	s_mov_b32 m0, s14
	ds_read_b128 v[210:213], v167
	ds_read_b128 v[214:217], v167 offset:1024
	ds_read_b128 v[218:221], v167 offset:2048
	ds_read_b128 v[222:225], v167 offset:3072
	global_load_lds_dwordx4 v132, s[64:65]
	s_add_i32 m0, s14, 0x2000
	s_nop 0
	global_load_lds_dwordx4 v136, s[64:65]
	s_barrier
	s_waitcnt lgkmcnt(0)
	s_waitcnt lgkmcnt(0)
	v_mfma_f32_16x16x32_bf16 v[118:121], v[210:213], v[158:161], v[118:121]
	v_mfma_f32_16x16x32_bf16 v[114:117], v[218:221], v[158:161], v[114:117]
	v_mfma_f32_16x16x32_bf16 v[102:105], v[210:213], v[172:175], v[102:105]
	v_mfma_f32_16x16x32_bf16 v[98:101], v[218:221], v[172:175], v[98:101]
	v_mfma_f32_16x16x32_bf16 v[86:89], v[210:213], v[194:197], v[86:89]
	v_mfma_f32_16x16x32_bf16 v[82:85], v[218:221], v[194:197], v[82:85]
	v_mfma_f32_16x16x32_bf16 v[70:73], v[210:213], v[202:205], v[70:73]
	v_mfma_f32_16x16x32_bf16 v[66:69], v[218:221], v[202:205], v[66:69]
	v_mfma_f32_16x16x32_bf16 v[118:121], v[214:217], v[168:171], v[118:121]
	v_mfma_f32_16x16x32_bf16 v[114:117], v[222:225], v[168:171], v[114:117]
	v_mfma_f32_16x16x32_bf16 v[102:105], v[214:217], v[190:193], v[102:105]
	v_mfma_f32_16x16x32_bf16 v[98:101], v[222:225], v[190:193], v[98:101]
	v_mfma_f32_16x16x32_bf16 v[86:89], v[214:217], v[198:201], v[86:89]
	v_mfma_f32_16x16x32_bf16 v[82:85], v[222:225], v[198:201], v[82:85]
	v_mfma_f32_16x16x32_bf16 v[70:73], v[214:217], v[206:209], v[70:73]
	v_mfma_f32_16x16x32_bf16 v[66:69], v[222:225], v[206:209], v[66:69]
	s_mov_b32 m0, s38
	s_barrier
	ds_read_b128 v[158:161], v166 offset:49152
	ds_read_b128 v[168:171], v166 offset:50176
	ds_read_b128 v[172:175], v166 offset:51200
	ds_read_b128 v[190:193], v166 offset:52224
	ds_read_b128 v[194:197], v166 offset:53248
	ds_read_b128 v[198:201], v166 offset:54272
	ds_read_b128 v[202:205], v166 offset:55296
	ds_read_b128 v[206:209], v166 offset:56320
	global_load_lds_dwordx4 v130, s[62:63]
	s_mov_b32 m0, s39
	s_nop 0
	global_load_lds_dwordx4 v134, s[62:63]
	s_barrier
	s_waitcnt lgkmcnt(0)
	s_waitcnt lgkmcnt(0)
	v_mfma_f32_16x16x32_bf16 v[62:65], v[142:145], v[158:161], v[62:65]
	v_mfma_f32_16x16x32_bf16 v[58:61], v[150:153], v[158:161], v[58:61]
	v_mfma_f32_16x16x32_bf16 v[46:49], v[142:145], v[172:175], v[46:49]
	v_mfma_f32_16x16x32_bf16 v[42:45], v[150:153], v[172:175], v[42:45]
	v_mfma_f32_16x16x32_bf16 v[30:33], v[142:145], v[194:197], v[30:33]
	v_mfma_f32_16x16x32_bf16 v[26:29], v[150:153], v[194:197], v[26:29]
	v_mfma_f32_16x16x32_bf16 v[14:17], v[142:145], v[202:205], v[14:17]
	v_mfma_f32_16x16x32_bf16 v[10:13], v[150:153], v[202:205], v[10:13]
	v_mfma_f32_16x16x32_bf16 v[62:65], v[146:149], v[168:171], v[62:65]
	v_mfma_f32_16x16x32_bf16 v[58:61], v[154:157], v[168:171], v[58:61]
	v_mfma_f32_16x16x32_bf16 v[46:49], v[146:149], v[190:193], v[46:49]
	v_mfma_f32_16x16x32_bf16 v[42:45], v[154:157], v[190:193], v[42:45]
	v_mfma_f32_16x16x32_bf16 v[30:33], v[146:149], v[198:201], v[30:33]
	v_mfma_f32_16x16x32_bf16 v[26:29], v[154:157], v[198:201], v[26:29]
	v_mfma_f32_16x16x32_bf16 v[14:17], v[146:149], v[206:209], v[14:17]
	v_mfma_f32_16x16x32_bf16 v[10:13], v[154:157], v[206:209], v[10:13]
	s_barrier
	s_add_u32 s14, s18, 0xb0080
	s_addc_u32 s15, s19, 0
	s_add_i32 s18, s20, s33
	s_mov_b32 m0, s18
	s_nop 0
	global_load_lds_dwordx4 v132, s[14:15]
	s_add_i32 m0, s18, 0x2000
	s_nop 0
	global_load_lds_dwordx4 v136, s[14:15]
	s_waitcnt vmcnt(6)
	s_barrier
	v_mfma_f32_16x16x32_bf16 v[54:57], v[210:213], v[158:161], v[54:57]
	v_mfma_f32_16x16x32_bf16 v[50:53], v[218:221], v[158:161], v[50:53]
	v_mfma_f32_16x16x32_bf16 v[38:41], v[210:213], v[172:175], v[38:41]
	v_mfma_f32_16x16x32_bf16 v[34:37], v[218:221], v[172:175], v[34:37]
	v_mfma_f32_16x16x32_bf16 v[22:25], v[210:213], v[194:197], v[22:25]
	v_mfma_f32_16x16x32_bf16 v[18:21], v[218:221], v[194:197], v[18:21]
	v_mfma_f32_16x16x32_bf16 v[6:9], v[210:213], v[202:205], v[6:9]
	v_mfma_f32_16x16x32_bf16 v[2:5], v[218:221], v[202:205], v[2:5]
	v_mfma_f32_16x16x32_bf16 v[54:57], v[214:217], v[168:171], v[54:57]
	v_mfma_f32_16x16x32_bf16 v[50:53], v[222:225], v[168:171], v[50:53]
	v_mfma_f32_16x16x32_bf16 v[38:41], v[214:217], v[190:193], v[38:41]
	v_mfma_f32_16x16x32_bf16 v[34:37], v[222:225], v[190:193], v[34:37]
	v_mfma_f32_16x16x32_bf16 v[22:25], v[214:217], v[198:201], v[22:25]
	v_mfma_f32_16x16x32_bf16 v[18:21], v[222:225], v[198:201], v[18:21]
	v_mfma_f32_16x16x32_bf16 v[6:9], v[214:217], v[206:209], v[6:9]
	v_mfma_f32_16x16x32_bf16 v[2:5], v[222:225], v[206:209], v[2:5]
	s_add_i32 s48, s48, 2
	s_add_u32 s46, s46, 0x100
	s_addc_u32 s47, s47, 0
	s_cmp_gt_u32 s48, 41
	s_mov_b64 s[14:15], s[16:17]
	s_barrier
	s_cbranch_scc0 .LBB0_400
	s_ashr_i32 s14, s44, 5
	v_lshl_or_b32 v176, s45, 8, v165
	s_mul_hi_i32 s15, s14, 0x9000
	s_mul_i32 s14, s14, 0x9000
	s_add_u32 s14, s26, s14
	v_ashrrev_i32_e32 v177, 31, v176
	s_addc_u32 s15, s27, s15
	v_lshlrev_b64 v[158:159], 2, v[176:177]
	v_lshl_add_u64 v[160:161], s[14:15], 0, v[158:159]
	global_load_dwordx4 v[142:145], v[160:161], off offset:16
	global_load_dwordx4 v[146:149], v[160:161], off
	v_lshl_add_u32 v162, s44, 8, v1
	v_ashrrev_i32_e32 v163, 31, v162
	s_mov_b64 s[14:15], 0x80000
	s_and_b64 vcc, exec, s[4:5]
	s_mov_b32 s45, s42
	s_mov_b32 s44, s43
	s_mov_b64 s[16:17], s[8:9]
	s_waitcnt vmcnt(0)
	v_pk_add_f32 v[144:145], v[144:145], 1.0 op_sel_hi:[1,0]
	v_pk_add_f32 v[148:149], v[148:149], 1.0 op_sel_hi:[1,0]
	v_pk_add_f32 v[146:147], v[146:147], 1.0 op_sel_hi:[1,0]
	v_pk_add_f32 v[142:143], v[142:143], 1.0 op_sel_hi:[1,0]
	v_pk_mul_f32 v[150:151], v[148:149], 0.5 op_sel_hi:[1,0]
	v_pk_mul_f32 v[152:153], v[146:147], 0.5 op_sel_hi:[1,0]
	v_pk_mul_f32 v[154:155], v[144:145], 0.5 op_sel_hi:[1,0]
	v_pk_mul_f32 v[156:157], v[142:143], 0.5 op_sel_hi:[1,0]
	global_load_dwordx4 v[146:149], v[160:161], off offset:528
	global_load_dwordx4 v[142:145], v[160:161], off offset:512
	s_waitcnt vmcnt(0)
	v_pk_add_f32 v[148:149], v[148:149], 1.0 op_sel_hi:[1,0]
	v_pk_add_f32 v[144:145], v[144:145], 1.0 op_sel_hi:[1,0]
	v_pk_add_f32 v[160:161], v[142:143], 1.0 op_sel_hi:[1,0]
	v_pk_mul_f32 v[142:143], v[144:145], 0.5 op_sel_hi:[1,0]
	v_pk_mul_f32 v[144:145], v[160:161], 0.5 op_sel_hi:[1,0]
	v_pk_add_f32 v[160:161], v[146:147], 1.0 op_sel_hi:[1,0]
	v_pk_mul_f32 v[146:147], v[148:149], 0.5 op_sel_hi:[1,0]
	v_pk_mul_f32 v[148:149], v[160:161], 0.5 op_sel_hi:[1,0]
	v_lshlrev_b64 v[160:161], 12, v[162:163]
	v_lshl_add_u64 v[168:169], s[2:3], 0, v[160:161]
	v_lshl_add_u64 v[186:187], v[168:169], 0, v[158:159]
	global_load_dwordx4 v[168:171], v[186:187], off offset:16
	global_load_dwordx4 v[172:175], v[186:187], off
	s_waitcnt vmcnt(0)
	v_pk_fma_f32 v[122:123], v[122:123], v[156:157], v[168:169]
	v_pk_fma_f32 v[128:129], v[128:129], v[150:151], v[174:175]
	v_pk_fma_f32 v[126:127], v[126:127], v[152:153], v[172:173]
	v_pk_fma_f32 v[170:171], v[124:125], v[154:155], v[170:171]
	v_cvt_pk_bf16_f32 v124, v126, v127
	v_cvt_pk_bf16_f32 v125, v128, v129
	v_cvt_pk_bf16_f32 v126, v122, v123
	v_lshl_add_u64 v[128:129], s[12:13], 0, v[160:161]
	v_lshlrev_b64 v[122:123], 1, v[176:177]
	v_cvt_pk_bf16_f32 v127, v170, v171
	v_lshl_add_u64 v[128:129], v[128:129], 0, v[122:123]
	global_store_dwordx4 v[128:129], v[124:127], off offset:2048
	global_load_dwordx4 v[124:127], v[186:187], off offset:528
	s_nop 0
	global_load_dwordx4 v[168:171], v[186:187], off offset:512
	s_waitcnt vmcnt(0)
	v_pk_fma_f32 v[126:127], v[116:117], v[146:147], v[126:127]
	v_pk_fma_f32 v[120:121], v[120:121], v[142:143], v[170:171]
	v_pk_fma_f32 v[118:119], v[118:119], v[144:145], v[168:169]
	v_pk_fma_f32 v[116:117], v[114:115], v[148:149], v[124:125]
	v_cvt_pk_bf16_f32 v114, v118, v119
	v_cvt_pk_bf16_f32 v115, v120, v121
	v_cvt_pk_bf16_f32 v116, v116, v117
	v_cvt_pk_bf16_f32 v117, v126, v127
	global_store_dwordx4 v[128:129], v[114:117], off offset:2304
	s_nop 1
	v_or_b32_e32 v114, 16, v162
	v_ashrrev_i32_e32 v115, 31, v114
	v_lshlrev_b64 v[124:125], 12, v[114:115]
	v_lshl_add_u64 v[114:115], s[2:3], 0, v[124:125]
	v_lshl_add_u64 v[126:127], v[114:115], 0, v[158:159]
	global_load_dwordx4 v[114:117], v[126:127], off offset:16
	global_load_dwordx4 v[118:121], v[126:127], off
	s_waitcnt vmcnt(0)
	v_pk_fma_f32 v[116:117], v[108:109], v[154:155], v[116:117]
	v_pk_fma_f32 v[110:111], v[110:111], v[152:153], v[118:119]
	v_pk_fma_f32 v[112:113], v[112:113], v[150:151], v[120:121]
	v_pk_fma_f32 v[108:109], v[106:107], v[156:157], v[114:115]
	v_cvt_pk_bf16_f32 v106, v110, v111
	v_lshl_add_u64 v[110:111], s[12:13], 0, v[124:125]
	v_cvt_pk_bf16_f32 v107, v112, v113
	v_cvt_pk_bf16_f32 v108, v108, v109
	v_cvt_pk_bf16_f32 v109, v116, v117
	v_lshl_add_u64 v[114:115], v[110:111], 0, v[122:123]
	global_store_dwordx4 v[114:115], v[106:109], off offset:2048
	global_load_dwordx4 v[106:109], v[126:127], off offset:528
	s_nop 0
	global_load_dwordx4 v[110:113], v[126:127], off offset:512
	s_waitcnt vmcnt(0)
	v_pk_fma_f32 v[108:109], v[100:101], v[146:147], v[108:109]
	v_pk_fma_f32 v[104:105], v[104:105], v[142:143], v[112:113]
	v_pk_fma_f32 v[102:103], v[102:103], v[144:145], v[110:111]
	v_pk_fma_f32 v[100:101], v[98:99], v[148:149], v[106:107]
	v_cvt_pk_bf16_f32 v98, v102, v103
	v_cvt_pk_bf16_f32 v99, v104, v105
	v_cvt_pk_bf16_f32 v100, v100, v101
	v_cvt_pk_bf16_f32 v101, v108, v109
	global_store_dwordx4 v[114:115], v[98:101], off offset:2304
	s_nop 1
	v_or_b32_e32 v98, 32, v162
	v_ashrrev_i32_e32 v99, 31, v98
	v_lshlrev_b64 v[106:107], 12, v[98:99]
	v_lshl_add_u64 v[98:99], s[2:3], 0, v[106:107]
	v_lshl_add_u64 v[108:109], v[98:99], 0, v[158:159]
	global_load_dwordx4 v[98:101], v[108:109], off offset:16
	global_load_dwordx4 v[102:105], v[108:109], off
	s_waitcnt vmcnt(0)
	v_pk_fma_f32 v[100:101], v[92:93], v[154:155], v[100:101]
	v_pk_fma_f32 v[94:95], v[94:95], v[152:153], v[102:103]
	v_pk_fma_f32 v[96:97], v[96:97], v[150:151], v[104:105]
	v_pk_fma_f32 v[92:93], v[90:91], v[156:157], v[98:99]
	v_cvt_pk_bf16_f32 v90, v94, v95
	v_lshl_add_u64 v[94:95], s[12:13], 0, v[106:107]
	v_cvt_pk_bf16_f32 v91, v96, v97
	v_cvt_pk_bf16_f32 v92, v92, v93
	v_cvt_pk_bf16_f32 v93, v100, v101
	v_lshl_add_u64 v[98:99], v[94:95], 0, v[122:123]
	global_store_dwordx4 v[98:99], v[90:93], off offset:2048
	global_load_dwordx4 v[90:93], v[108:109], off offset:528
	s_nop 0
	global_load_dwordx4 v[94:97], v[108:109], off offset:512
	s_waitcnt vmcnt(0)
	v_pk_fma_f32 v[92:93], v[84:85], v[146:147], v[92:93]
	v_pk_fma_f32 v[88:89], v[88:89], v[142:143], v[96:97]
	v_pk_fma_f32 v[86:87], v[86:87], v[144:145], v[94:95]
	v_pk_fma_f32 v[84:85], v[82:83], v[148:149], v[90:91]
	v_cvt_pk_bf16_f32 v82, v86, v87
	v_cvt_pk_bf16_f32 v83, v88, v89
	v_cvt_pk_bf16_f32 v84, v84, v85
	v_cvt_pk_bf16_f32 v85, v92, v93
	global_store_dwordx4 v[98:99], v[82:85], off offset:2304
	s_nop 1
	v_or_b32_e32 v82, 48, v162
	v_ashrrev_i32_e32 v83, 31, v82
	v_lshlrev_b64 v[90:91], 12, v[82:83]
	v_lshl_add_u64 v[82:83], s[2:3], 0, v[90:91]
	v_lshl_add_u64 v[92:93], v[82:83], 0, v[158:159]
	global_load_dwordx4 v[82:85], v[92:93], off offset:16
	global_load_dwordx4 v[86:89], v[92:93], off
	s_waitcnt vmcnt(0)
	v_pk_fma_f32 v[84:85], v[76:77], v[154:155], v[84:85]
	v_pk_fma_f32 v[78:79], v[78:79], v[152:153], v[86:87]
	v_pk_fma_f32 v[80:81], v[80:81], v[150:151], v[88:89]
	v_pk_fma_f32 v[76:77], v[74:75], v[156:157], v[82:83]
	v_cvt_pk_bf16_f32 v74, v78, v79
	v_lshl_add_u64 v[78:79], s[12:13], 0, v[90:91]
	v_cvt_pk_bf16_f32 v75, v80, v81
	v_cvt_pk_bf16_f32 v76, v76, v77
	v_cvt_pk_bf16_f32 v77, v84, v85
	v_lshl_add_u64 v[82:83], v[78:79], 0, v[122:123]
	global_store_dwordx4 v[82:83], v[74:77], off offset:2048
	global_load_dwordx4 v[74:77], v[92:93], off offset:528
	s_nop 0
	global_load_dwordx4 v[78:81], v[92:93], off offset:512
	s_waitcnt vmcnt(0)
	v_pk_fma_f32 v[76:77], v[68:69], v[146:147], v[76:77]
	v_pk_fma_f32 v[72:73], v[72:73], v[142:143], v[80:81]
	v_pk_fma_f32 v[70:71], v[70:71], v[144:145], v[78:79]
	v_pk_fma_f32 v[68:69], v[66:67], v[148:149], v[74:75]
	v_cvt_pk_bf16_f32 v66, v70, v71
	v_cvt_pk_bf16_f32 v67, v72, v73
	v_cvt_pk_bf16_f32 v68, v68, v69
	v_cvt_pk_bf16_f32 v69, v76, v77
	v_lshl_add_u64 v[74:75], v[160:161], 0, s[14:15]
	global_store_dwordx4 v[82:83], v[66:69], off offset:2304
	s_mov_b64 s[14:15], 0x90000
	s_nop 0
	v_lshl_add_u64 v[66:67], s[2:3], 0, v[74:75]
	v_lshl_add_u64 v[76:77], v[66:67], 0, v[158:159]
	global_load_dwordx4 v[66:69], v[76:77], off offset:16
	global_load_dwordx4 v[70:73], v[76:77], off
	s_waitcnt vmcnt(0)
	v_pk_fma_f32 v[68:69], v[60:61], v[154:155], v[68:69]
	v_pk_fma_f32 v[62:63], v[62:63], v[152:153], v[70:71]
	v_pk_fma_f32 v[64:65], v[64:65], v[150:151], v[72:73]
	v_pk_fma_f32 v[60:61], v[58:59], v[156:157], v[66:67]
	v_cvt_pk_bf16_f32 v58, v62, v63
	v_lshl_add_u64 v[62:63], s[12:13], 0, v[74:75]
	v_cvt_pk_bf16_f32 v59, v64, v65
	v_cvt_pk_bf16_f32 v60, v60, v61
	v_cvt_pk_bf16_f32 v61, v68, v69
	v_lshl_add_u64 v[66:67], v[62:63], 0, v[122:123]
	global_store_dwordx4 v[66:67], v[58:61], off offset:2048
	global_load_dwordx4 v[58:61], v[76:77], off offset:528
	s_nop 0
	global_load_dwordx4 v[62:65], v[76:77], off offset:512
	s_waitcnt vmcnt(0)
	v_pk_fma_f32 v[60:61], v[52:53], v[146:147], v[60:61]
	v_pk_fma_f32 v[56:57], v[56:57], v[142:143], v[64:65]
	v_pk_fma_f32 v[54:55], v[54:55], v[144:145], v[62:63]
	v_pk_fma_f32 v[52:53], v[50:51], v[148:149], v[58:59]
	v_cvt_pk_bf16_f32 v50, v54, v55
	v_cvt_pk_bf16_f32 v51, v56, v57
	v_cvt_pk_bf16_f32 v52, v52, v53
	v_cvt_pk_bf16_f32 v53, v60, v61
	v_lshl_add_u64 v[58:59], v[160:161], 0, s[14:15]
	global_store_dwordx4 v[66:67], v[50:53], off offset:2304
	s_mov_b64 s[14:15], 0xa0000
	s_nop 0
	v_lshl_add_u64 v[50:51], s[2:3], 0, v[58:59]
	v_lshl_add_u64 v[60:61], v[50:51], 0, v[158:159]
	global_load_dwordx4 v[50:53], v[60:61], off offset:16
	global_load_dwordx4 v[54:57], v[60:61], off
	s_waitcnt vmcnt(0)
	v_pk_fma_f32 v[52:53], v[44:45], v[154:155], v[52:53]
	v_pk_fma_f32 v[46:47], v[46:47], v[152:153], v[54:55]
	v_pk_fma_f32 v[48:49], v[48:49], v[150:151], v[56:57]
	v_pk_fma_f32 v[44:45], v[42:43], v[156:157], v[50:51]
	v_cvt_pk_bf16_f32 v42, v46, v47
	v_lshl_add_u64 v[46:47], s[12:13], 0, v[58:59]
	v_cvt_pk_bf16_f32 v43, v48, v49
	v_cvt_pk_bf16_f32 v44, v44, v45
	v_cvt_pk_bf16_f32 v45, v52, v53
	v_lshl_add_u64 v[50:51], v[46:47], 0, v[122:123]
	global_store_dwordx4 v[50:51], v[42:45], off offset:2048
	global_load_dwordx4 v[42:45], v[60:61], off offset:528
	s_nop 0
	global_load_dwordx4 v[46:49], v[60:61], off offset:512
	s_waitcnt vmcnt(0)
	v_pk_fma_f32 v[44:45], v[36:37], v[146:147], v[44:45]
	v_pk_fma_f32 v[40:41], v[40:41], v[142:143], v[48:49]
	v_pk_fma_f32 v[38:39], v[38:39], v[144:145], v[46:47]
	v_pk_fma_f32 v[36:37], v[34:35], v[148:149], v[42:43]
	v_cvt_pk_bf16_f32 v34, v38, v39
	v_cvt_pk_bf16_f32 v35, v40, v41
	v_cvt_pk_bf16_f32 v36, v36, v37
	v_cvt_pk_bf16_f32 v37, v44, v45
	v_lshl_add_u64 v[42:43], v[160:161], 0, s[14:15]
	global_store_dwordx4 v[50:51], v[34:37], off offset:2304
	s_mov_b64 s[14:15], 0xb0000
	s_nop 0
	v_lshl_add_u64 v[34:35], s[2:3], 0, v[42:43]
	v_lshl_add_u64 v[44:45], v[34:35], 0, v[158:159]
	global_load_dwordx4 v[34:37], v[44:45], off offset:16
	global_load_dwordx4 v[38:41], v[44:45], off
	s_waitcnt vmcnt(0)
	v_pk_fma_f32 v[36:37], v[28:29], v[154:155], v[36:37]
	v_pk_fma_f32 v[30:31], v[30:31], v[152:153], v[38:39]
	v_pk_fma_f32 v[32:33], v[32:33], v[150:151], v[40:41]
	v_pk_fma_f32 v[28:29], v[26:27], v[156:157], v[34:35]
	v_cvt_pk_bf16_f32 v26, v30, v31
	v_lshl_add_u64 v[30:31], s[12:13], 0, v[42:43]
	v_cvt_pk_bf16_f32 v27, v32, v33
	v_cvt_pk_bf16_f32 v28, v28, v29
	v_cvt_pk_bf16_f32 v29, v36, v37
	v_lshl_add_u64 v[34:35], v[30:31], 0, v[122:123]
	global_store_dwordx4 v[34:35], v[26:29], off offset:2048
	global_load_dwordx4 v[26:29], v[44:45], off offset:528
	s_nop 0
	global_load_dwordx4 v[30:33], v[44:45], off offset:512
	s_waitcnt vmcnt(0)
	v_pk_fma_f32 v[28:29], v[20:21], v[146:147], v[28:29]
	v_pk_fma_f32 v[24:25], v[24:25], v[142:143], v[32:33]
	v_pk_fma_f32 v[22:23], v[22:23], v[144:145], v[30:31]
	v_pk_fma_f32 v[20:21], v[18:19], v[148:149], v[26:27]
	v_cvt_pk_bf16_f32 v18, v22, v23
	v_cvt_pk_bf16_f32 v19, v24, v25
	v_cvt_pk_bf16_f32 v20, v20, v21
	v_cvt_pk_bf16_f32 v21, v28, v29
	v_lshl_add_u64 v[26:27], v[160:161], 0, s[14:15]
	global_store_dwordx4 v[34:35], v[18:21], off offset:2304
	s_mov_b64 s[14:15], s[6:7]
	s_nop 0
	v_lshl_add_u64 v[18:19], s[2:3], 0, v[26:27]
	v_lshl_add_u64 v[28:29], v[18:19], 0, v[158:159]
	global_load_dwordx4 v[18:21], v[28:29], off offset:16
	global_load_dwordx4 v[22:25], v[28:29], off
	s_waitcnt vmcnt(0)
	v_pk_fma_f32 v[20:21], v[12:13], v[154:155], v[20:21]
	v_pk_fma_f32 v[14:15], v[14:15], v[152:153], v[22:23]
	v_pk_fma_f32 v[16:17], v[16:17], v[150:151], v[24:25]
	v_pk_fma_f32 v[12:13], v[10:11], v[156:157], v[18:19]
	v_cvt_pk_bf16_f32 v10, v14, v15
	v_lshl_add_u64 v[14:15], s[12:13], 0, v[26:27]
	v_cvt_pk_bf16_f32 v11, v16, v17
	v_cvt_pk_bf16_f32 v12, v12, v13
	v_cvt_pk_bf16_f32 v13, v20, v21
	v_lshl_add_u64 v[18:19], v[14:15], 0, v[122:123]
	global_store_dwordx4 v[18:19], v[10:13], off offset:2048
	global_load_dwordx4 v[10:13], v[28:29], off offset:528
	s_nop 0
	global_load_dwordx4 v[14:17], v[28:29], off offset:512
	s_waitcnt vmcnt(0)
	v_pk_fma_f32 v[12:13], v[4:5], v[146:147], v[12:13]
	v_pk_fma_f32 v[8:9], v[8:9], v[142:143], v[16:17]
	v_pk_fma_f32 v[6:7], v[6:7], v[144:145], v[14:15]
	v_pk_fma_f32 v[4:5], v[2:3], v[148:149], v[10:11]
	v_cvt_pk_bf16_f32 v2, v6, v7
	v_cvt_pk_bf16_f32 v3, v8, v9
	v_cvt_pk_bf16_f32 v4, v4, v5
	v_cvt_pk_bf16_f32 v5, v12, v13
	global_store_dwordx4 v[18:19], v[2:5], off offset:2304
	s_cbranch_vccz .LBB0_389
	s_waitcnt vmcnt(0)
	s_cmpk_gt_u32 s30, 0xff
	s_cbranch_scc1 .LBB0_404
	s_barrier

.LBB0_528:
	s_add_u32 s22, s20, 0xfffc0080
	s_addc_u32 s23, s21, -1
	s_add_i32 s55, 0, 0x10000
	v_add_u32_e32 v144, s55, v146
	ds_read_b128 v[150:153], v144
	ds_read_b128 v[154:157], v144 offset:1024
	ds_read_b128 v[158:161], v144 offset:2048
	ds_read_b128 v[162:165], v144 offset:3072
	s_cmp_eq_u32 s54, 12
	s_cselect_b32 s25, s11, s23
	s_cselect_b32 s24, s15, s22
	s_cselect_b32 s23, s13, s53
	s_cselect_b32 s22, s51, s52
	s_add_i32 m0, s41, 0xc000
	ds_read_b128 v[166:169], v148
	ds_read_b128 v[170:173], v148 offset:1024
	ds_read_b128 v[174:177], v148 offset:2048
	ds_read_b128 v[190:193], v148 offset:3072
	ds_read_b128 v[194:197], v148 offset:4096
	ds_read_b128 v[198:201], v148 offset:5120
	ds_read_b128 v[202:205], v148 offset:6144
	ds_read_b128 v[206:209], v148 offset:7168
	global_load_lds_dwordx4 v140, s[20:21]
	v_lshl_add_u64 v[144:145], s[20:21], 0, v[142:143]
	s_add_i32 m0, s41, 0xe000
	s_nop 0
	global_load_lds_dwordx4 v[144:145], off
	s_waitcnt lgkmcnt(8)
	s_barrier
	s_waitcnt lgkmcnt(0)
	s_waitcnt lgkmcnt(0)
	v_mfma_f32_16x16x32_bf16 v[86:89], v[150:153], v[166:169], v[86:89]
	v_mfma_f32_16x16x32_bf16 v[82:85], v[158:161], v[166:169], v[82:85]
	v_mfma_f32_16x16x32_bf16 v[78:81], v[150:153], v[174:177], v[78:81]
	v_mfma_f32_16x16x32_bf16 v[74:77], v[158:161], v[174:177], v[74:77]
	v_mfma_f32_16x16x32_bf16 v[62:65], v[150:153], v[194:197], v[62:65]
	v_mfma_f32_16x16x32_bf16 v[58:61], v[158:161], v[194:197], v[58:61]
	v_mfma_f32_16x16x32_bf16 v[54:57], v[150:153], v[202:205], v[54:57]
	v_mfma_f32_16x16x32_bf16 v[50:53], v[158:161], v[202:205], v[50:53]
	v_mfma_f32_16x16x32_bf16 v[86:89], v[154:157], v[170:173], v[86:89]
	v_mfma_f32_16x16x32_bf16 v[82:85], v[162:165], v[170:173], v[82:85]
	v_mfma_f32_16x16x32_bf16 v[78:81], v[154:157], v[190:193], v[78:81]
	v_mfma_f32_16x16x32_bf16 v[74:77], v[162:165], v[190:193], v[74:77]
	v_mfma_f32_16x16x32_bf16 v[62:65], v[154:157], v[198:201], v[62:65]
	v_mfma_f32_16x16x32_bf16 v[58:61], v[162:165], v[198:201], v[58:61]
	v_mfma_f32_16x16x32_bf16 v[54:57], v[154:157], v[206:209], v[54:57]
	v_mfma_f32_16x16x32_bf16 v[50:53], v[162:165], v[206:209], v[50:53]
	s_barrier
	s_add_i32 s58, 0, 0x14000
	v_add_u32_e32 v144, s58, v146
	s_add_i32 s55, s55, s35
	ds_read_b128 v[210:213], v144
	ds_read_b128 v[214:217], v144 offset:1024
	ds_read_b128 v[218:221], v144 offset:2048
	ds_read_b128 v[222:225], v144 offset:3072
	s_add_u32 s64, s22, 0x80
	s_addc_u32 s65, s23, 0
	s_mov_b32 m0, s55
	s_nop 0
	global_load_lds_dwordx4 v134, s[22:23]
	s_add_i32 m0, s55, 0x2000
	s_nop 0
	global_load_lds_dwordx4 v130, s[22:23]
	s_barrier
	s_waitcnt lgkmcnt(0)
	s_waitcnt lgkmcnt(0)
	v_mfma_f32_16x16x32_bf16 v[126:129], v[210:213], v[166:169], v[126:129]
	v_mfma_f32_16x16x32_bf16 v[122:125], v[218:221], v[166:169], v[122:125]
	v_mfma_f32_16x16x32_bf16 v[118:121], v[210:213], v[174:177], v[118:121]
	v_mfma_f32_16x16x32_bf16 v[114:117], v[218:221], v[174:177], v[114:117]
	v_mfma_f32_16x16x32_bf16 v[110:113], v[210:213], v[194:197], v[110:113]
	v_mfma_f32_16x16x32_bf16 v[106:109], v[218:221], v[194:197], v[106:109]
	v_mfma_f32_16x16x32_bf16 v[102:105], v[210:213], v[202:205], v[102:105]
	v_mfma_f32_16x16x32_bf16 v[98:101], v[218:221], v[202:205], v[98:101]
	v_mfma_f32_16x16x32_bf16 v[126:129], v[214:217], v[170:173], v[126:129]
	v_mfma_f32_16x16x32_bf16 v[122:125], v[222:225], v[170:173], v[122:125]
	v_mfma_f32_16x16x32_bf16 v[118:121], v[214:217], v[190:193], v[118:121]
	v_mfma_f32_16x16x32_bf16 v[114:117], v[222:225], v[190:193], v[114:117]
	v_mfma_f32_16x16x32_bf16 v[110:113], v[214:217], v[198:201], v[110:113]
	v_mfma_f32_16x16x32_bf16 v[106:109], v[222:225], v[198:201], v[106:109]
	v_mfma_f32_16x16x32_bf16 v[102:105], v[214:217], v[206:209], v[102:105]
	v_mfma_f32_16x16x32_bf16 v[98:101], v[222:225], v[206:209], v[98:101]
	s_mov_b32 m0, s41
	s_add_u32 s62, s24, 0x80
	s_addc_u32 s63, s25, 0
	s_barrier
	ds_read_b128 v[166:169], v148 offset:16384
	ds_read_b128 v[170:173], v148 offset:17408
	ds_read_b128 v[174:177], v148 offset:18432
	ds_read_b128 v[190:193], v148 offset:19456
	ds_read_b128 v[194:197], v148 offset:20480
	ds_read_b128 v[198:201], v148 offset:21504
	ds_read_b128 v[202:205], v148 offset:22528
	ds_read_b128 v[206:209], v148 offset:23552
	global_load_lds_dwordx4 v136, s[24:25]
	s_mov_b32 m0, s42
	s_nop 0
	global_load_lds_dwordx4 v132, s[24:25]
	s_barrier
	s_waitcnt lgkmcnt(0)
	s_waitcnt lgkmcnt(0)
	v_mfma_f32_16x16x32_bf16 v[34:37], v[150:153], v[166:169], v[34:37]
	v_mfma_f32_16x16x32_bf16 v[26:29], v[158:161], v[166:169], v[26:29]
	v_mfma_f32_16x16x32_bf16 v[22:25], v[150:153], v[174:177], v[22:25]
	v_mfma_f32_16x16x32_bf16 v[18:21], v[158:161], v[174:177], v[18:21]
	v_mfma_f32_16x16x32_bf16 v[14:17], v[150:153], v[194:197], v[14:17]
	v_mfma_f32_16x16x32_bf16 v[10:13], v[158:161], v[194:197], v[10:13]
	v_mfma_f32_16x16x32_bf16 v[6:9], v[150:153], v[202:205], v[6:9]
	v_mfma_f32_16x16x32_bf16 v[2:5], v[158:161], v[202:205], v[2:5]
	v_mfma_f32_16x16x32_bf16 v[34:37], v[154:157], v[170:173], v[34:37]
	v_mfma_f32_16x16x32_bf16 v[26:29], v[162:165], v[170:173], v[26:29]
	v_mfma_f32_16x16x32_bf16 v[22:25], v[154:157], v[190:193], v[22:25]
	v_mfma_f32_16x16x32_bf16 v[18:21], v[162:165], v[190:193], v[18:21]
	v_mfma_f32_16x16x32_bf16 v[14:17], v[154:157], v[198:201], v[14:17]
	v_mfma_f32_16x16x32_bf16 v[10:13], v[162:165], v[198:201], v[10:13]
	v_mfma_f32_16x16x32_bf16 v[6:9], v[154:157], v[206:209], v[6:9]
	v_mfma_f32_16x16x32_bf16 v[2:5], v[162:165], v[206:209], v[2:5]
	s_barrier
	s_add_u32 s56, s22, 0x40000
	s_addc_u32 s57, s23, 0
	s_add_i32 s55, s58, s35
	s_mov_b32 m0, s55
	s_nop 0
	global_load_lds_dwordx4 v134, s[56:57]
	s_add_i32 m0, s55, 0x2000
	s_nop 0
	global_load_lds_dwordx4 v130, s[56:57]
	s_waitcnt vmcnt(6)
	s_barrier
	v_mfma_f32_16x16x32_bf16 v[94:97], v[210:213], v[166:169], v[94:97]
	v_mfma_f32_16x16x32_bf16 v[90:93], v[218:221], v[166:169], v[90:93]
	v_mfma_f32_16x16x32_bf16 v[70:73], v[210:213], v[174:177], v[70:73]
	v_mfma_f32_16x16x32_bf16 v[66:69], v[218:221], v[174:177], v[66:69]
	v_mfma_f32_16x16x32_bf16 v[46:49], v[210:213], v[194:197], v[46:49]
	v_mfma_f32_16x16x32_bf16 v[42:45], v[218:221], v[194:197], v[42:45]
	v_mfma_f32_16x16x32_bf16 v[38:41], v[210:213], v[202:205], v[38:41]
	v_mfma_f32_16x16x32_bf16 v[30:33], v[218:221], v[202:205], v[30:33]
	v_mfma_f32_16x16x32_bf16 v[94:97], v[214:217], v[170:173], v[94:97]
	v_mfma_f32_16x16x32_bf16 v[90:93], v[222:225], v[170:173], v[90:93]
	v_mfma_f32_16x16x32_bf16 v[70:73], v[214:217], v[190:193], v[70:73]
	v_mfma_f32_16x16x32_bf16 v[66:69], v[222:225], v[190:193], v[66:69]
	v_mfma_f32_16x16x32_bf16 v[46:49], v[214:217], v[198:201], v[46:49]
	v_mfma_f32_16x16x32_bf16 v[42:45], v[222:225], v[198:201], v[42:45]
	v_mfma_f32_16x16x32_bf16 v[38:41], v[214:217], v[206:209], v[38:41]
	v_mfma_f32_16x16x32_bf16 v[30:33], v[222:225], v[206:209], v[30:33]
	s_add_i32 s55, 0, 0x18000
	v_add_u32_e32 v149, s55, v146
	ds_read_b128 v[150:153], v149
	ds_read_b128 v[154:157], v149 offset:1024
	ds_read_b128 v[158:161], v149 offset:2048
	ds_read_b128 v[162:165], v149 offset:3072
	s_barrier
	s_add_u32 s24, s24, 0x40000
	s_addc_u32 s25, s25, 0
	s_mov_b32 m0, s43
	ds_read_b128 v[166:169], v148 offset:32768
	ds_read_b128 v[170:173], v148 offset:33792
	ds_read_b128 v[174:177], v148 offset:34816
	ds_read_b128 v[190:193], v148 offset:35840
	ds_read_b128 v[194:197], v148 offset:36864
	ds_read_b128 v[198:201], v148 offset:37888
	ds_read_b128 v[202:205], v148 offset:38912
	ds_read_b128 v[206:209], v148 offset:39936
	global_load_lds_dwordx4 v136, s[24:25]
	s_mov_b32 m0, s44
	s_nop 0
	global_load_lds_dwordx4 v132, s[24:25]
	s_waitcnt lgkmcnt(8)
	s_barrier
	s_waitcnt lgkmcnt(0)
	s_waitcnt lgkmcnt(0)
	v_mfma_f32_16x16x32_bf16 v[86:89], v[150:153], v[166:169], v[86:89]
	v_mfma_f32_16x16x32_bf16 v[82:85], v[158:161], v[166:169], v[82:85]
	v_mfma_f32_16x16x32_bf16 v[78:81], v[150:153], v[174:177], v[78:81]
	v_mfma_f32_16x16x32_bf16 v[74:77], v[158:161], v[174:177], v[74:77]
	v_mfma_f32_16x16x32_bf16 v[62:65], v[150:153], v[194:197], v[62:65]
	v_mfma_f32_16x16x32_bf16 v[58:61], v[158:161], v[194:197], v[58:61]
	v_mfma_f32_16x16x32_bf16 v[54:57], v[150:153], v[202:205], v[54:57]
	v_mfma_f32_16x16x32_bf16 v[50:53], v[158:161], v[202:205], v[50:53]
	v_mfma_f32_16x16x32_bf16 v[86:89], v[154:157], v[170:173], v[86:89]
	v_mfma_f32_16x16x32_bf16 v[82:85], v[162:165], v[170:173], v[82:85]
	v_mfma_f32_16x16x32_bf16 v[78:81], v[154:157], v[190:193], v[78:81]
	v_mfma_f32_16x16x32_bf16 v[74:77], v[162:165], v[190:193], v[74:77]
	v_mfma_f32_16x16x32_bf16 v[62:65], v[154:157], v[198:201], v[62:65]
	v_mfma_f32_16x16x32_bf16 v[58:61], v[162:165], v[198:201], v[58:61]
	v_mfma_f32_16x16x32_bf16 v[54:57], v[154:157], v[206:209], v[54:57]
	v_mfma_f32_16x16x32_bf16 v[50:53], v[162:165], v[206:209], v[50:53]
	s_barrier
	s_add_i32 s24, 0, 0x1c000
	s_add_i32 s25, s55, s35
	v_add_u32_e32 v149, s24, v146
	s_mov_b32 m0, s25
	ds_read_b128 v[210:213], v149
	ds_read_b128 v[214:217], v149 offset:1024
	ds_read_b128 v[218:221], v149 offset:2048
	ds_read_b128 v[222:225], v149 offset:3072
	global_load_lds_dwordx4 v134, s[64:65]
	s_add_i32 m0, s25, 0x2000
	s_nop 0
	global_load_lds_dwordx4 v130, s[64:65]
	s_barrier
	s_waitcnt lgkmcnt(0)
	s_waitcnt lgkmcnt(0)
	v_mfma_f32_16x16x32_bf16 v[126:129], v[210:213], v[166:169], v[126:129]
	v_mfma_f32_16x16x32_bf16 v[122:125], v[218:221], v[166:169], v[122:125]
	v_mfma_f32_16x16x32_bf16 v[118:121], v[210:213], v[174:177], v[118:121]
	v_mfma_f32_16x16x32_bf16 v[114:117], v[218:221], v[174:177], v[114:117]
	v_mfma_f32_16x16x32_bf16 v[110:113], v[210:213], v[194:197], v[110:113]
	v_mfma_f32_16x16x32_bf16 v[106:109], v[218:221], v[194:197], v[106:109]
	v_mfma_f32_16x16x32_bf16 v[102:105], v[210:213], v[202:205], v[102:105]
	v_mfma_f32_16x16x32_bf16 v[98:101], v[218:221], v[202:205], v[98:101]
	v_mfma_f32_16x16x32_bf16 v[126:129], v[214:217], v[170:173], v[126:129]
	v_mfma_f32_16x16x32_bf16 v[122:125], v[222:225], v[170:173], v[122:125]
	v_mfma_f32_16x16x32_bf16 v[118:121], v[214:217], v[190:193], v[118:121]
	v_mfma_f32_16x16x32_bf16 v[114:117], v[222:225], v[190:193], v[114:117]
	v_mfma_f32_16x16x32_bf16 v[110:113], v[214:217], v[198:201], v[110:113]
	v_mfma_f32_16x16x32_bf16 v[106:109], v[222:225], v[198:201], v[106:109]
	v_mfma_f32_16x16x32_bf16 v[102:105], v[214:217], v[206:209], v[102:105]
	v_mfma_f32_16x16x32_bf16 v[98:101], v[222:225], v[206:209], v[98:101]
	s_mov_b32 m0, s46
	s_barrier
	ds_read_b128 v[166:169], v148 offset:49152
	ds_read_b128 v[170:173], v148 offset:50176
	ds_read_b128 v[174:177], v148 offset:51200
	ds_read_b128 v[190:193], v148 offset:52224
	ds_read_b128 v[194:197], v148 offset:53248
	ds_read_b128 v[198:201], v148 offset:54272
	ds_read_b128 v[202:205], v148 offset:55296
	ds_read_b128 v[206:209], v148 offset:56320
	global_load_lds_dwordx4 v136, s[62:63]
	s_mov_b32 m0, s47
	s_nop 0
	global_load_lds_dwordx4 v132, s[62:63]
	s_barrier
	s_waitcnt lgkmcnt(0)
	s_waitcnt lgkmcnt(0)
	v_mfma_f32_16x16x32_bf16 v[34:37], v[150:153], v[166:169], v[34:37]
	v_mfma_f32_16x16x32_bf16 v[26:29], v[158:161], v[166:169], v[26:29]
	v_mfma_f32_16x16x32_bf16 v[22:25], v[150:153], v[174:177], v[22:25]
	v_mfma_f32_16x16x32_bf16 v[18:21], v[158:161], v[174:177], v[18:21]
	v_mfma_f32_16x16x32_bf16 v[14:17], v[150:153], v[194:197], v[14:17]
	v_mfma_f32_16x16x32_bf16 v[10:13], v[158:161], v[194:197], v[10:13]
	v_mfma_f32_16x16x32_bf16 v[6:9], v[150:153], v[202:205], v[6:9]
	v_mfma_f32_16x16x32_bf16 v[2:5], v[158:161], v[202:205], v[2:5]
	v_mfma_f32_16x16x32_bf16 v[34:37], v[154:157], v[170:173], v[34:37]
	v_mfma_f32_16x16x32_bf16 v[26:29], v[162:165], v[170:173], v[26:29]
	v_mfma_f32_16x16x32_bf16 v[22:25], v[154:157], v[190:193], v[22:25]
	v_mfma_f32_16x16x32_bf16 v[18:21], v[162:165], v[190:193], v[18:21]
	v_mfma_f32_16x16x32_bf16 v[14:17], v[154:157], v[198:201], v[14:17]
	v_mfma_f32_16x16x32_bf16 v[10:13], v[162:165], v[198:201], v[10:13]
	v_mfma_f32_16x16x32_bf16 v[6:9], v[154:157], v[206:209], v[6:9]
	v_mfma_f32_16x16x32_bf16 v[2:5], v[162:165], v[206:209], v[2:5]
	s_barrier
	s_add_u32 s22, s22, 0x40080
	s_addc_u32 s23, s23, 0
	s_add_i32 s24, s24, s35
	s_mov_b32 m0, s24
	s_nop 0
	global_load_lds_dwordx4 v134, s[22:23]
	v_lshl_add_u64 v[144:145], s[22:23], 0, v[130:131]
	s_add_i32 m0, s24, 0x2000
	s_nop 0
	global_load_lds_dwordx4 v[144:145], off
	s_waitcnt vmcnt(6)
	s_barrier
	v_mfma_f32_16x16x32_bf16 v[94:97], v[210:213], v[166:169], v[94:97]
	v_mfma_f32_16x16x32_bf16 v[90:93], v[218:221], v[166:169], v[90:93]
	v_mfma_f32_16x16x32_bf16 v[70:73], v[210:213], v[174:177], v[70:73]
	v_mfma_f32_16x16x32_bf16 v[66:69], v[218:221], v[174:177], v[66:69]
	v_mfma_f32_16x16x32_bf16 v[46:49], v[210:213], v[194:197], v[46:49]
	v_mfma_f32_16x16x32_bf16 v[42:45], v[218:221], v[194:197], v[42:45]
	v_mfma_f32_16x16x32_bf16 v[38:41], v[210:213], v[202:205], v[38:41]
	v_mfma_f32_16x16x32_bf16 v[30:33], v[218:221], v[202:205], v[30:33]
	v_mfma_f32_16x16x32_bf16 v[94:97], v[214:217], v[170:173], v[94:97]
	v_mfma_f32_16x16x32_bf16 v[90:93], v[222:225], v[170:173], v[90:93]
	v_mfma_f32_16x16x32_bf16 v[70:73], v[214:217], v[190:193], v[70:73]
	v_mfma_f32_16x16x32_bf16 v[66:69], v[222:225], v[190:193], v[66:69]
	v_mfma_f32_16x16x32_bf16 v[46:49], v[214:217], v[198:201], v[46:49]
	v_mfma_f32_16x16x32_bf16 v[42:45], v[222:225], v[198:201], v[42:45]
	v_mfma_f32_16x16x32_bf16 v[38:41], v[214:217], v[206:209], v[38:41]
	v_mfma_f32_16x16x32_bf16 v[30:33], v[222:225], v[206:209], v[30:33]
	s_add_i32 s54, s54, 2
	s_add_u32 s20, s20, 0x100
	s_addc_u32 s21, s21, 0
	s_add_u32 s52, s52, 0x100
	s_addc_u32 s53, s53, 0
	s_cmp_gt_u32 s54, 13
	s_barrier
	s_cbranch_scc0 .LBB0_528
	v_lshl_add_u32 v144, s10, 8, v1
	s_cmp_lg_u32 s50, s45
	s_mov_b64 s[10:11], -1
	s_cbranch_scc0 .LBB0_531
	v_lshl_or_b32 v154, s50, 8, v147
	v_readlane_b32 s13, v255, 32
	v_ashrrev_i32_e32 v155, 31, v154
	v_lshlrev_b64 v[154:155], 1, v[154:155]
	v_mad_i64_i32 v[156:157], s[10:11], v144, s13, 0
	v_lshl_add_u64 v[156:157], v[156:157], 1, s[6:7]
	v_lshl_add_u64 v[156:157], v[156:157], 0, v[154:155]
	v_cvt_pk_bf16_f32 v126, v126, v127
	v_cvt_pk_bf16_f32 v127, v128, v129
	v_cvt_pk_bf16_f32 v128, v122, v123
	v_cvt_pk_bf16_f32 v129, v124, v125
	global_store_dwordx4 v[156:157], v[126:129], off offset:256
	v_cvt_pk_bf16_f32 v150, v86, v87
	v_cvt_pk_bf16_f32 v151, v88, v89
	v_or_b32_e32 v126, 16, v144
	v_mad_i64_i32 v[126:127], s[10:11], v126, s13, 0
	v_lshl_add_u64 v[126:127], v[126:127], 1, s[6:7]
	v_cvt_pk_bf16_f32 v152, v82, v83
	v_cvt_pk_bf16_f32 v153, v84, v85
	v_lshl_add_u64 v[126:127], v[126:127], 0, v[154:155]
	v_cvt_pk_bf16_f32 v118, v118, v119
	v_cvt_pk_bf16_f32 v119, v120, v121
	v_cvt_pk_bf16_f32 v120, v114, v115
	v_cvt_pk_bf16_f32 v121, v116, v117
	global_store_dwordx4 v[156:157], v[150:153], off
	global_store_dwordx4 v[126:127], v[118:121], off offset:256
	v_cvt_pk_bf16_f32 v122, v78, v79
	v_cvt_pk_bf16_f32 v123, v80, v81
	v_or_b32_e32 v118, 32, v144
	v_mad_i64_i32 v[118:119], s[10:11], v118, s13, 0
	v_lshl_add_u64 v[118:119], v[118:119], 1, s[6:7]
	v_cvt_pk_bf16_f32 v124, v74, v75
	v_cvt_pk_bf16_f32 v125, v76, v77
	v_lshl_add_u64 v[118:119], v[118:119], 0, v[154:155]
	v_cvt_pk_bf16_f32 v110, v110, v111
	v_cvt_pk_bf16_f32 v111, v112, v113
	v_cvt_pk_bf16_f32 v112, v106, v107
	v_cvt_pk_bf16_f32 v113, v108, v109
	global_store_dwordx4 v[126:127], v[122:125], off
	global_store_dwordx4 v[118:119], v[110:113], off offset:256
	v_cvt_pk_bf16_f32 v114, v62, v63
	v_cvt_pk_bf16_f32 v115, v64, v65
	v_or_b32_e32 v110, 48, v144
	v_mad_i64_i32 v[110:111], s[10:11], v110, s13, 0
	v_lshl_add_u64 v[110:111], v[110:111], 1, s[6:7]
	v_cvt_pk_bf16_f32 v116, v58, v59
	v_cvt_pk_bf16_f32 v117, v60, v61
	v_lshl_add_u64 v[110:111], v[110:111], 0, v[154:155]
	v_cvt_pk_bf16_f32 v102, v102, v103
	v_cvt_pk_bf16_f32 v103, v104, v105
	v_cvt_pk_bf16_f32 v104, v98, v99
	v_cvt_pk_bf16_f32 v105, v100, v101
	global_store_dwordx4 v[118:119], v[114:117], off
	global_store_dwordx4 v[110:111], v[102:105], off offset:256
	v_cvt_pk_bf16_f32 v106, v54, v55
	v_cvt_pk_bf16_f32 v107, v56, v57
	v_add_u32_e32 v102, 0x80, v144
	v_mad_i64_i32 v[102:103], s[10:11], v102, s13, 0
	v_lshl_add_u64 v[102:103], v[102:103], 1, s[6:7]
	v_cvt_pk_bf16_f32 v108, v50, v51
	v_cvt_pk_bf16_f32 v109, v52, v53
	v_lshl_add_u64 v[102:103], v[102:103], 0, v[154:155]
	v_cvt_pk_bf16_f32 v94, v94, v95
	v_cvt_pk_bf16_f32 v95, v96, v97
	v_cvt_pk_bf16_f32 v96, v90, v91
	v_cvt_pk_bf16_f32 v97, v92, v93
	global_store_dwordx4 v[110:111], v[106:109], off
	global_store_dwordx4 v[102:103], v[94:97], off offset:256
	v_cvt_pk_bf16_f32 v98, v34, v35
	v_cvt_pk_bf16_f32 v99, v36, v37
	v_add_u32_e32 v94, 0x90, v144
	v_mad_i64_i32 v[94:95], s[10:11], v94, s13, 0
	v_lshl_add_u64 v[94:95], v[94:95], 1, s[6:7]
	v_cvt_pk_bf16_f32 v100, v26, v27
	v_cvt_pk_bf16_f32 v101, v28, v29
	v_lshl_add_u64 v[94:95], v[94:95], 0, v[154:155]
	v_cvt_pk_bf16_f32 v70, v70, v71
	v_cvt_pk_bf16_f32 v71, v72, v73
	v_cvt_pk_bf16_f32 v72, v66, v67
	v_cvt_pk_bf16_f32 v73, v68, v69
	global_store_dwordx4 v[102:103], v[98:101], off
	global_store_dwordx4 v[94:95], v[70:73], off offset:256
	v_cvt_pk_bf16_f32 v90, v22, v23
	v_cvt_pk_bf16_f32 v91, v24, v25
	v_add_u32_e32 v70, 0xa0, v144
	v_mad_i64_i32 v[70:71], s[10:11], v70, s13, 0
	v_lshl_add_u64 v[70:71], v[70:71], 1, s[6:7]
	v_cvt_pk_bf16_f32 v92, v18, v19
	v_cvt_pk_bf16_f32 v93, v20, v21
	v_lshl_add_u64 v[70:71], v[70:71], 0, v[154:155]
	v_cvt_pk_bf16_f32 v46, v46, v47
	v_cvt_pk_bf16_f32 v47, v48, v49
	v_cvt_pk_bf16_f32 v48, v42, v43
	v_cvt_pk_bf16_f32 v49, v44, v45
	global_store_dwordx4 v[94:95], v[90:93], off
	global_store_dwordx4 v[70:71], v[46:49], off offset:256
	v_cvt_pk_bf16_f32 v66, v14, v15
	v_cvt_pk_bf16_f32 v67, v16, v17
	v_add_u32_e32 v46, 0xb0, v144
	v_mad_i64_i32 v[46:47], s[10:11], v46, s13, 0
	v_lshl_add_u64 v[46:47], v[46:47], 1, s[6:7]
	v_cvt_pk_bf16_f32 v68, v10, v11
	v_cvt_pk_bf16_f32 v69, v12, v13
	v_cvt_pk_bf16_f32 v42, v6, v7
	v_cvt_pk_bf16_f32 v43, v8, v9
	v_cvt_pk_bf16_f32 v44, v2, v3
	v_cvt_pk_bf16_f32 v45, v4, v5
	v_lshl_add_u64 v[46:47], v[46:47], 0, v[154:155]
	v_cvt_pk_bf16_f32 v38, v38, v39
	v_cvt_pk_bf16_f32 v39, v40, v41
	v_cvt_pk_bf16_f32 v40, v30, v31
	v_cvt_pk_bf16_f32 v41, v32, v33
	global_store_dwordx4 v[70:71], v[66:69], off
	global_store_dwordx4 v[46:47], v[42:45], off
	global_store_dwordx4 v[46:47], v[38:41], off offset:256
	s_mov_b64 s[10:11], 0

.LBB0_1408:
	s_add_u32 s16, s14, s6
	s_addc_u32 s17, s15, s7
	s_add_u32 s16, s16, 0x100
	s_addc_u32 s17, s17, 0
	s_add_u32 s48, s45, s6
	s_addc_u32 s49, s46, s7
	s_add_i32 s50, 0, 0x10000
	v_add_u32_e32 v158, s50, v164
	ds_read_b128 v[146:149], v158
	ds_read_b128 v[150:153], v158 offset:1024
	ds_read_b128 v[154:157], v158 offset:2048
	ds_read_b128 v[158:161], v158 offset:3072
	s_cmpk_eq_i32 s6, 0xf00
	s_cselect_b32 s19, s11, s17
	s_cselect_b32 s18, s10, s16
	s_cselect_b32 s17, s3, s49
	s_cselect_b32 s16, s44, s48
	v_lshl_add_u64 v[162:163], v[142:143], 0, s[6:7]
	s_add_i32 m0, s30, 0xc000
	ds_read_b128 v[168:171], v166
	ds_read_b128 v[172:175], v166 offset:1024
	ds_read_b128 v[186:189], v166 offset:2048
	ds_read_b128 v[190:193], v166 offset:3072
	ds_read_b128 v[194:197], v166 offset:4096
	ds_read_b128 v[198:201], v166 offset:5120
	ds_read_b128 v[202:205], v166 offset:6144
	ds_read_b128 v[206:209], v166 offset:7168
	global_load_lds_dwordx4 v[162:163], off
	v_lshl_add_u64 v[162:163], v[144:145], 0, s[6:7]
	s_add_i32 m0, s30, 0xe000
	s_nop 0
	global_load_lds_dwordx4 v[162:163], off
	s_waitcnt lgkmcnt(8)
	s_barrier
	s_waitcnt lgkmcnt(0)
	s_waitcnt lgkmcnt(0)
	v_mfma_f32_16x16x32_bf16 v[126:129], v[146:149], v[168:171], v[126:129]
	v_mfma_f32_16x16x32_bf16 v[122:125], v[154:157], v[168:171], v[122:125]
	v_mfma_f32_16x16x32_bf16 v[110:113], v[146:149], v[186:189], v[110:113]
	v_mfma_f32_16x16x32_bf16 v[106:109], v[154:157], v[186:189], v[106:109]
	v_mfma_f32_16x16x32_bf16 v[94:97], v[146:149], v[194:197], v[94:97]
	v_mfma_f32_16x16x32_bf16 v[90:93], v[154:157], v[194:197], v[90:93]
	v_mfma_f32_16x16x32_bf16 v[78:81], v[146:149], v[202:205], v[78:81]
	v_mfma_f32_16x16x32_bf16 v[74:77], v[154:157], v[202:205], v[74:77]
	v_mfma_f32_16x16x32_bf16 v[126:129], v[150:153], v[172:175], v[126:129]
	v_mfma_f32_16x16x32_bf16 v[122:125], v[158:161], v[172:175], v[122:125]
	v_mfma_f32_16x16x32_bf16 v[110:113], v[150:153], v[190:193], v[110:113]
	v_mfma_f32_16x16x32_bf16 v[106:109], v[158:161], v[190:193], v[106:109]
	v_mfma_f32_16x16x32_bf16 v[94:97], v[150:153], v[198:201], v[94:97]
	v_mfma_f32_16x16x32_bf16 v[90:93], v[158:161], v[198:201], v[90:93]
	v_mfma_f32_16x16x32_bf16 v[78:81], v[150:153], v[206:209], v[78:81]
	v_mfma_f32_16x16x32_bf16 v[74:77], v[158:161], v[206:209], v[74:77]
	s_barrier
	s_add_i32 s51, 0, 0x14000
	v_add_u32_e32 v162, s51, v164
	s_add_i32 s48, s50, s29
	ds_read_b128 v[210:213], v162
	ds_read_b128 v[214:217], v162 offset:1024
	ds_read_b128 v[218:221], v162 offset:2048
	ds_read_b128 v[222:225], v162 offset:3072
	s_add_u32 s64, s16, 0x80
	s_addc_u32 s65, s17, 0
	s_mov_b32 m0, s48
	s_nop 0
	global_load_lds_dwordx4 v132, s[16:17]
	s_add_i32 m0, s48, 0x2000
	s_nop 0
	global_load_lds_dwordx4 v136, s[16:17]
	s_barrier
	s_waitcnt lgkmcnt(0)
	s_waitcnt lgkmcnt(0)
	v_mfma_f32_16x16x32_bf16 v[118:121], v[210:213], v[168:171], v[118:121]
	v_mfma_f32_16x16x32_bf16 v[114:117], v[218:221], v[168:171], v[114:117]
	v_mfma_f32_16x16x32_bf16 v[102:105], v[210:213], v[186:189], v[102:105]
	v_mfma_f32_16x16x32_bf16 v[98:101], v[218:221], v[186:189], v[98:101]
	v_mfma_f32_16x16x32_bf16 v[86:89], v[210:213], v[194:197], v[86:89]
	v_mfma_f32_16x16x32_bf16 v[82:85], v[218:221], v[194:197], v[82:85]
	v_mfma_f32_16x16x32_bf16 v[70:73], v[210:213], v[202:205], v[70:73]
	v_mfma_f32_16x16x32_bf16 v[66:69], v[218:221], v[202:205], v[66:69]
	v_mfma_f32_16x16x32_bf16 v[118:121], v[214:217], v[172:175], v[118:121]
	v_mfma_f32_16x16x32_bf16 v[114:117], v[222:225], v[172:175], v[114:117]
	v_mfma_f32_16x16x32_bf16 v[102:105], v[214:217], v[190:193], v[102:105]
	v_mfma_f32_16x16x32_bf16 v[98:101], v[222:225], v[190:193], v[98:101]
	v_mfma_f32_16x16x32_bf16 v[86:89], v[214:217], v[198:201], v[86:89]
	v_mfma_f32_16x16x32_bf16 v[82:85], v[222:225], v[198:201], v[82:85]
	v_mfma_f32_16x16x32_bf16 v[70:73], v[214:217], v[206:209], v[70:73]
	v_mfma_f32_16x16x32_bf16 v[66:69], v[222:225], v[206:209], v[66:69]
	s_mov_b32 m0, s30
	s_add_u32 s62, s18, 0x80
	s_addc_u32 s63, s19, 0
	s_barrier
	ds_read_b128 v[168:171], v166 offset:16384
	ds_read_b128 v[172:175], v166 offset:17408
	ds_read_b128 v[186:189], v166 offset:18432
	ds_read_b128 v[190:193], v166 offset:19456
	ds_read_b128 v[194:197], v166 offset:20480
	ds_read_b128 v[198:201], v166 offset:21504
	ds_read_b128 v[202:205], v166 offset:22528
	ds_read_b128 v[206:209], v166 offset:23552
	global_load_lds_dwordx4 v130, s[18:19]
	s_mov_b32 m0, s31
	s_nop 0
	global_load_lds_dwordx4 v134, s[18:19]
	s_barrier
	s_waitcnt lgkmcnt(0)
	s_waitcnt lgkmcnt(0)
	v_mfma_f32_16x16x32_bf16 v[62:65], v[146:149], v[168:171], v[62:65]
	v_mfma_f32_16x16x32_bf16 v[58:61], v[154:157], v[168:171], v[58:61]
	v_mfma_f32_16x16x32_bf16 v[46:49], v[146:149], v[186:189], v[46:49]
	v_mfma_f32_16x16x32_bf16 v[42:45], v[154:157], v[186:189], v[42:45]
	v_mfma_f32_16x16x32_bf16 v[30:33], v[146:149], v[194:197], v[30:33]
	v_mfma_f32_16x16x32_bf16 v[26:29], v[154:157], v[194:197], v[26:29]
	v_mfma_f32_16x16x32_bf16 v[14:17], v[146:149], v[202:205], v[14:17]
	v_mfma_f32_16x16x32_bf16 v[10:13], v[154:157], v[202:205], v[10:13]
	v_mfma_f32_16x16x32_bf16 v[62:65], v[150:153], v[172:175], v[62:65]
	v_mfma_f32_16x16x32_bf16 v[58:61], v[158:161], v[172:175], v[58:61]
	v_mfma_f32_16x16x32_bf16 v[46:49], v[150:153], v[190:193], v[46:49]
	v_mfma_f32_16x16x32_bf16 v[42:45], v[158:161], v[190:193], v[42:45]
	v_mfma_f32_16x16x32_bf16 v[30:33], v[150:153], v[198:201], v[30:33]
	v_mfma_f32_16x16x32_bf16 v[26:29], v[158:161], v[198:201], v[26:29]
	v_mfma_f32_16x16x32_bf16 v[14:17], v[150:153], v[206:209], v[14:17]
	v_mfma_f32_16x16x32_bf16 v[10:13], v[158:161], v[206:209], v[10:13]
	s_barrier
	s_add_u32 s48, s16, 0x80000
	s_addc_u32 s49, s17, 0
	s_add_i32 s50, s51, s29
	s_mov_b32 m0, s50
	s_nop 0
	global_load_lds_dwordx4 v132, s[48:49]
	s_add_i32 m0, s50, 0x2000
	s_nop 0
	global_load_lds_dwordx4 v136, s[48:49]
	s_waitcnt vmcnt(6)
	s_barrier
	v_mfma_f32_16x16x32_bf16 v[54:57], v[210:213], v[168:171], v[54:57]
	v_mfma_f32_16x16x32_bf16 v[50:53], v[218:221], v[168:171], v[50:53]
	v_mfma_f32_16x16x32_bf16 v[38:41], v[210:213], v[186:189], v[38:41]
	v_mfma_f32_16x16x32_bf16 v[34:37], v[218:221], v[186:189], v[34:37]
	v_mfma_f32_16x16x32_bf16 v[22:25], v[210:213], v[194:197], v[22:25]
	v_mfma_f32_16x16x32_bf16 v[18:21], v[218:221], v[194:197], v[18:21]
	v_mfma_f32_16x16x32_bf16 v[6:9], v[210:213], v[202:205], v[6:9]
	v_mfma_f32_16x16x32_bf16 v[2:5], v[218:221], v[202:205], v[2:5]
	v_mfma_f32_16x16x32_bf16 v[54:57], v[214:217], v[172:175], v[54:57]
	v_mfma_f32_16x16x32_bf16 v[50:53], v[222:225], v[172:175], v[50:53]
	v_mfma_f32_16x16x32_bf16 v[38:41], v[214:217], v[190:193], v[38:41]
	v_mfma_f32_16x16x32_bf16 v[34:37], v[222:225], v[190:193], v[34:37]
	v_mfma_f32_16x16x32_bf16 v[22:25], v[214:217], v[198:201], v[22:25]
	v_mfma_f32_16x16x32_bf16 v[18:21], v[222:225], v[198:201], v[18:21]
	v_mfma_f32_16x16x32_bf16 v[6:9], v[214:217], v[206:209], v[6:9]
	v_mfma_f32_16x16x32_bf16 v[2:5], v[222:225], v[206:209], v[2:5]
	s_add_i32 s48, 0, 0x18000
	v_add_u32_e32 v158, s48, v164
	ds_read_b128 v[146:149], v158
	ds_read_b128 v[150:153], v158 offset:1024
	ds_read_b128 v[154:157], v158 offset:2048
	ds_read_b128 v[158:161], v158 offset:3072
	s_barrier
	s_add_u32 s18, s18, s80
	s_addc_u32 s19, s19, 0
	s_mov_b32 m0, s34
	ds_read_b128 v[168:171], v166 offset:32768
	ds_read_b128 v[172:175], v166 offset:33792
	ds_read_b128 v[186:189], v166 offset:34816
	ds_read_b128 v[190:193], v166 offset:35840
	ds_read_b128 v[194:197], v166 offset:36864
	ds_read_b128 v[198:201], v166 offset:37888
	ds_read_b128 v[202:205], v166 offset:38912
	ds_read_b128 v[206:209], v166 offset:39936
	global_load_lds_dwordx4 v130, s[18:19]
	s_mov_b32 m0, s35
	s_nop 0
	global_load_lds_dwordx4 v134, s[18:19]
	s_waitcnt lgkmcnt(8)
	s_barrier
	s_waitcnt lgkmcnt(0)
	s_waitcnt lgkmcnt(0)
	v_mfma_f32_16x16x32_bf16 v[126:129], v[146:149], v[168:171], v[126:129]
	v_mfma_f32_16x16x32_bf16 v[122:125], v[154:157], v[168:171], v[122:125]
	v_mfma_f32_16x16x32_bf16 v[110:113], v[146:149], v[186:189], v[110:113]
	v_mfma_f32_16x16x32_bf16 v[106:109], v[154:157], v[186:189], v[106:109]
	v_mfma_f32_16x16x32_bf16 v[94:97], v[146:149], v[194:197], v[94:97]
	v_mfma_f32_16x16x32_bf16 v[90:93], v[154:157], v[194:197], v[90:93]
	v_mfma_f32_16x16x32_bf16 v[78:81], v[146:149], v[202:205], v[78:81]
	v_mfma_f32_16x16x32_bf16 v[74:77], v[154:157], v[202:205], v[74:77]
	v_mfma_f32_16x16x32_bf16 v[126:129], v[150:153], v[172:175], v[126:129]
	v_mfma_f32_16x16x32_bf16 v[122:125], v[158:161], v[172:175], v[122:125]
	v_mfma_f32_16x16x32_bf16 v[110:113], v[150:153], v[190:193], v[110:113]
	v_mfma_f32_16x16x32_bf16 v[106:109], v[158:161], v[190:193], v[106:109]
	v_mfma_f32_16x16x32_bf16 v[94:97], v[150:153], v[198:201], v[94:97]
	v_mfma_f32_16x16x32_bf16 v[90:93], v[158:161], v[198:201], v[90:93]
	v_mfma_f32_16x16x32_bf16 v[78:81], v[150:153], v[206:209], v[78:81]
	v_mfma_f32_16x16x32_bf16 v[74:77], v[158:161], v[206:209], v[74:77]
	s_barrier
	s_add_i32 s18, 0, 0x1c000
	s_add_i32 s19, s48, s29
	v_add_u32_e32 v167, s18, v164
	s_mov_b32 m0, s19
	ds_read_b128 v[210:213], v167
	ds_read_b128 v[214:217], v167 offset:1024
	ds_read_b128 v[218:221], v167 offset:2048
	ds_read_b128 v[222:225], v167 offset:3072
	global_load_lds_dwordx4 v132, s[64:65]
	s_add_i32 m0, s19, 0x2000
	s_nop 0
	global_load_lds_dwordx4 v136, s[64:65]
	s_barrier
	s_waitcnt lgkmcnt(0)
	s_waitcnt lgkmcnt(0)
	v_mfma_f32_16x16x32_bf16 v[118:121], v[210:213], v[168:171], v[118:121]
	v_mfma_f32_16x16x32_bf16 v[114:117], v[218:221], v[168:171], v[114:117]
	v_mfma_f32_16x16x32_bf16 v[102:105], v[210:213], v[186:189], v[102:105]
	v_mfma_f32_16x16x32_bf16 v[98:101], v[218:221], v[186:189], v[98:101]
	v_mfma_f32_16x16x32_bf16 v[86:89], v[210:213], v[194:197], v[86:89]
	v_mfma_f32_16x16x32_bf16 v[82:85], v[218:221], v[194:197], v[82:85]
	v_mfma_f32_16x16x32_bf16 v[70:73], v[210:213], v[202:205], v[70:73]
	v_mfma_f32_16x16x32_bf16 v[66:69], v[218:221], v[202:205], v[66:69]
	v_mfma_f32_16x16x32_bf16 v[118:121], v[214:217], v[172:175], v[118:121]
	v_mfma_f32_16x16x32_bf16 v[114:117], v[222:225], v[172:175], v[114:117]
	v_mfma_f32_16x16x32_bf16 v[102:105], v[214:217], v[190:193], v[102:105]
	v_mfma_f32_16x16x32_bf16 v[98:101], v[222:225], v[190:193], v[98:101]
	v_mfma_f32_16x16x32_bf16 v[86:89], v[214:217], v[198:201], v[86:89]
	v_mfma_f32_16x16x32_bf16 v[82:85], v[222:225], v[198:201], v[82:85]
	v_mfma_f32_16x16x32_bf16 v[70:73], v[214:217], v[206:209], v[70:73]
	v_mfma_f32_16x16x32_bf16 v[66:69], v[222:225], v[206:209], v[66:69]
	s_mov_b32 m0, s38
	s_barrier
	ds_read_b128 v[168:171], v166 offset:49152
	ds_read_b128 v[172:175], v166 offset:50176
	ds_read_b128 v[186:189], v166 offset:51200
	ds_read_b128 v[190:193], v166 offset:52224
	ds_read_b128 v[194:197], v166 offset:53248
	ds_read_b128 v[198:201], v166 offset:54272
	ds_read_b128 v[202:205], v166 offset:55296
	ds_read_b128 v[206:209], v166 offset:56320
	global_load_lds_dwordx4 v130, s[62:63]
	s_mov_b32 m0, s39
	s_nop 0
	global_load_lds_dwordx4 v134, s[62:63]
	s_barrier
	s_waitcnt lgkmcnt(0)
	s_waitcnt lgkmcnt(0)
	v_mfma_f32_16x16x32_bf16 v[62:65], v[146:149], v[168:171], v[62:65]
	v_mfma_f32_16x16x32_bf16 v[58:61], v[154:157], v[168:171], v[58:61]
	v_mfma_f32_16x16x32_bf16 v[46:49], v[146:149], v[186:189], v[46:49]
	v_mfma_f32_16x16x32_bf16 v[42:45], v[154:157], v[186:189], v[42:45]
	v_mfma_f32_16x16x32_bf16 v[30:33], v[146:149], v[194:197], v[30:33]
	v_mfma_f32_16x16x32_bf16 v[26:29], v[154:157], v[194:197], v[26:29]
	v_mfma_f32_16x16x32_bf16 v[14:17], v[146:149], v[202:205], v[14:17]
	v_mfma_f32_16x16x32_bf16 v[10:13], v[154:157], v[202:205], v[10:13]
	v_mfma_f32_16x16x32_bf16 v[62:65], v[150:153], v[172:175], v[62:65]
	v_mfma_f32_16x16x32_bf16 v[58:61], v[158:161], v[172:175], v[58:61]
	v_mfma_f32_16x16x32_bf16 v[46:49], v[150:153], v[190:193], v[46:49]
	v_mfma_f32_16x16x32_bf16 v[42:45], v[158:161], v[190:193], v[42:45]
	v_mfma_f32_16x16x32_bf16 v[30:33], v[150:153], v[198:201], v[30:33]
	v_mfma_f32_16x16x32_bf16 v[26:29], v[158:161], v[198:201], v[26:29]
	v_mfma_f32_16x16x32_bf16 v[14:17], v[150:153], v[206:209], v[14:17]
	v_mfma_f32_16x16x32_bf16 v[10:13], v[158:161], v[206:209], v[10:13]
	s_barrier
	s_add_u32 s16, s16, 0x80080
	s_addc_u32 s17, s17, 0
	s_add_i32 s18, s18, s29
	s_mov_b32 m0, s18
	s_nop 0
	global_load_lds_dwordx4 v132, s[16:17]
	s_add_i32 m0, s18, 0x2000
	s_nop 0
	global_load_lds_dwordx4 v136, s[16:17]
	s_waitcnt vmcnt(6)
	s_barrier
	v_mfma_f32_16x16x32_bf16 v[54:57], v[210:213], v[168:171], v[54:57]
	v_mfma_f32_16x16x32_bf16 v[50:53], v[218:221], v[168:171], v[50:53]
	v_mfma_f32_16x16x32_bf16 v[38:41], v[210:213], v[186:189], v[38:41]
	v_mfma_f32_16x16x32_bf16 v[34:37], v[218:221], v[186:189], v[34:37]
	v_mfma_f32_16x16x32_bf16 v[22:25], v[210:213], v[194:197], v[22:25]
	v_mfma_f32_16x16x32_bf16 v[18:21], v[218:221], v[194:197], v[18:21]
	v_mfma_f32_16x16x32_bf16 v[6:9], v[210:213], v[202:205], v[6:9]
	v_mfma_f32_16x16x32_bf16 v[2:5], v[218:221], v[202:205], v[2:5]
	v_mfma_f32_16x16x32_bf16 v[54:57], v[214:217], v[172:175], v[54:57]
	v_mfma_f32_16x16x32_bf16 v[50:53], v[222:225], v[172:175], v[50:53]
	v_mfma_f32_16x16x32_bf16 v[38:41], v[214:217], v[190:193], v[38:41]
	v_mfma_f32_16x16x32_bf16 v[34:37], v[222:225], v[190:193], v[34:37]
	v_mfma_f32_16x16x32_bf16 v[22:25], v[214:217], v[198:201], v[22:25]
	v_mfma_f32_16x16x32_bf16 v[18:21], v[222:225], v[198:201], v[18:21]
	v_mfma_f32_16x16x32_bf16 v[6:9], v[214:217], v[206:209], v[6:9]
	v_mfma_f32_16x16x32_bf16 v[2:5], v[222:225], v[206:209], v[2:5]
	s_add_i32 s47, s47, 2
	s_add_u32 s6, s6, 0x100
	s_addc_u32 s7, s7, 0
	s_cmp_gt_u32 s47, 29
	s_barrier
	s_cbranch_scc0 .LBB0_1408
	s_ashr_i32 s3, s33, 5
	s_mul_hi_i32 s7, s3, 0x9000
	s_mul_i32 s3, s3, 0x9000
	v_lshl_or_b32 v168, s43, 8, v165
	s_add_u32 s6, s36, s3
	s_addc_u32 s7, s37, s7
	v_ashrrev_i32_e32 v169, 31, v168
	v_lshl_add_u64 v[162:163], v[168:169], 2, s[6:7]
	global_load_dwordx4 v[142:145], v[162:163], off offset:16
	global_load_dwordx4 v[146:149], v[162:163], off
	s_mov_b64 s[6:7], 0x80000
	s_and_b64 vcc, exec, s[4:5]
	s_mov_b32 s43, s2
	s_mov_b64 s[16:17], s[12:13]
	s_mov_b64 s[14:15], s[10:11]
	s_waitcnt vmcnt(0)
	v_pk_add_f32 v[150:151], v[144:145], 1.0 op_sel_hi:[1,0]
	v_pk_add_f32 v[154:155], v[142:143], 1.0 op_sel_hi:[1,0]
	global_load_dwordx4 v[158:161], v[162:163], off offset:528
	global_load_dwordx4 v[142:145], v[162:163], off offset:512
	v_lshl_add_u32 v162, s33, 8, v1
	v_ashrrev_i32_e32 v163, 31, v162
	v_pk_add_f32 v[156:157], v[146:147], 1.0 op_sel_hi:[1,0]
	v_pk_add_f32 v[152:153], v[148:149], 1.0 op_sel_hi:[1,0]
	s_mov_b32 s33, s42
	s_waitcnt vmcnt(0)
	v_pk_add_f32 v[146:147], v[144:145], 1.0 op_sel_hi:[1,0]
	v_pk_add_f32 v[144:145], v[158:159], 1.0 op_sel_hi:[1,0]
	v_lshlrev_b64 v[158:159], 12, v[162:163]
	v_pk_add_f32 v[148:149], v[142:143], 1.0 op_sel_hi:[1,0]
	v_pk_add_f32 v[142:143], v[160:161], 1.0 op_sel_hi:[1,0]
	v_lshl_add_u64 v[158:159], s[8:9], 0, v[158:159]
	v_lshlrev_b64 v[160:161], 1, v[168:169]
	v_lshl_add_u64 v[158:159], v[158:159], 0, v[160:161]
	global_load_dwordx4 v[168:171], v[158:159], off offset:2048
	s_waitcnt vmcnt(0)
	v_lshlrev_b32_e32 v172, 16, v168
	v_and_b32_e32 v173, 0xffff0000, v168
	v_lshlrev_b32_e32 v168, 16, v169
	v_and_b32_e32 v169, 0xffff0000, v169
	v_pk_fma_f32 v[128:129], v[128:129], v[152:153], v[168:169]
	v_lshlrev_b32_e32 v168, 16, v170
	v_and_b32_e32 v169, 0xffff0000, v170
	v_pk_fma_f32 v[168:169], v[122:123], v[154:155], v[168:169]
	v_lshlrev_b32_e32 v122, 16, v171
	v_and_b32_e32 v123, 0xffff0000, v171
	v_pk_fma_f32 v[126:127], v[126:127], v[156:157], v[172:173]
	v_pk_fma_f32 v[170:171], v[124:125], v[150:151], v[122:123]
	v_cvt_pk_bf16_f32 v122, v126, v127
	v_cvt_pk_bf16_f32 v123, v128, v129
	v_cvt_pk_bf16_f32 v124, v168, v169
	v_cvt_pk_bf16_f32 v125, v170, v171
	global_store_dwordx4 v[158:159], v[122:125], off offset:2048
	global_load_dwordx4 v[122:125], v[158:159], off offset:2304
	s_waitcnt vmcnt(0)
	v_lshlrev_b32_e32 v126, 16, v122
	v_and_b32_e32 v127, 0xffff0000, v122
	v_lshlrev_b32_e32 v122, 16, v123
	v_and_b32_e32 v123, 0xffff0000, v123
	v_pk_fma_f32 v[120:121], v[120:121], v[146:147], v[122:123]
	v_lshlrev_b32_e32 v122, 16, v124
	v_and_b32_e32 v123, 0xffff0000, v124
	v_pk_fma_f32 v[122:123], v[114:115], v[144:145], v[122:123]
	v_lshlrev_b32_e32 v114, 16, v125
	v_and_b32_e32 v115, 0xffff0000, v125
	v_pk_fma_f32 v[118:119], v[118:119], v[148:149], v[126:127]
	v_pk_fma_f32 v[124:125], v[116:117], v[142:143], v[114:115]
	v_cvt_pk_bf16_f32 v114, v118, v119
	v_cvt_pk_bf16_f32 v115, v120, v121
	v_cvt_pk_bf16_f32 v116, v122, v123
	v_cvt_pk_bf16_f32 v117, v124, v125
	global_store_dwordx4 v[158:159], v[114:117], off offset:2304
	s_nop 1
	v_or_b32_e32 v114, 16, v162
	v_ashrrev_i32_e32 v115, 31, v114
	v_lshlrev_b64 v[114:115], 12, v[114:115]
	v_lshl_add_u64 v[114:115], s[8:9], 0, v[114:115]
	v_lshl_add_u64 v[118:119], v[114:115], 0, v[160:161]
	global_load_dwordx4 v[114:117], v[118:119], off offset:2048
	s_waitcnt vmcnt(0)
	v_lshlrev_b32_e32 v120, 16, v114
	v_and_b32_e32 v121, 0xffff0000, v114
	v_lshlrev_b32_e32 v114, 16, v115
	v_and_b32_e32 v115, 0xffff0000, v115
	v_pk_fma_f32 v[112:113], v[112:113], v[152:153], v[114:115]
	v_lshlrev_b32_e32 v114, 16, v116
	v_and_b32_e32 v115, 0xffff0000, v116
	v_pk_fma_f32 v[114:115], v[106:107], v[154:155], v[114:115]
	v_lshlrev_b32_e32 v106, 16, v117
	v_and_b32_e32 v107, 0xffff0000, v117
	v_pk_fma_f32 v[110:111], v[110:111], v[156:157], v[120:121]
	v_pk_fma_f32 v[116:117], v[108:109], v[150:151], v[106:107]
	v_cvt_pk_bf16_f32 v106, v110, v111
	v_cvt_pk_bf16_f32 v107, v112, v113
	v_cvt_pk_bf16_f32 v108, v114, v115
	v_cvt_pk_bf16_f32 v109, v116, v117
	global_store_dwordx4 v[118:119], v[106:109], off offset:2048
	global_load_dwordx4 v[106:109], v[118:119], off offset:2304
	s_waitcnt vmcnt(0)
	v_lshlrev_b32_e32 v110, 16, v106
	v_and_b32_e32 v111, 0xffff0000, v106
	v_lshlrev_b32_e32 v106, 16, v107
	v_and_b32_e32 v107, 0xffff0000, v107
	v_pk_fma_f32 v[104:105], v[104:105], v[146:147], v[106:107]
	v_lshlrev_b32_e32 v106, 16, v108
	v_and_b32_e32 v107, 0xffff0000, v108
	v_pk_fma_f32 v[106:107], v[98:99], v[144:145], v[106:107]
	v_lshlrev_b32_e32 v98, 16, v109
	v_and_b32_e32 v99, 0xffff0000, v109
	v_pk_fma_f32 v[102:103], v[102:103], v[148:149], v[110:111]
	v_pk_fma_f32 v[108:109], v[100:101], v[142:143], v[98:99]
	v_cvt_pk_bf16_f32 v98, v102, v103
	v_cvt_pk_bf16_f32 v99, v104, v105
	v_cvt_pk_bf16_f32 v100, v106, v107
	v_cvt_pk_bf16_f32 v101, v108, v109
	global_store_dwordx4 v[118:119], v[98:101], off offset:2304
	s_nop 1
	v_or_b32_e32 v98, 32, v162
	v_ashrrev_i32_e32 v99, 31, v98
	v_lshlrev_b64 v[98:99], 12, v[98:99]
	v_lshl_add_u64 v[98:99], s[8:9], 0, v[98:99]
	v_lshl_add_u64 v[102:103], v[98:99], 0, v[160:161]
	global_load_dwordx4 v[98:101], v[102:103], off offset:2048
	s_waitcnt vmcnt(0)
	v_lshlrev_b32_e32 v104, 16, v98
	v_and_b32_e32 v105, 0xffff0000, v98
	v_lshlrev_b32_e32 v98, 16, v99
	v_and_b32_e32 v99, 0xffff0000, v99
	v_pk_fma_f32 v[96:97], v[96:97], v[152:153], v[98:99]
	v_lshlrev_b32_e32 v98, 16, v100
	v_and_b32_e32 v99, 0xffff0000, v100
	v_pk_fma_f32 v[98:99], v[90:91], v[154:155], v[98:99]
	v_lshlrev_b32_e32 v90, 16, v101
	v_and_b32_e32 v91, 0xffff0000, v101
	v_pk_fma_f32 v[94:95], v[94:95], v[156:157], v[104:105]
	v_pk_fma_f32 v[100:101], v[92:93], v[150:151], v[90:91]
	v_cvt_pk_bf16_f32 v90, v94, v95
	v_cvt_pk_bf16_f32 v91, v96, v97
	v_cvt_pk_bf16_f32 v92, v98, v99
	v_cvt_pk_bf16_f32 v93, v100, v101
	global_store_dwordx4 v[102:103], v[90:93], off offset:2048
	global_load_dwordx4 v[90:93], v[102:103], off offset:2304
	s_waitcnt vmcnt(0)
	v_lshlrev_b32_e32 v94, 16, v90
	v_and_b32_e32 v95, 0xffff0000, v90
	v_lshlrev_b32_e32 v90, 16, v91
	v_and_b32_e32 v91, 0xffff0000, v91
	v_pk_fma_f32 v[88:89], v[88:89], v[146:147], v[90:91]
	v_lshlrev_b32_e32 v90, 16, v92
	v_and_b32_e32 v91, 0xffff0000, v92
	v_pk_fma_f32 v[90:91], v[82:83], v[144:145], v[90:91]
	v_lshlrev_b32_e32 v82, 16, v93
	v_and_b32_e32 v83, 0xffff0000, v93
	v_pk_fma_f32 v[86:87], v[86:87], v[148:149], v[94:95]
	v_pk_fma_f32 v[92:93], v[84:85], v[142:143], v[82:83]
	v_cvt_pk_bf16_f32 v82, v86, v87
	v_cvt_pk_bf16_f32 v83, v88, v89
	v_cvt_pk_bf16_f32 v84, v90, v91
	v_cvt_pk_bf16_f32 v85, v92, v93
	global_store_dwordx4 v[102:103], v[82:85], off offset:2304
	s_nop 1
	v_or_b32_e32 v82, 48, v162
	v_ashrrev_i32_e32 v83, 31, v82
	v_lshlrev_b64 v[82:83], 12, v[82:83]
	v_lshl_add_u64 v[82:83], s[8:9], 0, v[82:83]
	v_lshl_add_u64 v[82:83], v[82:83], 0, v[160:161]
	global_load_dwordx4 v[84:87], v[82:83], off offset:2048
	s_waitcnt vmcnt(0)
	v_lshlrev_b32_e32 v88, 16, v84
	v_and_b32_e32 v89, 0xffff0000, v84
	v_lshlrev_b32_e32 v84, 16, v85
	v_and_b32_e32 v85, 0xffff0000, v85
	v_pk_fma_f32 v[80:81], v[80:81], v[152:153], v[84:85]
	v_lshlrev_b32_e32 v84, 16, v86
	v_and_b32_e32 v85, 0xffff0000, v86
	v_pk_fma_f32 v[84:85], v[74:75], v[154:155], v[84:85]
	v_lshlrev_b32_e32 v74, 16, v87
	v_and_b32_e32 v75, 0xffff0000, v87
	v_pk_fma_f32 v[78:79], v[78:79], v[156:157], v[88:89]
	v_pk_fma_f32 v[86:87], v[76:77], v[150:151], v[74:75]
	v_cvt_pk_bf16_f32 v74, v78, v79
	v_cvt_pk_bf16_f32 v75, v80, v81
	v_cvt_pk_bf16_f32 v76, v84, v85
	v_cvt_pk_bf16_f32 v77, v86, v87
	global_store_dwordx4 v[82:83], v[74:77], off offset:2048
	global_load_dwordx4 v[74:77], v[82:83], off offset:2304
	s_waitcnt vmcnt(0)
	v_lshlrev_b32_e32 v78, 16, v74
	v_and_b32_e32 v79, 0xffff0000, v74
	v_lshlrev_b32_e32 v74, 16, v75
	v_and_b32_e32 v75, 0xffff0000, v75
	v_pk_fma_f32 v[72:73], v[72:73], v[146:147], v[74:75]
	v_lshlrev_b32_e32 v74, 16, v76
	v_and_b32_e32 v75, 0xffff0000, v76
	v_pk_fma_f32 v[74:75], v[66:67], v[144:145], v[74:75]
	v_lshlrev_b32_e32 v66, 16, v77
	v_and_b32_e32 v67, 0xffff0000, v77
	v_pk_fma_f32 v[70:71], v[70:71], v[148:149], v[78:79]
	v_pk_fma_f32 v[76:77], v[68:69], v[142:143], v[66:67]
	v_cvt_pk_bf16_f32 v66, v70, v71
	v_cvt_pk_bf16_f32 v67, v72, v73
	v_cvt_pk_bf16_f32 v68, v74, v75
	v_cvt_pk_bf16_f32 v69, v76, v77
	v_lshl_add_u64 v[70:71], v[158:159], 0, s[6:7]
	global_store_dwordx4 v[82:83], v[66:69], off offset:2304
	global_load_dwordx4 v[66:69], v[70:71], off offset:2048
	s_mov_b64 s[6:7], 0x90000
	s_waitcnt vmcnt(0)
	v_lshlrev_b32_e32 v72, 16, v66
	v_and_b32_e32 v73, 0xffff0000, v66
	v_lshlrev_b32_e32 v66, 16, v67
	v_and_b32_e32 v67, 0xffff0000, v67
	v_pk_fma_f32 v[64:65], v[64:65], v[152:153], v[66:67]
	v_lshlrev_b32_e32 v66, 16, v68
	v_and_b32_e32 v67, 0xffff0000, v68
	v_pk_fma_f32 v[66:67], v[58:59], v[154:155], v[66:67]
	v_lshlrev_b32_e32 v58, 16, v69
	v_and_b32_e32 v59, 0xffff0000, v69
	v_pk_fma_f32 v[62:63], v[62:63], v[156:157], v[72:73]
	v_pk_fma_f32 v[68:69], v[60:61], v[150:151], v[58:59]
	v_cvt_pk_bf16_f32 v58, v62, v63
	v_cvt_pk_bf16_f32 v59, v64, v65
	v_cvt_pk_bf16_f32 v60, v66, v67
	v_cvt_pk_bf16_f32 v61, v68, v69
	global_store_dwordx4 v[70:71], v[58:61], off offset:2048
	global_load_dwordx4 v[58:61], v[70:71], off offset:2304
	s_waitcnt vmcnt(0)
	v_lshlrev_b32_e32 v62, 16, v58
	v_and_b32_e32 v63, 0xffff0000, v58
	v_lshlrev_b32_e32 v58, 16, v59
	v_and_b32_e32 v59, 0xffff0000, v59
	v_pk_fma_f32 v[56:57], v[56:57], v[146:147], v[58:59]
	v_lshlrev_b32_e32 v58, 16, v60
	v_and_b32_e32 v59, 0xffff0000, v60
	v_pk_fma_f32 v[58:59], v[50:51], v[144:145], v[58:59]
	v_lshlrev_b32_e32 v50, 16, v61
	v_and_b32_e32 v51, 0xffff0000, v61
	v_pk_fma_f32 v[54:55], v[54:55], v[148:149], v[62:63]
	v_pk_fma_f32 v[60:61], v[52:53], v[142:143], v[50:51]
	v_cvt_pk_bf16_f32 v50, v54, v55
	v_cvt_pk_bf16_f32 v51, v56, v57
	v_cvt_pk_bf16_f32 v52, v58, v59
	v_cvt_pk_bf16_f32 v53, v60, v61
	v_lshl_add_u64 v[54:55], v[158:159], 0, s[6:7]
	global_store_dwordx4 v[70:71], v[50:53], off offset:2304
	global_load_dwordx4 v[50:53], v[54:55], off offset:2048
	s_mov_b64 s[6:7], 0xa0000
	s_waitcnt vmcnt(0)
	v_lshlrev_b32_e32 v56, 16, v50
	v_and_b32_e32 v57, 0xffff0000, v50
	v_lshlrev_b32_e32 v50, 16, v51
	v_and_b32_e32 v51, 0xffff0000, v51
	v_pk_fma_f32 v[48:49], v[48:49], v[152:153], v[50:51]
	v_lshlrev_b32_e32 v50, 16, v52
	v_and_b32_e32 v51, 0xffff0000, v52
	v_pk_fma_f32 v[50:51], v[42:43], v[154:155], v[50:51]
	v_lshlrev_b32_e32 v42, 16, v53
	v_and_b32_e32 v43, 0xffff0000, v53
	v_pk_fma_f32 v[46:47], v[46:47], v[156:157], v[56:57]
	v_pk_fma_f32 v[52:53], v[44:45], v[150:151], v[42:43]
	v_cvt_pk_bf16_f32 v42, v46, v47
	v_cvt_pk_bf16_f32 v43, v48, v49
	v_cvt_pk_bf16_f32 v44, v50, v51
	v_cvt_pk_bf16_f32 v45, v52, v53
	global_store_dwordx4 v[54:55], v[42:45], off offset:2048
	global_load_dwordx4 v[42:45], v[54:55], off offset:2304
	s_waitcnt vmcnt(0)
	v_lshlrev_b32_e32 v46, 16, v42
	v_and_b32_e32 v47, 0xffff0000, v42
	v_lshlrev_b32_e32 v42, 16, v43
	v_and_b32_e32 v43, 0xffff0000, v43
	v_pk_fma_f32 v[40:41], v[40:41], v[146:147], v[42:43]
	v_lshlrev_b32_e32 v42, 16, v44
	v_and_b32_e32 v43, 0xffff0000, v44
	v_pk_fma_f32 v[42:43], v[34:35], v[144:145], v[42:43]
	v_lshlrev_b32_e32 v34, 16, v45
	v_and_b32_e32 v35, 0xffff0000, v45
	v_pk_fma_f32 v[38:39], v[38:39], v[148:149], v[46:47]
	v_pk_fma_f32 v[44:45], v[36:37], v[142:143], v[34:35]
	v_cvt_pk_bf16_f32 v34, v38, v39
	v_cvt_pk_bf16_f32 v35, v40, v41
	v_cvt_pk_bf16_f32 v36, v42, v43
	v_cvt_pk_bf16_f32 v37, v44, v45
	v_lshl_add_u64 v[38:39], v[158:159], 0, s[6:7]
	global_store_dwordx4 v[54:55], v[34:37], off offset:2304
	global_load_dwordx4 v[34:37], v[38:39], off offset:2048
	s_mov_b64 s[6:7], 0xb0000
	s_waitcnt vmcnt(0)
	v_lshlrev_b32_e32 v40, 16, v34
	v_and_b32_e32 v41, 0xffff0000, v34
	v_lshlrev_b32_e32 v34, 16, v35
	v_and_b32_e32 v35, 0xffff0000, v35
	v_pk_fma_f32 v[32:33], v[32:33], v[152:153], v[34:35]
	v_lshlrev_b32_e32 v34, 16, v36
	v_and_b32_e32 v35, 0xffff0000, v36
	v_pk_fma_f32 v[34:35], v[26:27], v[154:155], v[34:35]
	v_lshlrev_b32_e32 v26, 16, v37
	v_and_b32_e32 v27, 0xffff0000, v37
	v_pk_fma_f32 v[30:31], v[30:31], v[156:157], v[40:41]
	v_pk_fma_f32 v[36:37], v[28:29], v[150:151], v[26:27]
	v_cvt_pk_bf16_f32 v26, v30, v31
	v_cvt_pk_bf16_f32 v27, v32, v33
	v_cvt_pk_bf16_f32 v28, v34, v35
	v_cvt_pk_bf16_f32 v29, v36, v37
	global_store_dwordx4 v[38:39], v[26:29], off offset:2048
	global_load_dwordx4 v[26:29], v[38:39], off offset:2304
	s_waitcnt vmcnt(0)
	v_lshlrev_b32_e32 v30, 16, v26
	v_and_b32_e32 v31, 0xffff0000, v26
	v_lshlrev_b32_e32 v26, 16, v27
	v_and_b32_e32 v27, 0xffff0000, v27
	v_pk_fma_f32 v[24:25], v[24:25], v[146:147], v[26:27]
	v_lshlrev_b32_e32 v26, 16, v28
	v_and_b32_e32 v27, 0xffff0000, v28
	v_pk_fma_f32 v[26:27], v[18:19], v[144:145], v[26:27]
	v_lshlrev_b32_e32 v18, 16, v29
	v_and_b32_e32 v19, 0xffff0000, v29
	v_pk_fma_f32 v[22:23], v[22:23], v[148:149], v[30:31]
	v_pk_fma_f32 v[28:29], v[20:21], v[142:143], v[18:19]
	v_cvt_pk_bf16_f32 v18, v22, v23
	v_cvt_pk_bf16_f32 v19, v24, v25
	v_cvt_pk_bf16_f32 v20, v26, v27
	v_cvt_pk_bf16_f32 v21, v28, v29
	global_store_dwordx4 v[38:39], v[18:21], off offset:2304
	s_nop 1
	v_lshl_add_u64 v[18:19], v[158:159], 0, s[6:7]
	global_load_dwordx4 v[20:23], v[18:19], off offset:2048
	s_waitcnt vmcnt(0)
	v_lshlrev_b32_e32 v24, 16, v20
	v_and_b32_e32 v25, 0xffff0000, v20
	v_lshlrev_b32_e32 v20, 16, v21
	v_and_b32_e32 v21, 0xffff0000, v21
	v_pk_fma_f32 v[16:17], v[16:17], v[152:153], v[20:21]
	v_lshlrev_b32_e32 v20, 16, v22
	v_and_b32_e32 v21, 0xffff0000, v22
	v_pk_fma_f32 v[20:21], v[10:11], v[154:155], v[20:21]
	v_lshlrev_b32_e32 v10, 16, v23
	v_and_b32_e32 v11, 0xffff0000, v23
	v_pk_fma_f32 v[14:15], v[14:15], v[156:157], v[24:25]
	v_pk_fma_f32 v[22:23], v[12:13], v[150:151], v[10:11]
	v_cvt_pk_bf16_f32 v10, v14, v15
	v_cvt_pk_bf16_f32 v11, v16, v17
	v_cvt_pk_bf16_f32 v12, v20, v21
	v_cvt_pk_bf16_f32 v13, v22, v23
	global_store_dwordx4 v[18:19], v[10:13], off offset:2048
	global_load_dwordx4 v[10:13], v[18:19], off offset:2304
	s_waitcnt vmcnt(0)
	v_lshlrev_b32_e32 v14, 16, v10
	v_and_b32_e32 v15, 0xffff0000, v10
	v_lshlrev_b32_e32 v10, 16, v11
	v_and_b32_e32 v11, 0xffff0000, v11
	v_pk_fma_f32 v[8:9], v[8:9], v[146:147], v[10:11]
	v_lshlrev_b32_e32 v10, 16, v12
	v_and_b32_e32 v11, 0xffff0000, v12
	v_pk_fma_f32 v[10:11], v[2:3], v[144:145], v[10:11]
	v_lshlrev_b32_e32 v2, 16, v13
	v_and_b32_e32 v3, 0xffff0000, v13
	v_pk_fma_f32 v[6:7], v[6:7], v[148:149], v[14:15]
	v_pk_fma_f32 v[12:13], v[4:5], v[142:143], v[2:3]
	v_cvt_pk_bf16_f32 v2, v6, v7
	v_cvt_pk_bf16_f32 v3, v8, v9
	v_cvt_pk_bf16_f32 v4, v10, v11
	v_cvt_pk_bf16_f32 v5, v12, v13
	global_store_dwordx4 v[18:19], v[2:5], off offset:2304
	s_cbranch_vccz .LBB0_1399
	s_waitcnt vmcnt(0)
	s_cmpk_gt_u32 s22, 0xff
	s_cbranch_scc1 .LBB0_1412
	s_barrier
